# hand-written P2 prompt mixer (single 16-token pass, SGPR row bases, counted vmcnt) on top of copies_to_p1+multi_to_p2
# speedup vs baseline: 1.0081x; 1.0081x over previous
;     __device__ __forceinline__ bf16_t* U() const { return (bf16_t*)(ws + WS_U); }
;     __device__ __forceinline__ bf16_t* P() const { return (bf16_t*)(ws + WS_P); }
;     __device__ __forceinline__ bf16_t* MIX() const { return (bf16_t*)(ws + WS_MIX); }
; __device__ __forceinline__ void mixer_prompt_run(const Args& p, int run, int c2) {
;     const int b = run >> 7, t0 = (run & 127) * 16;
;     const unsigned* U32 = (const unsigned*)p.U(); const unsigned* P32 = (const unsigned*)p.P(); unsigned* M32 = (unsigned*)p.MIX();
;     const size_t rowb = (size_t)b * SEQ;
;     {
;         unsigned pin[31];
; #pragma unroll
;         for (int i = 0; i < 31; ++i) { const int t = t0 - 15 + i; const unsigned v = P32[(rowb + (t >= 0 ? t : 0)) * 256 + c2]; pin[i] = (t >= 0) ? v : 0u; }
;         const int gi = __builtin_amdgcn_readfirstlane(c2 >> 6);
;         unsigned* dst = M32 + (rowb + t0) * 512 + 256 + c2;
;         if (gi == 0) pool_prompt_w<2>(pin, t0, dst); else if (gi == 1) pool_prompt_w<4>(pin, t0, dst); else if (gi == 2) pool_prompt_w<8>(pin, t0, dst); else pool_prompt_w<16>(pin, t0, dst);
;     }
;     asm volatile("" ::: "memory");
;     {
;         f32x2v w[31];
; #pragma unroll
;         for (int j = 0; j < 31; ++j) w[j] = *(const f32x2v*)(p.conv_w() + j * 512 + 2 * c2);
;         const f32x2v cb = *(const f32x2v*)(p.conv_b() + 2 * c2);
;         const f32x2v gg = *(const f32x2v*)(p.gn_g() + 2 * c2), gb = *(const f32x2v*)(p.gn_b() + 2 * c2);
.LBB0_604:
	s_andn2_b64 vcc, exec, s[0:1]
	s_cbranch_vccnz .LBB0_601
	s_add_i32 s62, s20, s41
	v_readfirstlane_b32 s75, v192
	v_lshlrev_b32_e32 v105, 2, v164
	s_lshr_b32 s63, s62, 7
	s_and_b32 s64, s62, 0x7f
	s_lshl_b32 s64, s64, 4
	s_lshl_b32 s63, s63, 11
	s_add_i32 s63, s63, s64
	s_lshr_b32 s75, s75, 6
	s_and_b32 s75, s75, 3
	s_sub_i32 s1, s63, 15
	s_lshl_b32 s65, s1, 10
	s_ashr_i32 s0, s65, 31
	s_add_u32 s68, s58, s65
	s_addc_u32 s69, s59, s0
	s_add_u32 s68, s68, 0x5d81000
	s_addc_u32 s69, s69, 0
	global_load_dword v208, v105, s[68:69] offset:-4096
	global_load_dword v209, v105, s[68:69] offset:-3072
	global_load_dword v210, v105, s[68:69] offset:-2048
	global_load_dword v211, v105, s[68:69] offset:-1024
	global_load_dword v212, v105, s[68:69] offset:0
	global_load_dword v213, v105, s[68:69] offset:1024
	global_load_dword v214, v105, s[68:69] offset:2048
	global_load_dword v215, v105, s[68:69] offset:3072
	s_add_u32 s68, s68, 0x2000
	s_addc_u32 s69, s69, 0
	global_load_dword v216, v105, s[68:69] offset:-4096
	global_load_dword v217, v105, s[68:69] offset:-3072
	global_load_dword v218, v105, s[68:69] offset:-2048
	global_load_dword v219, v105, s[68:69] offset:-1024
	global_load_dword v220, v105, s[68:69] offset:0
	global_load_dword v221, v105, s[68:69] offset:1024
	global_load_dword v222, v105, s[68:69] offset:2048
	global_load_dword v223, v105, s[68:69] offset:3072
	s_add_u32 s68, s68, 0x2000
	s_addc_u32 s69, s69, 0
	global_load_dword v224, v105, s[68:69] offset:-4096
	global_load_dword v225, v105, s[68:69] offset:-3072
	global_load_dword v226, v105, s[68:69] offset:-2048
	global_load_dword v227, v105, s[68:69] offset:-1024
	global_load_dword v228, v105, s[68:69] offset:0
	global_load_dword v229, v105, s[68:69] offset:1024
	global_load_dword v230, v105, s[68:69] offset:2048
	global_load_dword v231, v105, s[68:69] offset:3072
	s_add_u32 s68, s68, 0x2000
	s_addc_u32 s69, s69, 0
	global_load_dword v232, v105, s[68:69] offset:-4096
	global_load_dword v233, v105, s[68:69] offset:-3072
	global_load_dword v234, v105, s[68:69] offset:-2048
	global_load_dword v235, v105, s[68:69] offset:-1024
	global_load_dword v236, v105, s[68:69] offset:0
	global_load_dword v237, v105, s[68:69] offset:1024
	global_load_dword v238, v105, s[68:69] offset:2048
	s_waitcnt vmcnt(31)
	global_load_dwordx2 v[106:107], v[2:3], off
	global_load_dwordx2 v[108:109], v[2:3], off offset:2048
	global_load_dwordx2 v[110:111], v[4:5], off
	global_load_dwordx2 v[112:113], v[6:7], off
	global_load_dwordx2 v[114:115], v[8:9], off
	global_load_dwordx2 v[116:117], v[10:11], off
	global_load_dwordx2 v[118:119], v[12:13], off
	global_load_dwordx2 v[120:121], v[14:15], off
	global_load_dwordx2 v[122:123], v[16:17], off
	global_load_dwordx2 v[124:125], v[18:19], off
	global_load_dwordx2 v[126:127], v[20:21], off
	global_load_dwordx2 v[128:129], v[22:23], off
	global_load_dwordx2 v[130:131], v[24:25], off
	global_load_dwordx2 v[132:133], v[26:27], off
	global_load_dwordx2 v[134:135], v[28:29], off
	global_load_dwordx2 v[136:137], v[30:31], off
	global_load_dwordx2 v[138:139], v[32:33], off
	global_load_dwordx2 v[140:141], v[34:35], off
	global_load_dwordx2 v[142:143], v[36:37], off
	global_load_dwordx2 v[144:145], v[38:39], off
	global_load_dwordx2 v[146:147], v[40:41], off
	global_load_dwordx2 v[148:149], v[42:43], off
	global_load_dwordx2 v[150:151], v[44:45], off
	global_load_dwordx2 v[152:153], v[46:47], off
	global_load_dwordx2 v[154:155], v[48:49], off
	global_load_dwordx2 v[156:157], v[50:51], off
	global_load_dwordx2 v[158:159], v[52:53], off
	global_load_dwordx2 v[160:161], v[54:55], off
	s_sub_i32 s1, s63, 30
	s_lshl_b32 s65, s1, 10
	s_ashr_i32 s0, s65, 31
	s_add_u32 s66, s58, s65
	s_addc_u32 s67, s59, s0
	s_add_u32 s66, s66, 0x4d01000
	s_addc_u32 s67, s67, 0
	s_lshl_b32 s65, s63, 11
	s_ashr_i32 s0, s65, 31
	s_add_u32 s70, s58, s65
	s_addc_u32 s71, s59, s0
	s_add_u32 s70, s70, 0x6e01000
	s_addc_u32 s71, s71, 0
	s_mov_b32 s76, s70
	s_mov_b32 s77, s71
	s_lshl_b32 s74, 2, s75
	s_sub_i32 s72, 126, s75
	s_lshl_b32 s72, s72, 23
	s_mov_b32 s73, s72
	v_xor_b32_e32 v239, 16, v165
	v_lshlrev_b32_e32 v239, 2, v239
	s_cmp_lt_i32 s64, 32
	s_cselect_b64 vcc, -1, 0
	s_waitcnt vmcnt(28)
	s_cmp_eq_u32 s64, 0
	s_cbranch_scc0 .Lmx_pnz
	v_mov_b32_e32 v208, 0
	v_mov_b32_e32 v209, 0
	v_mov_b32_e32 v210, 0
	v_mov_b32_e32 v211, 0
	v_mov_b32_e32 v212, 0
	v_mov_b32_e32 v213, 0
	v_mov_b32_e32 v214, 0
	v_mov_b32_e32 v215, 0
	v_mov_b32_e32 v216, 0
	v_mov_b32_e32 v217, 0
	v_mov_b32_e32 v218, 0
	v_mov_b32_e32 v219, 0
	v_mov_b32_e32 v220, 0
	v_mov_b32_e32 v221, 0
	v_mov_b32_e32 v222, 0
.Lmx_pnz:
	global_load_dword v193, v105, s[66:67] offset:-4096
	global_load_dword v194, v105, s[66:67] offset:-3072
	global_load_dword v195, v105, s[66:67] offset:-2048
	global_load_dword v196, v105, s[66:67] offset:-1024
	global_load_dword v197, v105, s[66:67] offset:0
	global_load_dword v198, v105, s[66:67] offset:1024
	global_load_dword v199, v105, s[66:67] offset:2048
	global_load_dword v200, v105, s[66:67] offset:3072
	s_add_u32 s66, s66, 0x2000
	s_addc_u32 s67, s67, 0
	global_load_dword v201, v105, s[66:67] offset:-4096
	global_load_dword v202, v105, s[66:67] offset:-3072
	global_load_dword v203, v105, s[66:67] offset:-2048
	global_load_dword v204, v105, s[66:67] offset:-1024
	global_load_dword v205, v105, s[66:67] offset:0
	global_load_dword v206, v105, s[66:67] offset:1024
	global_load_dword v207, v105, s[66:67] offset:2048
	global_load_dwordx2 v[162:163], v[56:57], off
	global_load_dwordx2 v[168:169], v[58:59], off
	global_load_dwordx2 v[170:171], v[60:61], off
	global_load_dwordx2 v[90:91], v[62:63], off
	global_load_dwordx2 v[92:93], v[68:69], off
	global_load_dwordx2 v[94:95], v[70:71], off
	s_cmp_eq_u32 s75, 0
	s_cbranch_scc1 .Lmx_pool0
	s_cmp_eq_u32 s75, 1
	s_cbranch_scc1 .Lmx_pool1
	s_cmp_eq_u32 s75, 2
	s_cbranch_scc1 .Lmx_pool2
	s_branch .Lmx_pool3
; __device__ __forceinline__ unsigned pk2(float lo, float hi) { f32x2v v = {lo, hi}; b16x2v b = __builtin_convertvector(v, b16x2v); return __builtin_bit_cast(unsigned, b); }
; __device__ __forceinline__ f32x2v bf2(unsigned v) { return (f32x2v){bflo(v), bfhi(v)}; }
; template <int W>
; __device__ __forceinline__ void pool_prompt_w(const unsigned (&pin)[31], int t0, unsigned* dst  ) {
;     f32x2v s = {0.f, 0.f};
; #pragma unroll
;     for (int i = 0; i < W; ++i) s = s + bf2(pin[15 - i]);
; #pragma unroll
;     for (int t = 0; t < 16; ++t) {
;         if (t > 0) s = s + (bf2(pin[15 + t]) - bf2(pin[15 + t - W]));
;         const float cnt = (float)min(t0 + t + 1, W); const f32x2v cur = bf2(pin[15 + t]);
;         dst[(size_t)t * 512] = pk2(s.x / cnt - cur.x, s.y / cnt - cur.y);
.Lmx_pool0:
	v_lshlrev_b32_e32 v172, 16, v223
	v_and_b32_e32 v173, 0xffff0000, v223
	v_lshlrev_b32_e32 v176, 16, v222
	v_and_b32_e32 v177, 0xffff0000, v222
	v_pk_add_f32 v[172:173], v[172:173], v[176:177]
	v_lshlrev_b32_e32 v174, 16, v223
	v_and_b32_e32 v175, 0xffff0000, v223
	s_cmp_eq_u32 s64, 0
	s_cbranch_scc1 .Lmx_ps0_0
	v_pk_mul_f32 v[180:181], v[172:173], s[72:73] op_sel_hi:[1,0]
.Lmx_pb0_0:
	v_pk_add_f32 v[182:183], v[180:181], v[174:175] neg_lo:[0,1] neg_hi:[0,1]
	v_cvt_pk_bf16_f32 v184, v182, v183
	global_store_dword v105, v184, s[76:77] offset:-3072
	v_lshlrev_b32_e32 v174, 16, v224
	v_and_b32_e32 v175, 0xffff0000, v224
	v_lshlrev_b32_e32 v176, 16, v222
	v_and_b32_e32 v177, 0xffff0000, v222
	v_pk_add_f32 v[178:179], v[174:175], v[176:177] neg_lo:[0,1] neg_hi:[0,1]
	v_pk_add_f32 v[172:173], v[172:173], v[178:179]
	v_pk_mul_f32 v[180:181], v[172:173], s[72:73] op_sel_hi:[1,0]
	v_pk_add_f32 v[182:183], v[180:181], v[174:175] neg_lo:[0,1] neg_hi:[0,1]
	v_cvt_pk_bf16_f32 v185, v182, v183
	global_store_dword v105, v185, s[76:77] offset:-1024
	v_lshlrev_b32_e32 v174, 16, v225
	v_and_b32_e32 v175, 0xffff0000, v225
	v_lshlrev_b32_e32 v176, 16, v223
	v_and_b32_e32 v177, 0xffff0000, v223
	v_pk_add_f32 v[178:179], v[174:175], v[176:177] neg_lo:[0,1] neg_hi:[0,1]
	v_pk_add_f32 v[172:173], v[172:173], v[178:179]
	v_pk_mul_f32 v[180:181], v[172:173], s[72:73] op_sel_hi:[1,0]
	v_pk_add_f32 v[182:183], v[180:181], v[174:175] neg_lo:[0,1] neg_hi:[0,1]
	v_cvt_pk_bf16_f32 v186, v182, v183
	global_store_dword v105, v186, s[76:77] offset:1024
	v_lshlrev_b32_e32 v174, 16, v226
	v_and_b32_e32 v175, 0xffff0000, v226
	v_lshlrev_b32_e32 v176, 16, v224
	v_and_b32_e32 v177, 0xffff0000, v224
	v_pk_add_f32 v[178:179], v[174:175], v[176:177] neg_lo:[0,1] neg_hi:[0,1]
	v_pk_add_f32 v[172:173], v[172:173], v[178:179]
	v_pk_mul_f32 v[180:181], v[172:173], s[72:73] op_sel_hi:[1,0]
	v_pk_add_f32 v[182:183], v[180:181], v[174:175] neg_lo:[0,1] neg_hi:[0,1]
	v_cvt_pk_bf16_f32 v187, v182, v183
	global_store_dword v105, v187, s[76:77] offset:3072
	v_lshlrev_b32_e32 v174, 16, v227
	v_and_b32_e32 v175, 0xffff0000, v227
	v_lshlrev_b32_e32 v176, 16, v225
	v_and_b32_e32 v177, 0xffff0000, v225
	v_pk_add_f32 v[178:179], v[174:175], v[176:177] neg_lo:[0,1] neg_hi:[0,1]
	v_pk_add_f32 v[172:173], v[172:173], v[178:179]
	v_pk_mul_f32 v[180:181], v[172:173], s[72:73] op_sel_hi:[1,0]
	v_pk_add_f32 v[182:183], v[180:181], v[174:175] neg_lo:[0,1] neg_hi:[0,1]
	v_cvt_pk_bf16_f32 v184, v182, v183
	s_add_u32 s76, s76, 0x2000
	s_addc_u32 s77, s77, 0
	global_store_dword v105, v184, s[76:77] offset:-3072
	v_lshlrev_b32_e32 v174, 16, v228
	v_and_b32_e32 v175, 0xffff0000, v228
	v_lshlrev_b32_e32 v176, 16, v226
	v_and_b32_e32 v177, 0xffff0000, v226
	v_pk_add_f32 v[178:179], v[174:175], v[176:177] neg_lo:[0,1] neg_hi:[0,1]
	v_pk_add_f32 v[172:173], v[172:173], v[178:179]
	v_pk_mul_f32 v[180:181], v[172:173], s[72:73] op_sel_hi:[1,0]
	v_pk_add_f32 v[182:183], v[180:181], v[174:175] neg_lo:[0,1] neg_hi:[0,1]
	v_cvt_pk_bf16_f32 v185, v182, v183
	global_store_dword v105, v185, s[76:77] offset:-1024
	v_lshlrev_b32_e32 v174, 16, v229
	v_and_b32_e32 v175, 0xffff0000, v229
	v_lshlrev_b32_e32 v176, 16, v227
	v_and_b32_e32 v177, 0xffff0000, v227
	v_pk_add_f32 v[178:179], v[174:175], v[176:177] neg_lo:[0,1] neg_hi:[0,1]
	v_pk_add_f32 v[172:173], v[172:173], v[178:179]
	v_pk_mul_f32 v[180:181], v[172:173], s[72:73] op_sel_hi:[1,0]
	v_pk_add_f32 v[182:183], v[180:181], v[174:175] neg_lo:[0,1] neg_hi:[0,1]
	v_cvt_pk_bf16_f32 v186, v182, v183
	global_store_dword v105, v186, s[76:77] offset:1024
	v_lshlrev_b32_e32 v174, 16, v230
	v_and_b32_e32 v175, 0xffff0000, v230
	v_lshlrev_b32_e32 v176, 16, v228
	v_and_b32_e32 v177, 0xffff0000, v228
	v_pk_add_f32 v[178:179], v[174:175], v[176:177] neg_lo:[0,1] neg_hi:[0,1]
	v_pk_add_f32 v[172:173], v[172:173], v[178:179]
	v_pk_mul_f32 v[180:181], v[172:173], s[72:73] op_sel_hi:[1,0]
	v_pk_add_f32 v[182:183], v[180:181], v[174:175] neg_lo:[0,1] neg_hi:[0,1]
	v_cvt_pk_bf16_f32 v187, v182, v183
	global_store_dword v105, v187, s[76:77] offset:3072
	v_lshlrev_b32_e32 v174, 16, v231
	v_and_b32_e32 v175, 0xffff0000, v231
	v_lshlrev_b32_e32 v176, 16, v229
	v_and_b32_e32 v177, 0xffff0000, v229
	v_pk_add_f32 v[178:179], v[174:175], v[176:177] neg_lo:[0,1] neg_hi:[0,1]
	v_pk_add_f32 v[172:173], v[172:173], v[178:179]
	v_pk_mul_f32 v[180:181], v[172:173], s[72:73] op_sel_hi:[1,0]
	v_pk_add_f32 v[182:183], v[180:181], v[174:175] neg_lo:[0,1] neg_hi:[0,1]
	v_cvt_pk_bf16_f32 v184, v182, v183
	s_add_u32 s76, s76, 0x2000
	s_addc_u32 s77, s77, 0
	s_waitcnt vmcnt(40)
; __device__ __forceinline__ unsigned pk2(float lo, float hi) { f32x2v v = {lo, hi}; b16x2v b = __builtin_convertvector(v, b16x2v); return __builtin_bit_cast(unsigned, b); }
; __device__ __forceinline__ f32x2v bf2(unsigned v) { return (f32x2v){bflo(v), bfhi(v)}; }
; template <int W>
; __device__ __forceinline__ void pool_prompt_w(const unsigned (&pin)[31], int t0, unsigned* dst  ) {
;     f32x2v s = {0.f, 0.f};
; #pragma unroll
;     for (int i = 0; i < W; ++i) s = s + bf2(pin[15 - i]);
; #pragma unroll
;     for (int t = 0; t < 16; ++t) {
;         if (t > 0) s = s + (bf2(pin[15 + t]) - bf2(pin[15 + t - W]));
;         const float cnt = (float)min(t0 + t + 1, W); const f32x2v cur = bf2(pin[15 + t]);
;         dst[(size_t)t * 512] = pk2(s.x / cnt - cur.x, s.y / cnt - cur.y);
	global_store_dword v105, v184, s[76:77] offset:-3072
	v_lshlrev_b32_e32 v174, 16, v232
	v_and_b32_e32 v175, 0xffff0000, v232
	v_lshlrev_b32_e32 v176, 16, v230
	v_and_b32_e32 v177, 0xffff0000, v230
	v_pk_add_f32 v[178:179], v[174:175], v[176:177] neg_lo:[0,1] neg_hi:[0,1]
	v_pk_add_f32 v[172:173], v[172:173], v[178:179]
	v_pk_mul_f32 v[180:181], v[172:173], s[72:73] op_sel_hi:[1,0]
	v_pk_add_f32 v[182:183], v[180:181], v[174:175] neg_lo:[0,1] neg_hi:[0,1]
	v_cvt_pk_bf16_f32 v185, v182, v183
	global_store_dword v105, v185, s[76:77] offset:-1024
	v_lshlrev_b32_e32 v174, 16, v233
	v_and_b32_e32 v175, 0xffff0000, v233
	v_lshlrev_b32_e32 v176, 16, v231
	v_and_b32_e32 v177, 0xffff0000, v231
	v_pk_add_f32 v[178:179], v[174:175], v[176:177] neg_lo:[0,1] neg_hi:[0,1]
	v_pk_add_f32 v[172:173], v[172:173], v[178:179]
	v_pk_mul_f32 v[180:181], v[172:173], s[72:73] op_sel_hi:[1,0]
	v_pk_add_f32 v[182:183], v[180:181], v[174:175] neg_lo:[0,1] neg_hi:[0,1]
	v_cvt_pk_bf16_f32 v186, v182, v183
	global_store_dword v105, v186, s[76:77] offset:1024
	v_lshlrev_b32_e32 v174, 16, v234
	v_and_b32_e32 v175, 0xffff0000, v234
	v_lshlrev_b32_e32 v176, 16, v232
	v_and_b32_e32 v177, 0xffff0000, v232
	v_pk_add_f32 v[178:179], v[174:175], v[176:177] neg_lo:[0,1] neg_hi:[0,1]
	v_pk_add_f32 v[172:173], v[172:173], v[178:179]
	v_pk_mul_f32 v[180:181], v[172:173], s[72:73] op_sel_hi:[1,0]
	v_pk_add_f32 v[182:183], v[180:181], v[174:175] neg_lo:[0,1] neg_hi:[0,1]
	v_cvt_pk_bf16_f32 v187, v182, v183
	global_store_dword v105, v187, s[76:77] offset:3072
	v_lshlrev_b32_e32 v174, 16, v235
	v_and_b32_e32 v175, 0xffff0000, v235
	v_lshlrev_b32_e32 v176, 16, v233
	v_and_b32_e32 v177, 0xffff0000, v233
	v_pk_add_f32 v[178:179], v[174:175], v[176:177] neg_lo:[0,1] neg_hi:[0,1]
	v_pk_add_f32 v[172:173], v[172:173], v[178:179]
	v_pk_mul_f32 v[180:181], v[172:173], s[72:73] op_sel_hi:[1,0]
	v_pk_add_f32 v[182:183], v[180:181], v[174:175] neg_lo:[0,1] neg_hi:[0,1]
	v_cvt_pk_bf16_f32 v184, v182, v183
	s_add_u32 s76, s76, 0x2000
	s_addc_u32 s77, s77, 0
	global_store_dword v105, v184, s[76:77] offset:-3072
	v_lshlrev_b32_e32 v174, 16, v236
	v_and_b32_e32 v175, 0xffff0000, v236
	v_lshlrev_b32_e32 v176, 16, v234
	v_and_b32_e32 v177, 0xffff0000, v234
	v_pk_add_f32 v[178:179], v[174:175], v[176:177] neg_lo:[0,1] neg_hi:[0,1]
	v_pk_add_f32 v[172:173], v[172:173], v[178:179]
	v_pk_mul_f32 v[180:181], v[172:173], s[72:73] op_sel_hi:[1,0]
	v_pk_add_f32 v[182:183], v[180:181], v[174:175] neg_lo:[0,1] neg_hi:[0,1]
	v_cvt_pk_bf16_f32 v185, v182, v183
	global_store_dword v105, v185, s[76:77] offset:-1024
	v_lshlrev_b32_e32 v174, 16, v237
	v_and_b32_e32 v175, 0xffff0000, v237
	v_lshlrev_b32_e32 v176, 16, v235
	v_and_b32_e32 v177, 0xffff0000, v235
	v_pk_add_f32 v[178:179], v[174:175], v[176:177] neg_lo:[0,1] neg_hi:[0,1]
	v_pk_add_f32 v[172:173], v[172:173], v[178:179]
	v_pk_mul_f32 v[180:181], v[172:173], s[72:73] op_sel_hi:[1,0]
	v_pk_add_f32 v[182:183], v[180:181], v[174:175] neg_lo:[0,1] neg_hi:[0,1]
	v_cvt_pk_bf16_f32 v186, v182, v183
	global_store_dword v105, v186, s[76:77] offset:1024
	v_lshlrev_b32_e32 v174, 16, v238
	v_and_b32_e32 v175, 0xffff0000, v238
	v_lshlrev_b32_e32 v176, 16, v236
	v_and_b32_e32 v177, 0xffff0000, v236
	v_pk_add_f32 v[178:179], v[174:175], v[176:177] neg_lo:[0,1] neg_hi:[0,1]
	v_pk_add_f32 v[172:173], v[172:173], v[178:179]
	v_pk_mul_f32 v[180:181], v[172:173], s[72:73] op_sel_hi:[1,0]
	v_pk_add_f32 v[182:183], v[180:181], v[174:175] neg_lo:[0,1] neg_hi:[0,1]
	v_cvt_pk_bf16_f32 v187, v182, v183
	global_store_dword v105, v187, s[76:77] offset:3072
	s_branch .Lmx_pool_done
.Lmx_ps0_0:
	s_mov_b32 s78, 0x3f800000
	s_mov_b32 s79, 0x3f800000
	v_mul_f32_e32 v180, s79, v172
	v_fma_f32 v240, -v180, s78, v172
	v_fma_f32 v180, v240, s79, v180
	v_mul_f32_e32 v181, s79, v173
	v_fma_f32 v240, -v181, s78, v173
	v_fma_f32 v181, v240, s79, v181
	s_branch .Lmx_pb0_0
.Lmx_pool1:
	v_lshlrev_b32_e32 v172, 16, v223
	v_and_b32_e32 v173, 0xffff0000, v223
	v_lshlrev_b32_e32 v176, 16, v222
	v_and_b32_e32 v177, 0xffff0000, v222
	v_pk_add_f32 v[172:173], v[172:173], v[176:177]
	v_lshlrev_b32_e32 v176, 16, v221
	v_and_b32_e32 v177, 0xffff0000, v221
	v_pk_add_f32 v[172:173], v[172:173], v[176:177]
	v_lshlrev_b32_e32 v176, 16, v220
	v_and_b32_e32 v177, 0xffff0000, v220
	v_pk_add_f32 v[172:173], v[172:173], v[176:177]
	v_lshlrev_b32_e32 v174, 16, v223
	v_and_b32_e32 v175, 0xffff0000, v223
	s_cmp_eq_u32 s64, 0
	s_cbranch_scc1 .Lmx_ps1_0
	v_pk_mul_f32 v[180:181], v[172:173], s[72:73] op_sel_hi:[1,0]
.Lmx_pb1_0:
	v_pk_add_f32 v[182:183], v[180:181], v[174:175] neg_lo:[0,1] neg_hi:[0,1]
	v_cvt_pk_bf16_f32 v184, v182, v183
	global_store_dword v105, v184, s[76:77] offset:-3072
	v_lshlrev_b32_e32 v174, 16, v224
	v_and_b32_e32 v175, 0xffff0000, v224
	v_lshlrev_b32_e32 v176, 16, v220
	v_and_b32_e32 v177, 0xffff0000, v220
	v_pk_add_f32 v[178:179], v[174:175], v[176:177] neg_lo:[0,1] neg_hi:[0,1]
	v_pk_add_f32 v[172:173], v[172:173], v[178:179]
	s_cmp_eq_u32 s64, 0
	s_cbranch_scc1 .Lmx_ps1_1
	v_pk_mul_f32 v[180:181], v[172:173], s[72:73] op_sel_hi:[1,0]
.Lmx_pb1_1:
	v_pk_add_f32 v[182:183], v[180:181], v[174:175] neg_lo:[0,1] neg_hi:[0,1]
	v_cvt_pk_bf16_f32 v185, v182, v183
	global_store_dword v105, v185, s[76:77] offset:-1024
	v_lshlrev_b32_e32 v174, 16, v225
	v_and_b32_e32 v175, 0xffff0000, v225
	v_lshlrev_b32_e32 v176, 16, v221
	v_and_b32_e32 v177, 0xffff0000, v221
	v_pk_add_f32 v[178:179], v[174:175], v[176:177] neg_lo:[0,1] neg_hi:[0,1]
	v_pk_add_f32 v[172:173], v[172:173], v[178:179]
	s_cmp_eq_u32 s64, 0
	s_cbranch_scc1 .Lmx_ps1_2
	v_pk_mul_f32 v[180:181], v[172:173], s[72:73] op_sel_hi:[1,0]
; __device__ __forceinline__ unsigned pk2(float lo, float hi) { f32x2v v = {lo, hi}; b16x2v b = __builtin_convertvector(v, b16x2v); return __builtin_bit_cast(unsigned, b); }
; __device__ __forceinline__ f32x2v bf2(unsigned v) { return (f32x2v){bflo(v), bfhi(v)}; }
; template <int W>
; __device__ __forceinline__ void pool_prompt_w(const unsigned (&pin)[31], int t0, unsigned* dst  ) {
;     f32x2v s = {0.f, 0.f};
; #pragma unroll
;     for (int i = 0; i < W; ++i) s = s + bf2(pin[15 - i]);
; #pragma unroll
;     for (int t = 0; t < 16; ++t) {
;         if (t > 0) s = s + (bf2(pin[15 + t]) - bf2(pin[15 + t - W]));
;         const float cnt = (float)min(t0 + t + 1, W); const f32x2v cur = bf2(pin[15 + t]);
;         dst[(size_t)t * 512] = pk2(s.x / cnt - cur.x, s.y / cnt - cur.y);
;     }
; }
.Lmx_pb1_2:
	v_pk_add_f32 v[182:183], v[180:181], v[174:175] neg_lo:[0,1] neg_hi:[0,1]
	v_cvt_pk_bf16_f32 v186, v182, v183
	global_store_dword v105, v186, s[76:77] offset:1024
	v_lshlrev_b32_e32 v174, 16, v226
	v_and_b32_e32 v175, 0xffff0000, v226
	v_lshlrev_b32_e32 v176, 16, v222
	v_and_b32_e32 v177, 0xffff0000, v222
	v_pk_add_f32 v[178:179], v[174:175], v[176:177] neg_lo:[0,1] neg_hi:[0,1]
	v_pk_add_f32 v[172:173], v[172:173], v[178:179]
	v_pk_mul_f32 v[180:181], v[172:173], s[72:73] op_sel_hi:[1,0]
	v_pk_add_f32 v[182:183], v[180:181], v[174:175] neg_lo:[0,1] neg_hi:[0,1]
	v_cvt_pk_bf16_f32 v187, v182, v183
	global_store_dword v105, v187, s[76:77] offset:3072
	v_lshlrev_b32_e32 v174, 16, v227
	v_and_b32_e32 v175, 0xffff0000, v227
	v_lshlrev_b32_e32 v176, 16, v223
	v_and_b32_e32 v177, 0xffff0000, v223
	v_pk_add_f32 v[178:179], v[174:175], v[176:177] neg_lo:[0,1] neg_hi:[0,1]
	v_pk_add_f32 v[172:173], v[172:173], v[178:179]
	v_pk_mul_f32 v[180:181], v[172:173], s[72:73] op_sel_hi:[1,0]
	v_pk_add_f32 v[182:183], v[180:181], v[174:175] neg_lo:[0,1] neg_hi:[0,1]
	v_cvt_pk_bf16_f32 v184, v182, v183
	s_add_u32 s76, s76, 0x2000
	s_addc_u32 s77, s77, 0
	global_store_dword v105, v184, s[76:77] offset:-3072
	v_lshlrev_b32_e32 v174, 16, v228
	v_and_b32_e32 v175, 0xffff0000, v228
	v_lshlrev_b32_e32 v176, 16, v224
	v_and_b32_e32 v177, 0xffff0000, v224
	v_pk_add_f32 v[178:179], v[174:175], v[176:177] neg_lo:[0,1] neg_hi:[0,1]
	v_pk_add_f32 v[172:173], v[172:173], v[178:179]
	v_pk_mul_f32 v[180:181], v[172:173], s[72:73] op_sel_hi:[1,0]
	v_pk_add_f32 v[182:183], v[180:181], v[174:175] neg_lo:[0,1] neg_hi:[0,1]
	v_cvt_pk_bf16_f32 v185, v182, v183
	global_store_dword v105, v185, s[76:77] offset:-1024
	v_lshlrev_b32_e32 v174, 16, v229
	v_and_b32_e32 v175, 0xffff0000, v229
	v_lshlrev_b32_e32 v176, 16, v225
	v_and_b32_e32 v177, 0xffff0000, v225
	v_pk_add_f32 v[178:179], v[174:175], v[176:177] neg_lo:[0,1] neg_hi:[0,1]
	v_pk_add_f32 v[172:173], v[172:173], v[178:179]
	v_pk_mul_f32 v[180:181], v[172:173], s[72:73] op_sel_hi:[1,0]
	v_pk_add_f32 v[182:183], v[180:181], v[174:175] neg_lo:[0,1] neg_hi:[0,1]
	v_cvt_pk_bf16_f32 v186, v182, v183
	global_store_dword v105, v186, s[76:77] offset:1024
	v_lshlrev_b32_e32 v174, 16, v230
	v_and_b32_e32 v175, 0xffff0000, v230
	v_lshlrev_b32_e32 v176, 16, v226
	v_and_b32_e32 v177, 0xffff0000, v226
	v_pk_add_f32 v[178:179], v[174:175], v[176:177] neg_lo:[0,1] neg_hi:[0,1]
	v_pk_add_f32 v[172:173], v[172:173], v[178:179]
	v_pk_mul_f32 v[180:181], v[172:173], s[72:73] op_sel_hi:[1,0]
	v_pk_add_f32 v[182:183], v[180:181], v[174:175] neg_lo:[0,1] neg_hi:[0,1]
	v_cvt_pk_bf16_f32 v187, v182, v183
	global_store_dword v105, v187, s[76:77] offset:3072
	v_lshlrev_b32_e32 v174, 16, v231
	v_and_b32_e32 v175, 0xffff0000, v231
	v_lshlrev_b32_e32 v176, 16, v227
	v_and_b32_e32 v177, 0xffff0000, v227
	v_pk_add_f32 v[178:179], v[174:175], v[176:177] neg_lo:[0,1] neg_hi:[0,1]
	v_pk_add_f32 v[172:173], v[172:173], v[178:179]
	v_pk_mul_f32 v[180:181], v[172:173], s[72:73] op_sel_hi:[1,0]
	v_pk_add_f32 v[182:183], v[180:181], v[174:175] neg_lo:[0,1] neg_hi:[0,1]
	v_cvt_pk_bf16_f32 v184, v182, v183
	s_add_u32 s76, s76, 0x2000
	s_addc_u32 s77, s77, 0
	s_waitcnt vmcnt(40)
	global_store_dword v105, v184, s[76:77] offset:-3072
	v_lshlrev_b32_e32 v174, 16, v232
	v_and_b32_e32 v175, 0xffff0000, v232
	v_lshlrev_b32_e32 v176, 16, v228
	v_and_b32_e32 v177, 0xffff0000, v228
	v_pk_add_f32 v[178:179], v[174:175], v[176:177] neg_lo:[0,1] neg_hi:[0,1]
	v_pk_add_f32 v[172:173], v[172:173], v[178:179]
	v_pk_mul_f32 v[180:181], v[172:173], s[72:73] op_sel_hi:[1,0]
	v_pk_add_f32 v[182:183], v[180:181], v[174:175] neg_lo:[0,1] neg_hi:[0,1]
	v_cvt_pk_bf16_f32 v185, v182, v183
	global_store_dword v105, v185, s[76:77] offset:-1024
	v_lshlrev_b32_e32 v174, 16, v233
	v_and_b32_e32 v175, 0xffff0000, v233
	v_lshlrev_b32_e32 v176, 16, v229
	v_and_b32_e32 v177, 0xffff0000, v229
	v_pk_add_f32 v[178:179], v[174:175], v[176:177] neg_lo:[0,1] neg_hi:[0,1]
	v_pk_add_f32 v[172:173], v[172:173], v[178:179]
	v_pk_mul_f32 v[180:181], v[172:173], s[72:73] op_sel_hi:[1,0]
	v_pk_add_f32 v[182:183], v[180:181], v[174:175] neg_lo:[0,1] neg_hi:[0,1]
	v_cvt_pk_bf16_f32 v186, v182, v183
	global_store_dword v105, v186, s[76:77] offset:1024
	v_lshlrev_b32_e32 v174, 16, v234
	v_and_b32_e32 v175, 0xffff0000, v234
	v_lshlrev_b32_e32 v176, 16, v230
	v_and_b32_e32 v177, 0xffff0000, v230
	v_pk_add_f32 v[178:179], v[174:175], v[176:177] neg_lo:[0,1] neg_hi:[0,1]
	v_pk_add_f32 v[172:173], v[172:173], v[178:179]
	v_pk_mul_f32 v[180:181], v[172:173], s[72:73] op_sel_hi:[1,0]
	v_pk_add_f32 v[182:183], v[180:181], v[174:175] neg_lo:[0,1] neg_hi:[0,1]
	v_cvt_pk_bf16_f32 v187, v182, v183
	global_store_dword v105, v187, s[76:77] offset:3072
	v_lshlrev_b32_e32 v174, 16, v235
	v_and_b32_e32 v175, 0xffff0000, v235
	v_lshlrev_b32_e32 v176, 16, v231
	v_and_b32_e32 v177, 0xffff0000, v231
	v_pk_add_f32 v[178:179], v[174:175], v[176:177] neg_lo:[0,1] neg_hi:[0,1]
	v_pk_add_f32 v[172:173], v[172:173], v[178:179]
	v_pk_mul_f32 v[180:181], v[172:173], s[72:73] op_sel_hi:[1,0]
	v_pk_add_f32 v[182:183], v[180:181], v[174:175] neg_lo:[0,1] neg_hi:[0,1]
	v_cvt_pk_bf16_f32 v184, v182, v183
	s_add_u32 s76, s76, 0x2000
	s_addc_u32 s77, s77, 0
	global_store_dword v105, v184, s[76:77] offset:-3072
	v_lshlrev_b32_e32 v174, 16, v236
	v_and_b32_e32 v175, 0xffff0000, v236
	v_lshlrev_b32_e32 v176, 16, v232
	v_and_b32_e32 v177, 0xffff0000, v232
	v_pk_add_f32 v[178:179], v[174:175], v[176:177] neg_lo:[0,1] neg_hi:[0,1]
	v_pk_add_f32 v[172:173], v[172:173], v[178:179]
	v_pk_mul_f32 v[180:181], v[172:173], s[72:73] op_sel_hi:[1,0]
	v_pk_add_f32 v[182:183], v[180:181], v[174:175] neg_lo:[0,1] neg_hi:[0,1]
	v_cvt_pk_bf16_f32 v185, v182, v183
	global_store_dword v105, v185, s[76:77] offset:-1024
	v_lshlrev_b32_e32 v174, 16, v237
	v_and_b32_e32 v175, 0xffff0000, v237
	v_lshlrev_b32_e32 v176, 16, v233
	v_and_b32_e32 v177, 0xffff0000, v233
	v_pk_add_f32 v[178:179], v[174:175], v[176:177] neg_lo:[0,1] neg_hi:[0,1]
	v_pk_add_f32 v[172:173], v[172:173], v[178:179]
	v_pk_mul_f32 v[180:181], v[172:173], s[72:73] op_sel_hi:[1,0]
	v_pk_add_f32 v[182:183], v[180:181], v[174:175] neg_lo:[0,1] neg_hi:[0,1]
	v_cvt_pk_bf16_f32 v186, v182, v183
	global_store_dword v105, v186, s[76:77] offset:1024
	v_lshlrev_b32_e32 v174, 16, v238
	v_and_b32_e32 v175, 0xffff0000, v238
	v_lshlrev_b32_e32 v176, 16, v234
	v_and_b32_e32 v177, 0xffff0000, v234
	v_pk_add_f32 v[178:179], v[174:175], v[176:177] neg_lo:[0,1] neg_hi:[0,1]
	v_pk_add_f32 v[172:173], v[172:173], v[178:179]
	v_pk_mul_f32 v[180:181], v[172:173], s[72:73] op_sel_hi:[1,0]
	v_pk_add_f32 v[182:183], v[180:181], v[174:175] neg_lo:[0,1] neg_hi:[0,1]
	v_cvt_pk_bf16_f32 v187, v182, v183
	global_store_dword v105, v187, s[76:77] offset:3072
	s_branch .Lmx_pool_done

; __device__ __forceinline__ unsigned pk2(float lo, float hi) { f32x2v v = {lo, hi}; b16x2v b = __builtin_convertvector(v, b16x2v); return __builtin_bit_cast(unsigned, b); }
; __device__ __forceinline__ f32x2v bf2(unsigned v) { return (f32x2v){bflo(v), bfhi(v)}; }
; template <int W>
; __device__ __forceinline__ void pool_prompt_w(const unsigned (&pin)[31], int t0, unsigned* dst  ) {
;     f32x2v s = {0.f, 0.f};
; #pragma unroll
;     for (int i = 0; i < W; ++i) s = s + bf2(pin[15 - i]);
; #pragma unroll
;     for (int t = 0; t < 16; ++t) {
;         if (t > 0) s = s + (bf2(pin[15 + t]) - bf2(pin[15 + t - W]));
;         const float cnt = (float)min(t0 + t + 1, W); const f32x2v cur = bf2(pin[15 + t]);
;         dst[(size_t)t * 512] = pk2(s.x / cnt - cur.x, s.y / cnt - cur.y);
;     }
; }
.Lmx_ps1_1:
	s_mov_b32 s78, 0x40000000
	s_mov_b32 s79, 0x3f000000
	v_mul_f32_e32 v180, s79, v172
	v_fma_f32 v240, -v180, s78, v172
	v_fma_f32 v180, v240, s79, v180
	v_mul_f32_e32 v181, s79, v173
	v_fma_f32 v240, -v181, s78, v173
	v_fma_f32 v181, v240, s79, v181
	s_branch .Lmx_pb1_1
.Lmx_ps1_2:
	s_mov_b32 s78, 0x40400000
	s_mov_b32 s79, 0x3eaaaaab
	v_mul_f32_e32 v180, s79, v172
	v_fma_f32 v240, -v180, s78, v172
	v_fma_f32 v180, v240, s79, v180
	v_mul_f32_e32 v181, s79, v173
	v_fma_f32 v240, -v181, s78, v173
	v_fma_f32 v181, v240, s79, v181
	s_branch .Lmx_pb1_2
.Lmx_pool2:
	v_lshlrev_b32_e32 v172, 16, v223
	v_and_b32_e32 v173, 0xffff0000, v223
	v_lshlrev_b32_e32 v176, 16, v222
	v_and_b32_e32 v177, 0xffff0000, v222
	v_pk_add_f32 v[172:173], v[172:173], v[176:177]
	v_lshlrev_b32_e32 v176, 16, v221
	v_and_b32_e32 v177, 0xffff0000, v221
	v_pk_add_f32 v[172:173], v[172:173], v[176:177]
	v_lshlrev_b32_e32 v176, 16, v220
	v_and_b32_e32 v177, 0xffff0000, v220
	v_pk_add_f32 v[172:173], v[172:173], v[176:177]
	v_lshlrev_b32_e32 v176, 16, v219
	v_and_b32_e32 v177, 0xffff0000, v219
	v_pk_add_f32 v[172:173], v[172:173], v[176:177]
	v_lshlrev_b32_e32 v176, 16, v218
	v_and_b32_e32 v177, 0xffff0000, v218
	v_pk_add_f32 v[172:173], v[172:173], v[176:177]
	v_lshlrev_b32_e32 v176, 16, v217
	v_and_b32_e32 v177, 0xffff0000, v217
	v_pk_add_f32 v[172:173], v[172:173], v[176:177]
	v_lshlrev_b32_e32 v176, 16, v216
	v_and_b32_e32 v177, 0xffff0000, v216
	v_pk_add_f32 v[172:173], v[172:173], v[176:177]
	v_lshlrev_b32_e32 v174, 16, v223
	v_and_b32_e32 v175, 0xffff0000, v223
	s_cmp_eq_u32 s64, 0
	s_cbranch_scc1 .Lmx_ps2_0
	v_pk_mul_f32 v[180:181], v[172:173], s[72:73] op_sel_hi:[1,0]
.Lmx_pb2_0:
	v_pk_add_f32 v[182:183], v[180:181], v[174:175] neg_lo:[0,1] neg_hi:[0,1]
	v_cvt_pk_bf16_f32 v184, v182, v183
	global_store_dword v105, v184, s[76:77] offset:-3072
	v_lshlrev_b32_e32 v174, 16, v224
	v_and_b32_e32 v175, 0xffff0000, v224
	v_lshlrev_b32_e32 v176, 16, v216
	v_and_b32_e32 v177, 0xffff0000, v216
	v_pk_add_f32 v[178:179], v[174:175], v[176:177] neg_lo:[0,1] neg_hi:[0,1]
	v_pk_add_f32 v[172:173], v[172:173], v[178:179]
	s_cmp_eq_u32 s64, 0
	s_cbranch_scc1 .Lmx_ps2_1
	v_pk_mul_f32 v[180:181], v[172:173], s[72:73] op_sel_hi:[1,0]
.Lmx_pb2_1:
	v_pk_add_f32 v[182:183], v[180:181], v[174:175] neg_lo:[0,1] neg_hi:[0,1]
	v_cvt_pk_bf16_f32 v185, v182, v183
	global_store_dword v105, v185, s[76:77] offset:-1024
	v_lshlrev_b32_e32 v174, 16, v225
	v_and_b32_e32 v175, 0xffff0000, v225
	v_lshlrev_b32_e32 v176, 16, v217
	v_and_b32_e32 v177, 0xffff0000, v217
	v_pk_add_f32 v[178:179], v[174:175], v[176:177] neg_lo:[0,1] neg_hi:[0,1]
	v_pk_add_f32 v[172:173], v[172:173], v[178:179]
	s_cmp_eq_u32 s64, 0
	s_cbranch_scc1 .Lmx_ps2_2
	v_pk_mul_f32 v[180:181], v[172:173], s[72:73] op_sel_hi:[1,0]
.Lmx_pb2_2:
	v_pk_add_f32 v[182:183], v[180:181], v[174:175] neg_lo:[0,1] neg_hi:[0,1]
	v_cvt_pk_bf16_f32 v186, v182, v183
	global_store_dword v105, v186, s[76:77] offset:1024
	v_lshlrev_b32_e32 v174, 16, v226
	v_and_b32_e32 v175, 0xffff0000, v226
	v_lshlrev_b32_e32 v176, 16, v218
	v_and_b32_e32 v177, 0xffff0000, v218
	v_pk_add_f32 v[178:179], v[174:175], v[176:177] neg_lo:[0,1] neg_hi:[0,1]
	v_pk_add_f32 v[172:173], v[172:173], v[178:179]
	s_cmp_eq_u32 s64, 0
	s_cbranch_scc1 .Lmx_ps2_3
	v_pk_mul_f32 v[180:181], v[172:173], s[72:73] op_sel_hi:[1,0]
.Lmx_pb2_3:
	v_pk_add_f32 v[182:183], v[180:181], v[174:175] neg_lo:[0,1] neg_hi:[0,1]
	v_cvt_pk_bf16_f32 v187, v182, v183
	global_store_dword v105, v187, s[76:77] offset:3072
	v_lshlrev_b32_e32 v174, 16, v227
	v_and_b32_e32 v175, 0xffff0000, v227
	v_lshlrev_b32_e32 v176, 16, v219
	v_and_b32_e32 v177, 0xffff0000, v219
	v_pk_add_f32 v[178:179], v[174:175], v[176:177] neg_lo:[0,1] neg_hi:[0,1]
	v_pk_add_f32 v[172:173], v[172:173], v[178:179]
	s_cmp_eq_u32 s64, 0
	s_cbranch_scc1 .Lmx_ps2_4
	v_pk_mul_f32 v[180:181], v[172:173], s[72:73] op_sel_hi:[1,0]
.Lmx_pb2_4:
	v_pk_add_f32 v[182:183], v[180:181], v[174:175] neg_lo:[0,1] neg_hi:[0,1]
	v_cvt_pk_bf16_f32 v184, v182, v183
	s_add_u32 s76, s76, 0x2000
	s_addc_u32 s77, s77, 0
	global_store_dword v105, v184, s[76:77] offset:-3072
	v_lshlrev_b32_e32 v174, 16, v228
	v_and_b32_e32 v175, 0xffff0000, v228
	v_lshlrev_b32_e32 v176, 16, v220
	v_and_b32_e32 v177, 0xffff0000, v220
	v_pk_add_f32 v[178:179], v[174:175], v[176:177] neg_lo:[0,1] neg_hi:[0,1]
	v_pk_add_f32 v[172:173], v[172:173], v[178:179]
	s_cmp_eq_u32 s64, 0
	s_cbranch_scc1 .Lmx_ps2_5
	v_pk_mul_f32 v[180:181], v[172:173], s[72:73] op_sel_hi:[1,0]
.Lmx_pb2_5:
	v_pk_add_f32 v[182:183], v[180:181], v[174:175] neg_lo:[0,1] neg_hi:[0,1]
	v_cvt_pk_bf16_f32 v185, v182, v183
	global_store_dword v105, v185, s[76:77] offset:-1024
	v_lshlrev_b32_e32 v174, 16, v229
	v_and_b32_e32 v175, 0xffff0000, v229
	v_lshlrev_b32_e32 v176, 16, v221
	v_and_b32_e32 v177, 0xffff0000, v221
	v_pk_add_f32 v[178:179], v[174:175], v[176:177] neg_lo:[0,1] neg_hi:[0,1]
	v_pk_add_f32 v[172:173], v[172:173], v[178:179]
	s_cmp_eq_u32 s64, 0
	s_cbranch_scc1 .Lmx_ps2_6
	v_pk_mul_f32 v[180:181], v[172:173], s[72:73] op_sel_hi:[1,0]
; __device__ __forceinline__ unsigned pk2(float lo, float hi) { f32x2v v = {lo, hi}; b16x2v b = __builtin_convertvector(v, b16x2v); return __builtin_bit_cast(unsigned, b); }
; __device__ __forceinline__ f32x2v bf2(unsigned v) { return (f32x2v){bflo(v), bfhi(v)}; }
; template <int W>
; __device__ __forceinline__ void pool_prompt_w(const unsigned (&pin)[31], int t0, unsigned* dst  ) {
;     f32x2v s = {0.f, 0.f};
; #pragma unroll
;     for (int i = 0; i < W; ++i) s = s + bf2(pin[15 - i]);
; #pragma unroll
;     for (int t = 0; t < 16; ++t) {
;         if (t > 0) s = s + (bf2(pin[15 + t]) - bf2(pin[15 + t - W]));
;         const float cnt = (float)min(t0 + t + 1, W); const f32x2v cur = bf2(pin[15 + t]);
;         dst[(size_t)t * 512] = pk2(s.x / cnt - cur.x, s.y / cnt - cur.y);
;     }
; }
.Lmx_pb2_6:
	v_pk_add_f32 v[182:183], v[180:181], v[174:175] neg_lo:[0,1] neg_hi:[0,1]
	v_cvt_pk_bf16_f32 v186, v182, v183
	global_store_dword v105, v186, s[76:77] offset:1024
	v_lshlrev_b32_e32 v174, 16, v230
	v_and_b32_e32 v175, 0xffff0000, v230
	v_lshlrev_b32_e32 v176, 16, v222
	v_and_b32_e32 v177, 0xffff0000, v222
	v_pk_add_f32 v[178:179], v[174:175], v[176:177] neg_lo:[0,1] neg_hi:[0,1]
	v_pk_add_f32 v[172:173], v[172:173], v[178:179]
	v_pk_mul_f32 v[180:181], v[172:173], s[72:73] op_sel_hi:[1,0]
	v_pk_add_f32 v[182:183], v[180:181], v[174:175] neg_lo:[0,1] neg_hi:[0,1]
	v_cvt_pk_bf16_f32 v187, v182, v183
	global_store_dword v105, v187, s[76:77] offset:3072
	v_lshlrev_b32_e32 v174, 16, v231
	v_and_b32_e32 v175, 0xffff0000, v231
	v_lshlrev_b32_e32 v176, 16, v223
	v_and_b32_e32 v177, 0xffff0000, v223
	v_pk_add_f32 v[178:179], v[174:175], v[176:177] neg_lo:[0,1] neg_hi:[0,1]
	v_pk_add_f32 v[172:173], v[172:173], v[178:179]
	v_pk_mul_f32 v[180:181], v[172:173], s[72:73] op_sel_hi:[1,0]
	v_pk_add_f32 v[182:183], v[180:181], v[174:175] neg_lo:[0,1] neg_hi:[0,1]
	v_cvt_pk_bf16_f32 v184, v182, v183
	s_add_u32 s76, s76, 0x2000
	s_addc_u32 s77, s77, 0
	s_waitcnt vmcnt(40)
	global_store_dword v105, v184, s[76:77] offset:-3072
	v_lshlrev_b32_e32 v174, 16, v232
	v_and_b32_e32 v175, 0xffff0000, v232
	v_lshlrev_b32_e32 v176, 16, v224
	v_and_b32_e32 v177, 0xffff0000, v224
	v_pk_add_f32 v[178:179], v[174:175], v[176:177] neg_lo:[0,1] neg_hi:[0,1]
	v_pk_add_f32 v[172:173], v[172:173], v[178:179]
	v_pk_mul_f32 v[180:181], v[172:173], s[72:73] op_sel_hi:[1,0]
	v_pk_add_f32 v[182:183], v[180:181], v[174:175] neg_lo:[0,1] neg_hi:[0,1]
	v_cvt_pk_bf16_f32 v185, v182, v183
	global_store_dword v105, v185, s[76:77] offset:-1024
	v_lshlrev_b32_e32 v174, 16, v233
	v_and_b32_e32 v175, 0xffff0000, v233
	v_lshlrev_b32_e32 v176, 16, v225
	v_and_b32_e32 v177, 0xffff0000, v225
	v_pk_add_f32 v[178:179], v[174:175], v[176:177] neg_lo:[0,1] neg_hi:[0,1]
	v_pk_add_f32 v[172:173], v[172:173], v[178:179]
	v_pk_mul_f32 v[180:181], v[172:173], s[72:73] op_sel_hi:[1,0]
	v_pk_add_f32 v[182:183], v[180:181], v[174:175] neg_lo:[0,1] neg_hi:[0,1]
	v_cvt_pk_bf16_f32 v186, v182, v183
	global_store_dword v105, v186, s[76:77] offset:1024
	v_lshlrev_b32_e32 v174, 16, v234
	v_and_b32_e32 v175, 0xffff0000, v234
	v_lshlrev_b32_e32 v176, 16, v226
	v_and_b32_e32 v177, 0xffff0000, v226
	v_pk_add_f32 v[178:179], v[174:175], v[176:177] neg_lo:[0,1] neg_hi:[0,1]
	v_pk_add_f32 v[172:173], v[172:173], v[178:179]
	v_pk_mul_f32 v[180:181], v[172:173], s[72:73] op_sel_hi:[1,0]
	v_pk_add_f32 v[182:183], v[180:181], v[174:175] neg_lo:[0,1] neg_hi:[0,1]
	v_cvt_pk_bf16_f32 v187, v182, v183
	global_store_dword v105, v187, s[76:77] offset:3072
	v_lshlrev_b32_e32 v174, 16, v235
	v_and_b32_e32 v175, 0xffff0000, v235
	v_lshlrev_b32_e32 v176, 16, v227
	v_and_b32_e32 v177, 0xffff0000, v227
	v_pk_add_f32 v[178:179], v[174:175], v[176:177] neg_lo:[0,1] neg_hi:[0,1]
	v_pk_add_f32 v[172:173], v[172:173], v[178:179]
	v_pk_mul_f32 v[180:181], v[172:173], s[72:73] op_sel_hi:[1,0]
	v_pk_add_f32 v[182:183], v[180:181], v[174:175] neg_lo:[0,1] neg_hi:[0,1]
	v_cvt_pk_bf16_f32 v184, v182, v183
	s_add_u32 s76, s76, 0x2000
	s_addc_u32 s77, s77, 0
	global_store_dword v105, v184, s[76:77] offset:-3072
	v_lshlrev_b32_e32 v174, 16, v236
	v_and_b32_e32 v175, 0xffff0000, v236
	v_lshlrev_b32_e32 v176, 16, v228
	v_and_b32_e32 v177, 0xffff0000, v228
	v_pk_add_f32 v[178:179], v[174:175], v[176:177] neg_lo:[0,1] neg_hi:[0,1]
	v_pk_add_f32 v[172:173], v[172:173], v[178:179]
	v_pk_mul_f32 v[180:181], v[172:173], s[72:73] op_sel_hi:[1,0]
	v_pk_add_f32 v[182:183], v[180:181], v[174:175] neg_lo:[0,1] neg_hi:[0,1]
	v_cvt_pk_bf16_f32 v185, v182, v183
	global_store_dword v105, v185, s[76:77] offset:-1024
	v_lshlrev_b32_e32 v174, 16, v237
	v_and_b32_e32 v175, 0xffff0000, v237
	v_lshlrev_b32_e32 v176, 16, v229
	v_and_b32_e32 v177, 0xffff0000, v229
	v_pk_add_f32 v[178:179], v[174:175], v[176:177] neg_lo:[0,1] neg_hi:[0,1]
	v_pk_add_f32 v[172:173], v[172:173], v[178:179]
	v_pk_mul_f32 v[180:181], v[172:173], s[72:73] op_sel_hi:[1,0]
	v_pk_add_f32 v[182:183], v[180:181], v[174:175] neg_lo:[0,1] neg_hi:[0,1]
	v_cvt_pk_bf16_f32 v186, v182, v183
	global_store_dword v105, v186, s[76:77] offset:1024
	v_lshlrev_b32_e32 v174, 16, v238
	v_and_b32_e32 v175, 0xffff0000, v238
	v_lshlrev_b32_e32 v176, 16, v230
	v_and_b32_e32 v177, 0xffff0000, v230
	v_pk_add_f32 v[178:179], v[174:175], v[176:177] neg_lo:[0,1] neg_hi:[0,1]
	v_pk_add_f32 v[172:173], v[172:173], v[178:179]
	v_pk_mul_f32 v[180:181], v[172:173], s[72:73] op_sel_hi:[1,0]
	v_pk_add_f32 v[182:183], v[180:181], v[174:175] neg_lo:[0,1] neg_hi:[0,1]
	v_cvt_pk_bf16_f32 v187, v182, v183
	global_store_dword v105, v187, s[76:77] offset:3072
	s_branch .Lmx_pool_done

; __device__ __forceinline__ unsigned pk2(float lo, float hi) { f32x2v v = {lo, hi}; b16x2v b = __builtin_convertvector(v, b16x2v); return __builtin_bit_cast(unsigned, b); }
; __device__ __forceinline__ f32x2v bf2(unsigned v) { return (f32x2v){bflo(v), bfhi(v)}; }
; template <int W>
; __device__ __forceinline__ void pool_prompt_w(const unsigned (&pin)[31], int t0, unsigned* dst  ) {
;     f32x2v s = {0.f, 0.f};
; #pragma unroll
;     for (int i = 0; i < W; ++i) s = s + bf2(pin[15 - i]);
; #pragma unroll
;     for (int t = 0; t < 16; ++t) {
;         if (t > 0) s = s + (bf2(pin[15 + t]) - bf2(pin[15 + t - W]));
;         const float cnt = (float)min(t0 + t + 1, W); const f32x2v cur = bf2(pin[15 + t]);
;         dst[(size_t)t * 512] = pk2(s.x / cnt - cur.x, s.y / cnt - cur.y);
;     }
; }
.Lmx_ps2_3:
	s_mov_b32 s78, 0x40800000
	s_mov_b32 s79, 0x3e800000
	v_mul_f32_e32 v180, s79, v172
	v_fma_f32 v240, -v180, s78, v172
	v_fma_f32 v180, v240, s79, v180
	v_mul_f32_e32 v181, s79, v173
	v_fma_f32 v240, -v181, s78, v173
	v_fma_f32 v181, v240, s79, v181
	s_branch .Lmx_pb2_3
.Lmx_ps2_4:
	s_mov_b32 s78, 0x40a00000
	s_mov_b32 s79, 0x3e4ccccd
	v_mul_f32_e32 v180, s79, v172
	v_fma_f32 v240, -v180, s78, v172
	v_fma_f32 v180, v240, s79, v180
	v_mul_f32_e32 v181, s79, v173
	v_fma_f32 v240, -v181, s78, v173
	v_fma_f32 v181, v240, s79, v181
	s_branch .Lmx_pb2_4
.Lmx_ps2_5:
	s_mov_b32 s78, 0x40c00000
	s_mov_b32 s79, 0x3e2aaaab
	v_mul_f32_e32 v180, s79, v172
	v_fma_f32 v240, -v180, s78, v172
	v_fma_f32 v180, v240, s79, v180
	v_mul_f32_e32 v181, s79, v173
	v_fma_f32 v240, -v181, s78, v173
	v_fma_f32 v181, v240, s79, v181
	s_branch .Lmx_pb2_5
.Lmx_ps2_6:
	s_mov_b32 s78, 0x40e00000
	s_mov_b32 s79, 0x3e124925
	v_mul_f32_e32 v180, s79, v172
	v_fma_f32 v240, -v180, s78, v172
	v_fma_f32 v180, v240, s79, v180
	v_mul_f32_e32 v181, s79, v173
	v_fma_f32 v240, -v181, s78, v173
	v_fma_f32 v181, v240, s79, v181
	s_branch .Lmx_pb2_6
.Lmx_pool3:
	v_lshlrev_b32_e32 v172, 16, v223
	v_and_b32_e32 v173, 0xffff0000, v223
	v_lshlrev_b32_e32 v176, 16, v222
	v_and_b32_e32 v177, 0xffff0000, v222
	v_pk_add_f32 v[172:173], v[172:173], v[176:177]
	v_lshlrev_b32_e32 v176, 16, v221
	v_and_b32_e32 v177, 0xffff0000, v221
	v_pk_add_f32 v[172:173], v[172:173], v[176:177]
	v_lshlrev_b32_e32 v176, 16, v220
	v_and_b32_e32 v177, 0xffff0000, v220
	v_pk_add_f32 v[172:173], v[172:173], v[176:177]
	v_lshlrev_b32_e32 v176, 16, v219
	v_and_b32_e32 v177, 0xffff0000, v219
	v_pk_add_f32 v[172:173], v[172:173], v[176:177]
	v_lshlrev_b32_e32 v176, 16, v218
	v_and_b32_e32 v177, 0xffff0000, v218
	v_pk_add_f32 v[172:173], v[172:173], v[176:177]
	v_lshlrev_b32_e32 v176, 16, v217
	v_and_b32_e32 v177, 0xffff0000, v217
	v_pk_add_f32 v[172:173], v[172:173], v[176:177]
	v_lshlrev_b32_e32 v176, 16, v216
	v_and_b32_e32 v177, 0xffff0000, v216
	v_pk_add_f32 v[172:173], v[172:173], v[176:177]
	v_lshlrev_b32_e32 v176, 16, v215
	v_and_b32_e32 v177, 0xffff0000, v215
	v_pk_add_f32 v[172:173], v[172:173], v[176:177]
	v_lshlrev_b32_e32 v176, 16, v214
	v_and_b32_e32 v177, 0xffff0000, v214
	v_pk_add_f32 v[172:173], v[172:173], v[176:177]
	v_lshlrev_b32_e32 v176, 16, v213
	v_and_b32_e32 v177, 0xffff0000, v213
	v_pk_add_f32 v[172:173], v[172:173], v[176:177]
	v_lshlrev_b32_e32 v176, 16, v212
	v_and_b32_e32 v177, 0xffff0000, v212
	v_pk_add_f32 v[172:173], v[172:173], v[176:177]
	v_lshlrev_b32_e32 v176, 16, v211
	v_and_b32_e32 v177, 0xffff0000, v211
	v_pk_add_f32 v[172:173], v[172:173], v[176:177]
	v_lshlrev_b32_e32 v176, 16, v210
	v_and_b32_e32 v177, 0xffff0000, v210
	v_pk_add_f32 v[172:173], v[172:173], v[176:177]
	v_lshlrev_b32_e32 v176, 16, v209
	v_and_b32_e32 v177, 0xffff0000, v209
	v_pk_add_f32 v[172:173], v[172:173], v[176:177]
	v_lshlrev_b32_e32 v176, 16, v208
	v_and_b32_e32 v177, 0xffff0000, v208
	v_pk_add_f32 v[172:173], v[172:173], v[176:177]
	v_lshlrev_b32_e32 v174, 16, v223
	v_and_b32_e32 v175, 0xffff0000, v223
	s_cmp_eq_u32 s64, 0
	s_cbranch_scc1 .Lmx_ps3_0
	v_pk_mul_f32 v[180:181], v[172:173], s[72:73] op_sel_hi:[1,0]
.Lmx_pb3_0:
	v_pk_add_f32 v[182:183], v[180:181], v[174:175] neg_lo:[0,1] neg_hi:[0,1]
	v_cvt_pk_bf16_f32 v184, v182, v183
	global_store_dword v105, v184, s[76:77] offset:-3072
	v_lshlrev_b32_e32 v174, 16, v224
	v_and_b32_e32 v175, 0xffff0000, v224
	v_lshlrev_b32_e32 v176, 16, v208
	v_and_b32_e32 v177, 0xffff0000, v208
	v_pk_add_f32 v[178:179], v[174:175], v[176:177] neg_lo:[0,1] neg_hi:[0,1]
	v_pk_add_f32 v[172:173], v[172:173], v[178:179]
	s_cmp_eq_u32 s64, 0
	s_cbranch_scc1 .Lmx_ps3_1
	v_pk_mul_f32 v[180:181], v[172:173], s[72:73] op_sel_hi:[1,0]
.Lmx_pb3_1:
	v_pk_add_f32 v[182:183], v[180:181], v[174:175] neg_lo:[0,1] neg_hi:[0,1]
	v_cvt_pk_bf16_f32 v185, v182, v183
	global_store_dword v105, v185, s[76:77] offset:-1024
	v_lshlrev_b32_e32 v174, 16, v225
	v_and_b32_e32 v175, 0xffff0000, v225
	v_lshlrev_b32_e32 v176, 16, v209
	v_and_b32_e32 v177, 0xffff0000, v209
	v_pk_add_f32 v[178:179], v[174:175], v[176:177] neg_lo:[0,1] neg_hi:[0,1]
	v_pk_add_f32 v[172:173], v[172:173], v[178:179]
	s_cmp_eq_u32 s64, 0
	s_cbranch_scc1 .Lmx_ps3_2
	v_pk_mul_f32 v[180:181], v[172:173], s[72:73] op_sel_hi:[1,0]
.Lmx_pb3_2:
	v_pk_add_f32 v[182:183], v[180:181], v[174:175] neg_lo:[0,1] neg_hi:[0,1]
	v_cvt_pk_bf16_f32 v186, v182, v183
	global_store_dword v105, v186, s[76:77] offset:1024
	v_lshlrev_b32_e32 v174, 16, v226
	v_and_b32_e32 v175, 0xffff0000, v226
	v_lshlrev_b32_e32 v176, 16, v210
	v_and_b32_e32 v177, 0xffff0000, v210
	v_pk_add_f32 v[178:179], v[174:175], v[176:177] neg_lo:[0,1] neg_hi:[0,1]
	v_pk_add_f32 v[172:173], v[172:173], v[178:179]
	s_cmp_eq_u32 s64, 0
	s_cbranch_scc1 .Lmx_ps3_3
	v_pk_mul_f32 v[180:181], v[172:173], s[72:73] op_sel_hi:[1,0]
.Lmx_pb3_3:
	v_pk_add_f32 v[182:183], v[180:181], v[174:175] neg_lo:[0,1] neg_hi:[0,1]
	v_cvt_pk_bf16_f32 v187, v182, v183
	global_store_dword v105, v187, s[76:77] offset:3072
	v_lshlrev_b32_e32 v174, 16, v227
	v_and_b32_e32 v175, 0xffff0000, v227
	v_lshlrev_b32_e32 v176, 16, v211
	v_and_b32_e32 v177, 0xffff0000, v211
	v_pk_add_f32 v[178:179], v[174:175], v[176:177] neg_lo:[0,1] neg_hi:[0,1]
	v_pk_add_f32 v[172:173], v[172:173], v[178:179]
	s_cmp_eq_u32 s64, 0
	s_cbranch_scc1 .Lmx_ps3_4
	v_pk_mul_f32 v[180:181], v[172:173], s[72:73] op_sel_hi:[1,0]
; __device__ __forceinline__ unsigned pk2(float lo, float hi) { f32x2v v = {lo, hi}; b16x2v b = __builtin_convertvector(v, b16x2v); return __builtin_bit_cast(unsigned, b); }
; __device__ __forceinline__ f32x2v bf2(unsigned v) { return (f32x2v){bflo(v), bfhi(v)}; }
; template <int W>
; __device__ __forceinline__ void pool_prompt_w(const unsigned (&pin)[31], int t0, unsigned* dst  ) {
;     f32x2v s = {0.f, 0.f};
; #pragma unroll
;     for (int i = 0; i < W; ++i) s = s + bf2(pin[15 - i]);
; #pragma unroll
;     for (int t = 0; t < 16; ++t) {
;         if (t > 0) s = s + (bf2(pin[15 + t]) - bf2(pin[15 + t - W]));
;         const float cnt = (float)min(t0 + t + 1, W); const f32x2v cur = bf2(pin[15 + t]);
;         dst[(size_t)t * 512] = pk2(s.x / cnt - cur.x, s.y / cnt - cur.y);
;     }
; }
.Lmx_pb3_4:
	v_pk_add_f32 v[182:183], v[180:181], v[174:175] neg_lo:[0,1] neg_hi:[0,1]
	v_cvt_pk_bf16_f32 v184, v182, v183
	s_add_u32 s76, s76, 0x2000
	s_addc_u32 s77, s77, 0
	global_store_dword v105, v184, s[76:77] offset:-3072
	v_lshlrev_b32_e32 v174, 16, v228
	v_and_b32_e32 v175, 0xffff0000, v228
	v_lshlrev_b32_e32 v176, 16, v212
	v_and_b32_e32 v177, 0xffff0000, v212
	v_pk_add_f32 v[178:179], v[174:175], v[176:177] neg_lo:[0,1] neg_hi:[0,1]
	v_pk_add_f32 v[172:173], v[172:173], v[178:179]
	s_cmp_eq_u32 s64, 0
	s_cbranch_scc1 .Lmx_ps3_5
	v_pk_mul_f32 v[180:181], v[172:173], s[72:73] op_sel_hi:[1,0]
.Lmx_pb3_5:
	v_pk_add_f32 v[182:183], v[180:181], v[174:175] neg_lo:[0,1] neg_hi:[0,1]
	v_cvt_pk_bf16_f32 v185, v182, v183
	global_store_dword v105, v185, s[76:77] offset:-1024
	v_lshlrev_b32_e32 v174, 16, v229
	v_and_b32_e32 v175, 0xffff0000, v229
	v_lshlrev_b32_e32 v176, 16, v213
	v_and_b32_e32 v177, 0xffff0000, v213
	v_pk_add_f32 v[178:179], v[174:175], v[176:177] neg_lo:[0,1] neg_hi:[0,1]
	v_pk_add_f32 v[172:173], v[172:173], v[178:179]
	s_cmp_eq_u32 s64, 0
	s_cbranch_scc1 .Lmx_ps3_6
	v_pk_mul_f32 v[180:181], v[172:173], s[72:73] op_sel_hi:[1,0]
.Lmx_pb3_6:
	v_pk_add_f32 v[182:183], v[180:181], v[174:175] neg_lo:[0,1] neg_hi:[0,1]
	v_cvt_pk_bf16_f32 v186, v182, v183
	global_store_dword v105, v186, s[76:77] offset:1024
	v_lshlrev_b32_e32 v174, 16, v230
	v_and_b32_e32 v175, 0xffff0000, v230
	v_lshlrev_b32_e32 v176, 16, v214
	v_and_b32_e32 v177, 0xffff0000, v214
	v_pk_add_f32 v[178:179], v[174:175], v[176:177] neg_lo:[0,1] neg_hi:[0,1]
	v_pk_add_f32 v[172:173], v[172:173], v[178:179]
	s_cmp_eq_u32 s64, 0
	s_cbranch_scc1 .Lmx_ps3_7
	v_pk_mul_f32 v[180:181], v[172:173], s[72:73] op_sel_hi:[1,0]
.Lmx_pb3_7:
	v_pk_add_f32 v[182:183], v[180:181], v[174:175] neg_lo:[0,1] neg_hi:[0,1]
	v_cvt_pk_bf16_f32 v187, v182, v183
	global_store_dword v105, v187, s[76:77] offset:3072
	v_lshlrev_b32_e32 v174, 16, v231
	v_and_b32_e32 v175, 0xffff0000, v231
	v_lshlrev_b32_e32 v176, 16, v215
	v_and_b32_e32 v177, 0xffff0000, v215
	v_pk_add_f32 v[178:179], v[174:175], v[176:177] neg_lo:[0,1] neg_hi:[0,1]
	v_pk_add_f32 v[172:173], v[172:173], v[178:179]
	s_cmp_eq_u32 s64, 0
	s_cbranch_scc1 .Lmx_ps3_8
	v_pk_mul_f32 v[180:181], v[172:173], s[72:73] op_sel_hi:[1,0]
.Lmx_pb3_8:
	v_pk_add_f32 v[182:183], v[180:181], v[174:175] neg_lo:[0,1] neg_hi:[0,1]
	v_cvt_pk_bf16_f32 v184, v182, v183
	s_add_u32 s76, s76, 0x2000
	s_addc_u32 s77, s77, 0
	s_waitcnt vmcnt(40)
	global_store_dword v105, v184, s[76:77] offset:-3072
	v_lshlrev_b32_e32 v174, 16, v232
	v_and_b32_e32 v175, 0xffff0000, v232
	v_lshlrev_b32_e32 v176, 16, v216
	v_and_b32_e32 v177, 0xffff0000, v216
	v_pk_add_f32 v[178:179], v[174:175], v[176:177] neg_lo:[0,1] neg_hi:[0,1]
	v_pk_add_f32 v[172:173], v[172:173], v[178:179]
	s_cmp_eq_u32 s64, 0
	s_cbranch_scc1 .Lmx_ps3_9
	v_pk_mul_f32 v[180:181], v[172:173], s[72:73] op_sel_hi:[1,0]
.Lmx_pb3_9:
	v_pk_add_f32 v[182:183], v[180:181], v[174:175] neg_lo:[0,1] neg_hi:[0,1]
	v_cvt_pk_bf16_f32 v185, v182, v183
	global_store_dword v105, v185, s[76:77] offset:-1024
	v_lshlrev_b32_e32 v174, 16, v233
	v_and_b32_e32 v175, 0xffff0000, v233
	v_lshlrev_b32_e32 v176, 16, v217
	v_and_b32_e32 v177, 0xffff0000, v217
	v_pk_add_f32 v[178:179], v[174:175], v[176:177] neg_lo:[0,1] neg_hi:[0,1]
	v_pk_add_f32 v[172:173], v[172:173], v[178:179]
	s_cmp_eq_u32 s64, 0
	s_cbranch_scc1 .Lmx_ps3_10
	v_pk_mul_f32 v[180:181], v[172:173], s[72:73] op_sel_hi:[1,0]
.Lmx_pb3_10:
	v_pk_add_f32 v[182:183], v[180:181], v[174:175] neg_lo:[0,1] neg_hi:[0,1]
	v_cvt_pk_bf16_f32 v186, v182, v183
	global_store_dword v105, v186, s[76:77] offset:1024
	v_lshlrev_b32_e32 v174, 16, v234
	v_and_b32_e32 v175, 0xffff0000, v234
	v_lshlrev_b32_e32 v176, 16, v218
	v_and_b32_e32 v177, 0xffff0000, v218
	v_pk_add_f32 v[178:179], v[174:175], v[176:177] neg_lo:[0,1] neg_hi:[0,1]
	v_pk_add_f32 v[172:173], v[172:173], v[178:179]
	s_cmp_eq_u32 s64, 0
	s_cbranch_scc1 .Lmx_ps3_11
	v_pk_mul_f32 v[180:181], v[172:173], s[72:73] op_sel_hi:[1,0]
.Lmx_pb3_11:
	v_pk_add_f32 v[182:183], v[180:181], v[174:175] neg_lo:[0,1] neg_hi:[0,1]
	v_cvt_pk_bf16_f32 v187, v182, v183
	global_store_dword v105, v187, s[76:77] offset:3072
	v_lshlrev_b32_e32 v174, 16, v235
	v_and_b32_e32 v175, 0xffff0000, v235
	v_lshlrev_b32_e32 v176, 16, v219
	v_and_b32_e32 v177, 0xffff0000, v219
	v_pk_add_f32 v[178:179], v[174:175], v[176:177] neg_lo:[0,1] neg_hi:[0,1]
	v_pk_add_f32 v[172:173], v[172:173], v[178:179]
	s_cmp_eq_u32 s64, 0
	s_cbranch_scc1 .Lmx_ps3_12
	v_pk_mul_f32 v[180:181], v[172:173], s[72:73] op_sel_hi:[1,0]
.Lmx_pb3_12:
	v_pk_add_f32 v[182:183], v[180:181], v[174:175] neg_lo:[0,1] neg_hi:[0,1]
	v_cvt_pk_bf16_f32 v184, v182, v183
	s_add_u32 s76, s76, 0x2000
	s_addc_u32 s77, s77, 0
	global_store_dword v105, v184, s[76:77] offset:-3072
	v_lshlrev_b32_e32 v174, 16, v236
	v_and_b32_e32 v175, 0xffff0000, v236
	v_lshlrev_b32_e32 v176, 16, v220
	v_and_b32_e32 v177, 0xffff0000, v220
	v_pk_add_f32 v[178:179], v[174:175], v[176:177] neg_lo:[0,1] neg_hi:[0,1]
	v_pk_add_f32 v[172:173], v[172:173], v[178:179]
	s_cmp_eq_u32 s64, 0
	s_cbranch_scc1 .Lmx_ps3_13
	v_pk_mul_f32 v[180:181], v[172:173], s[72:73] op_sel_hi:[1,0]
.Lmx_pb3_13:
	v_pk_add_f32 v[182:183], v[180:181], v[174:175] neg_lo:[0,1] neg_hi:[0,1]
	v_cvt_pk_bf16_f32 v185, v182, v183
	global_store_dword v105, v185, s[76:77] offset:-1024
	v_lshlrev_b32_e32 v174, 16, v237
	v_and_b32_e32 v175, 0xffff0000, v237
	v_lshlrev_b32_e32 v176, 16, v221
	v_and_b32_e32 v177, 0xffff0000, v221
	v_pk_add_f32 v[178:179], v[174:175], v[176:177] neg_lo:[0,1] neg_hi:[0,1]
	v_pk_add_f32 v[172:173], v[172:173], v[178:179]
	s_cmp_eq_u32 s64, 0
	s_cbranch_scc1 .Lmx_ps3_14
	v_pk_mul_f32 v[180:181], v[172:173], s[72:73] op_sel_hi:[1,0]
.Lmx_pb3_14:
	v_pk_add_f32 v[182:183], v[180:181], v[174:175] neg_lo:[0,1] neg_hi:[0,1]
	v_cvt_pk_bf16_f32 v186, v182, v183
	global_store_dword v105, v186, s[76:77] offset:1024
	v_lshlrev_b32_e32 v174, 16, v238
	v_and_b32_e32 v175, 0xffff0000, v238
	v_lshlrev_b32_e32 v176, 16, v222
	v_and_b32_e32 v177, 0xffff0000, v222
	v_pk_add_f32 v[178:179], v[174:175], v[176:177] neg_lo:[0,1] neg_hi:[0,1]
	v_pk_add_f32 v[172:173], v[172:173], v[178:179]
	v_pk_mul_f32 v[180:181], v[172:173], s[72:73] op_sel_hi:[1,0]
	v_pk_add_f32 v[182:183], v[180:181], v[174:175] neg_lo:[0,1] neg_hi:[0,1]
	v_cvt_pk_bf16_f32 v187, v182, v183
	global_store_dword v105, v187, s[76:77] offset:3072
	s_branch .Lmx_pool_done

; __device__ __forceinline__ unsigned pk2(float lo, float hi) { f32x2v v = {lo, hi}; b16x2v b = __builtin_convertvector(v, b16x2v); return __builtin_bit_cast(unsigned, b); }
; __device__ __forceinline__ f32x2v bf2(unsigned v) { return (f32x2v){bflo(v), bfhi(v)}; }
; template <int W>
; __device__ __forceinline__ void pool_prompt_w(const unsigned (&pin)[31], int t0, unsigned* dst  ) {
;     f32x2v s = {0.f, 0.f};
; #pragma unroll
;     for (int i = 0; i < W; ++i) s = s + bf2(pin[15 - i]);
; #pragma unroll
;     for (int t = 0; t < 16; ++t) {
;         if (t > 0) s = s + (bf2(pin[15 + t]) - bf2(pin[15 + t - W]));
;         const float cnt = (float)min(t0 + t + 1, W); const f32x2v cur = bf2(pin[15 + t]);
;         dst[(size_t)t * 512] = pk2(s.x / cnt - cur.x, s.y / cnt - cur.y);
;     }
; }
; __device__ __forceinline__ void mixer_prompt_run(const Args& p, int run, int c2) {
;     ...
;         for (int j = 0; j < 31; ++j) w[j] = *(const f32x2v*)(p.conv_w() + j * 512 + 2 * c2);
;         const f32x2v cb = *(const f32x2v*)(p.conv_b() + 2 * c2);
;         const f32x2v gg = *(const f32x2v*)(p.gn_g() + 2 * c2), gb = *(const f32x2v*)(p.gn_b() + 2 * c2);
; #pragma unroll 1
;         for (int hh = 0; hh < 2; ++hh) {
;             f32x2v a[8];
; #pragma unroll
;             for (int t = 0; t < 8; ++t) a[t] = cb;
; #pragma unroll
;             for (int i = 0; i < 38; ++i) {
;                 const int ti = t0 + 8 * hh - 30 + i; unsigned v = U32[(rowb + (ti >= 0 ? ti : 0)) * 256 + c2]; v = (ti >= 0) ? v : 0u; const f32x2v x = bf2(v);
; #pragma unroll
;                 for (int t = 0; t < 8; ++t) { const int j = i - t; if (j >= 0 && j <= 30) a[t] = w[j] * x + a[t]; }
.Lmx_ps3_7:
	s_mov_b32 s78, 0x41000000
	s_mov_b32 s79, 0x3e000000
	v_mul_f32_e32 v180, s79, v172
	v_fma_f32 v240, -v180, s78, v172
	v_fma_f32 v180, v240, s79, v180
	v_mul_f32_e32 v181, s79, v173
	v_fma_f32 v240, -v181, s78, v173
	v_fma_f32 v181, v240, s79, v181
	s_branch .Lmx_pb3_7
.Lmx_ps3_8:
	s_mov_b32 s78, 0x41100000
	s_mov_b32 s79, 0x3de38e39
	v_mul_f32_e32 v180, s79, v172
	v_fma_f32 v240, -v180, s78, v172
	v_fma_f32 v180, v240, s79, v180
	v_mul_f32_e32 v181, s79, v173
	v_fma_f32 v240, -v181, s78, v173
	v_fma_f32 v181, v240, s79, v181
	s_branch .Lmx_pb3_8
.Lmx_ps3_9:
	s_mov_b32 s78, 0x41200000
	s_mov_b32 s79, 0x3dcccccd
	v_mul_f32_e32 v180, s79, v172
	v_fma_f32 v240, -v180, s78, v172
	v_fma_f32 v180, v240, s79, v180
	v_mul_f32_e32 v181, s79, v173
	v_fma_f32 v240, -v181, s78, v173
	v_fma_f32 v181, v240, s79, v181
	s_branch .Lmx_pb3_9
.Lmx_ps3_10:
	s_mov_b32 s78, 0x41300000
	s_mov_b32 s79, 0x3dba2e8c
	v_mul_f32_e32 v180, s79, v172
	v_fma_f32 v240, -v180, s78, v172
	v_fma_f32 v180, v240, s79, v180
	v_mul_f32_e32 v181, s79, v173
	v_fma_f32 v240, -v181, s78, v173
	v_fma_f32 v181, v240, s79, v181
	s_branch .Lmx_pb3_10
.Lmx_ps3_11:
	s_mov_b32 s78, 0x41400000
	s_mov_b32 s79, 0x3daaaaab
	v_mul_f32_e32 v180, s79, v172
	v_fma_f32 v240, -v180, s78, v172
	v_fma_f32 v180, v240, s79, v180
	v_mul_f32_e32 v181, s79, v173
	v_fma_f32 v240, -v181, s78, v173
	v_fma_f32 v181, v240, s79, v181
	s_branch .Lmx_pb3_11
.Lmx_ps3_12:
	s_mov_b32 s78, 0x41500000
	s_mov_b32 s79, 0x3d9d89d9
	v_mul_f32_e32 v180, s79, v172
	v_fma_f32 v240, -v180, s78, v172
	v_fma_f32 v180, v240, s79, v180
	v_mul_f32_e32 v181, s79, v173
	v_fma_f32 v240, -v181, s78, v173
	v_fma_f32 v181, v240, s79, v181
	s_branch .Lmx_pb3_12
.Lmx_ps3_13:
	s_mov_b32 s78, 0x41600000
	s_mov_b32 s79, 0x3d924925
	v_mul_f32_e32 v180, s79, v172
	v_fma_f32 v240, -v180, s78, v172
	v_fma_f32 v180, v240, s79, v180
	v_mul_f32_e32 v181, s79, v173
	v_fma_f32 v240, -v181, s78, v173
	v_fma_f32 v181, v240, s79, v181
	s_branch .Lmx_pb3_13
.Lmx_ps3_14:
	s_mov_b32 s78, 0x41700000
	s_mov_b32 s79, 0x3d888889
	v_mul_f32_e32 v180, s79, v172
	v_fma_f32 v240, -v180, s78, v172
	v_fma_f32 v180, v240, s79, v180
	v_mul_f32_e32 v181, s79, v173
	v_fma_f32 v240, -v181, s78, v173
	v_fma_f32 v181, v240, s79, v181
	s_branch .Lmx_pb3_14
.Lmx_pool_done:
	s_waitcnt vmcnt(30)
	global_load_dword v208, v105, s[66:67] offset:3072
	s_add_u32 s66, s66, 0x2000
	s_addc_u32 s67, s67, 0
	global_load_dword v209, v105, s[66:67] offset:-4096
	global_load_dword v210, v105, s[66:67] offset:-3072
	global_load_dword v211, v105, s[66:67] offset:-2048
	global_load_dword v212, v105, s[66:67] offset:-1024
	global_load_dword v213, v105, s[66:67] offset:0
	global_load_dword v214, v105, s[66:67] offset:1024
	global_load_dword v215, v105, s[66:67] offset:2048
	global_load_dword v216, v105, s[66:67] offset:3072
	s_add_u32 s66, s66, 0x2000
	s_addc_u32 s67, s67, 0
	global_load_dword v217, v105, s[66:67] offset:-4096
	global_load_dword v218, v105, s[66:67] offset:-3072
	global_load_dword v219, v105, s[66:67] offset:-2048
	global_load_dword v220, v105, s[66:67] offset:-1024
	global_load_dword v221, v105, s[66:67] offset:0
	global_load_dword v222, v105, s[66:67] offset:1024
	global_load_dword v223, v105, s[66:67] offset:2048
	global_load_dword v224, v105, s[66:67] offset:3072
	s_add_u32 s66, s66, 0x2000
	s_addc_u32 s67, s67, 0
	global_load_dword v225, v105, s[66:67] offset:-4096
	global_load_dword v226, v105, s[66:67] offset:-3072
	global_load_dword v227, v105, s[66:67] offset:-2048
	global_load_dword v228, v105, s[66:67] offset:-1024
	global_load_dword v229, v105, s[66:67] offset:0
	global_load_dword v230, v105, s[66:67] offset:1024
	global_load_dword v231, v105, s[66:67] offset:2048
	global_load_dword v232, v105, s[66:67] offset:3072
	s_add_u32 s66, s66, 0x2000
	s_addc_u32 s67, s67, 0
	global_load_dword v233, v105, s[66:67] offset:-4096
	global_load_dword v234, v105, s[66:67] offset:-3072
	global_load_dword v235, v105, s[66:67] offset:-2048
	global_load_dword v236, v105, s[66:67] offset:-1024
	global_load_dword v237, v105, s[66:67] offset:0
	global_load_dword v238, v105, s[66:67] offset:1024
	s_waitcnt vmcnt(47)
	s_cbranch_vccnz .Lmx_e0
.Lmx_b0:
	v_lshlrev_b32_e32 v96, 16, v193
	v_and_b32_e32 v97, 0xffff0000, v193
	v_pk_fma_f32 v[172:173], v[106:107], v[96:97], v[90:91]
	s_cbranch_vccnz .Lmx_e1
.Lmx_b1:
	v_lshlrev_b32_e32 v98, 16, v194
	v_and_b32_e32 v99, 0xffff0000, v194
	v_pk_fma_f32 v[172:173], v[108:109], v[98:99], v[172:173]
	v_pk_fma_f32 v[174:175], v[106:107], v[98:99], v[90:91]
	s_cbranch_vccnz .Lmx_e2
.Lmx_b2:
	v_lshlrev_b32_e32 v96, 16, v195
	v_and_b32_e32 v97, 0xffff0000, v195
	v_pk_fma_f32 v[172:173], v[110:111], v[96:97], v[172:173]
	v_pk_fma_f32 v[174:175], v[108:109], v[96:97], v[174:175]
	v_pk_fma_f32 v[176:177], v[106:107], v[96:97], v[90:91]
	s_cbranch_vccnz .Lmx_e3
.Lmx_b3:
	v_lshlrev_b32_e32 v98, 16, v196
	v_and_b32_e32 v99, 0xffff0000, v196
	v_pk_fma_f32 v[172:173], v[112:113], v[98:99], v[172:173]
	v_pk_fma_f32 v[174:175], v[110:111], v[98:99], v[174:175]
	v_pk_fma_f32 v[176:177], v[108:109], v[98:99], v[176:177]
	v_pk_fma_f32 v[178:179], v[106:107], v[98:99], v[90:91]
	s_cbranch_vccnz .Lmx_e4
.Lmx_b4:
	v_lshlrev_b32_e32 v96, 16, v197
	v_and_b32_e32 v97, 0xffff0000, v197
	v_pk_fma_f32 v[172:173], v[114:115], v[96:97], v[172:173]
	v_pk_fma_f32 v[174:175], v[112:113], v[96:97], v[174:175]
	v_pk_fma_f32 v[176:177], v[110:111], v[96:97], v[176:177]
	v_pk_fma_f32 v[178:179], v[108:109], v[96:97], v[178:179]
	v_pk_fma_f32 v[180:181], v[106:107], v[96:97], v[90:91]
	s_cbranch_vccnz .Lmx_e5
; __device__ __forceinline__ f32x2v bf2(unsigned v) { return (f32x2v){bflo(v), bfhi(v)}; }
; __device__ __forceinline__ void mixer_prompt_run(const Args& p, int run, int c2) {
;     ...
;             for (int i = 0; i < 38; ++i) {
;                 const int ti = t0 + 8 * hh - 30 + i; unsigned v = U32[(rowb + (ti >= 0 ? ti : 0)) * 256 + c2]; v = (ti >= 0) ? v : 0u; const f32x2v x = bf2(v);
; #pragma unroll
;                 for (int t = 0; t < 8; ++t) { const int j = i - t; if (j >= 0 && j <= 30) a[t] = w[j] * x + a[t]; }
.Lmx_b5:
	v_lshlrev_b32_e32 v98, 16, v198
	v_and_b32_e32 v99, 0xffff0000, v198
	v_pk_fma_f32 v[172:173], v[116:117], v[98:99], v[172:173]
	v_pk_fma_f32 v[174:175], v[114:115], v[98:99], v[174:175]
	v_pk_fma_f32 v[176:177], v[112:113], v[98:99], v[176:177]
	v_pk_fma_f32 v[178:179], v[110:111], v[98:99], v[178:179]
	v_pk_fma_f32 v[180:181], v[108:109], v[98:99], v[180:181]
	v_pk_fma_f32 v[182:183], v[106:107], v[98:99], v[90:91]
	s_cbranch_vccnz .Lmx_e6
.Lmx_b6:
	v_lshlrev_b32_e32 v96, 16, v199
	v_and_b32_e32 v97, 0xffff0000, v199
	v_pk_fma_f32 v[172:173], v[118:119], v[96:97], v[172:173]
	v_pk_fma_f32 v[174:175], v[116:117], v[96:97], v[174:175]
	v_pk_fma_f32 v[176:177], v[114:115], v[96:97], v[176:177]
	v_pk_fma_f32 v[178:179], v[112:113], v[96:97], v[178:179]
	v_pk_fma_f32 v[180:181], v[110:111], v[96:97], v[180:181]
	v_pk_fma_f32 v[182:183], v[108:109], v[96:97], v[182:183]
	v_pk_fma_f32 v[184:185], v[106:107], v[96:97], v[90:91]
	s_cbranch_vccnz .Lmx_e7
.Lmx_b7:
	v_lshlrev_b32_e32 v98, 16, v200
	v_and_b32_e32 v99, 0xffff0000, v200
	v_pk_fma_f32 v[172:173], v[120:121], v[98:99], v[172:173]
	v_pk_fma_f32 v[174:175], v[118:119], v[98:99], v[174:175]
	v_pk_fma_f32 v[176:177], v[116:117], v[98:99], v[176:177]
	v_pk_fma_f32 v[178:179], v[114:115], v[98:99], v[178:179]
	v_pk_fma_f32 v[180:181], v[112:113], v[98:99], v[180:181]
	v_pk_fma_f32 v[182:183], v[110:111], v[98:99], v[182:183]
	v_pk_fma_f32 v[184:185], v[108:109], v[98:99], v[184:185]
	v_pk_fma_f32 v[186:187], v[106:107], v[98:99], v[90:91]
	s_cbranch_vccnz .Lmx_e8
.Lmx_b8:
	v_lshlrev_b32_e32 v96, 16, v201
	v_and_b32_e32 v97, 0xffff0000, v201
	v_pk_fma_f32 v[172:173], v[122:123], v[96:97], v[172:173]
	v_pk_fma_f32 v[174:175], v[120:121], v[96:97], v[174:175]
	v_pk_fma_f32 v[176:177], v[118:119], v[96:97], v[176:177]
	v_pk_fma_f32 v[178:179], v[116:117], v[96:97], v[178:179]
	v_pk_fma_f32 v[180:181], v[114:115], v[96:97], v[180:181]
	v_pk_fma_f32 v[182:183], v[112:113], v[96:97], v[182:183]
	v_pk_fma_f32 v[184:185], v[110:111], v[96:97], v[184:185]
	v_pk_fma_f32 v[186:187], v[108:109], v[96:97], v[186:187]
	v_pk_fma_f32 v[188:189], v[106:107], v[96:97], v[90:91]
	s_cbranch_vccnz .Lmx_e9
.Lmx_b9:
	v_lshlrev_b32_e32 v98, 16, v202
	v_and_b32_e32 v99, 0xffff0000, v202
	v_pk_fma_f32 v[172:173], v[124:125], v[98:99], v[172:173]
	v_pk_fma_f32 v[174:175], v[122:123], v[98:99], v[174:175]
	v_pk_fma_f32 v[176:177], v[120:121], v[98:99], v[176:177]
	v_pk_fma_f32 v[178:179], v[118:119], v[98:99], v[178:179]
	v_pk_fma_f32 v[180:181], v[116:117], v[98:99], v[180:181]
	v_pk_fma_f32 v[182:183], v[114:115], v[98:99], v[182:183]
	v_pk_fma_f32 v[184:185], v[112:113], v[98:99], v[184:185]
	v_pk_fma_f32 v[186:187], v[110:111], v[98:99], v[186:187]
	v_pk_fma_f32 v[188:189], v[108:109], v[98:99], v[188:189]
	v_pk_fma_f32 v[190:191], v[106:107], v[98:99], v[90:91]
	s_cbranch_vccnz .Lmx_e10
.Lmx_b10:
	v_lshlrev_b32_e32 v96, 16, v203
	v_and_b32_e32 v97, 0xffff0000, v203
	v_pk_fma_f32 v[172:173], v[126:127], v[96:97], v[172:173]
	v_pk_fma_f32 v[174:175], v[124:125], v[96:97], v[174:175]
	v_pk_fma_f32 v[176:177], v[122:123], v[96:97], v[176:177]
	v_pk_fma_f32 v[178:179], v[120:121], v[96:97], v[178:179]
	v_pk_fma_f32 v[180:181], v[118:119], v[96:97], v[180:181]
	v_pk_fma_f32 v[182:183], v[116:117], v[96:97], v[182:183]
	v_pk_fma_f32 v[184:185], v[114:115], v[96:97], v[184:185]
	v_pk_fma_f32 v[186:187], v[112:113], v[96:97], v[186:187]
	v_pk_fma_f32 v[188:189], v[110:111], v[96:97], v[188:189]
	v_pk_fma_f32 v[190:191], v[108:109], v[96:97], v[190:191]
	v_pk_fma_f32 v[78:79], v[106:107], v[96:97], v[90:91]
	s_cbranch_vccnz .Lmx_e11
.Lmx_b11:
	v_lshlrev_b32_e32 v98, 16, v204
	v_and_b32_e32 v99, 0xffff0000, v204
	v_pk_fma_f32 v[172:173], v[128:129], v[98:99], v[172:173]
	v_pk_fma_f32 v[174:175], v[126:127], v[98:99], v[174:175]
	v_pk_fma_f32 v[176:177], v[124:125], v[98:99], v[176:177]
	v_pk_fma_f32 v[178:179], v[122:123], v[98:99], v[178:179]
	v_pk_fma_f32 v[180:181], v[120:121], v[98:99], v[180:181]
	v_pk_fma_f32 v[182:183], v[118:119], v[98:99], v[182:183]
	v_pk_fma_f32 v[184:185], v[116:117], v[98:99], v[184:185]
	v_pk_fma_f32 v[186:187], v[114:115], v[98:99], v[186:187]
	v_pk_fma_f32 v[188:189], v[112:113], v[98:99], v[188:189]
	v_pk_fma_f32 v[190:191], v[110:111], v[98:99], v[190:191]
	v_pk_fma_f32 v[78:79], v[108:109], v[98:99], v[78:79]
	v_pk_fma_f32 v[80:81], v[106:107], v[98:99], v[90:91]
	s_cbranch_vccnz .Lmx_e12
.Lmx_b12:
	v_lshlrev_b32_e32 v96, 16, v205
	v_and_b32_e32 v97, 0xffff0000, v205
	v_pk_fma_f32 v[172:173], v[130:131], v[96:97], v[172:173]
	v_pk_fma_f32 v[174:175], v[128:129], v[96:97], v[174:175]
	v_pk_fma_f32 v[176:177], v[126:127], v[96:97], v[176:177]
	v_pk_fma_f32 v[178:179], v[124:125], v[96:97], v[178:179]
	v_pk_fma_f32 v[180:181], v[122:123], v[96:97], v[180:181]
	v_pk_fma_f32 v[182:183], v[120:121], v[96:97], v[182:183]
	v_pk_fma_f32 v[184:185], v[118:119], v[96:97], v[184:185]
	v_pk_fma_f32 v[186:187], v[116:117], v[96:97], v[186:187]
	v_pk_fma_f32 v[188:189], v[114:115], v[96:97], v[188:189]
	v_pk_fma_f32 v[190:191], v[112:113], v[96:97], v[190:191]
	v_pk_fma_f32 v[78:79], v[110:111], v[96:97], v[78:79]
	v_pk_fma_f32 v[80:81], v[108:109], v[96:97], v[80:81]
	v_pk_fma_f32 v[82:83], v[106:107], v[96:97], v[90:91]
	s_cbranch_vccnz .Lmx_e13
; __device__ __forceinline__ f32x2v bf2(unsigned v) { return (f32x2v){bflo(v), bfhi(v)}; }
; __device__ __forceinline__ void mixer_prompt_run(const Args& p, int run, int c2) {
;     ...
;             for (int i = 0; i < 38; ++i) {
;                 const int ti = t0 + 8 * hh - 30 + i; unsigned v = U32[(rowb + (ti >= 0 ? ti : 0)) * 256 + c2]; v = (ti >= 0) ? v : 0u; const f32x2v x = bf2(v);
; #pragma unroll
;                 for (int t = 0; t < 8; ++t) { const int j = i - t; if (j >= 0 && j <= 30) a[t] = w[j] * x + a[t]; }
.Lmx_b13:
	v_lshlrev_b32_e32 v98, 16, v206
	v_and_b32_e32 v99, 0xffff0000, v206
	v_pk_fma_f32 v[172:173], v[132:133], v[98:99], v[172:173]
	v_pk_fma_f32 v[174:175], v[130:131], v[98:99], v[174:175]
	v_pk_fma_f32 v[176:177], v[128:129], v[98:99], v[176:177]
	v_pk_fma_f32 v[178:179], v[126:127], v[98:99], v[178:179]
	v_pk_fma_f32 v[180:181], v[124:125], v[98:99], v[180:181]
	v_pk_fma_f32 v[182:183], v[122:123], v[98:99], v[182:183]
	v_pk_fma_f32 v[184:185], v[120:121], v[98:99], v[184:185]
	v_pk_fma_f32 v[186:187], v[118:119], v[98:99], v[186:187]
	v_pk_fma_f32 v[188:189], v[116:117], v[98:99], v[188:189]
	v_pk_fma_f32 v[190:191], v[114:115], v[98:99], v[190:191]
	v_pk_fma_f32 v[78:79], v[112:113], v[98:99], v[78:79]
	v_pk_fma_f32 v[80:81], v[110:111], v[98:99], v[80:81]
	v_pk_fma_f32 v[82:83], v[108:109], v[98:99], v[82:83]
	v_pk_fma_f32 v[84:85], v[106:107], v[98:99], v[90:91]
	s_cbranch_vccnz .Lmx_e14
.Lmx_b14:
	v_lshlrev_b32_e32 v96, 16, v207
	v_and_b32_e32 v97, 0xffff0000, v207
	v_pk_fma_f32 v[172:173], v[134:135], v[96:97], v[172:173]
	v_pk_fma_f32 v[174:175], v[132:133], v[96:97], v[174:175]
	v_pk_fma_f32 v[176:177], v[130:131], v[96:97], v[176:177]
	v_pk_fma_f32 v[178:179], v[128:129], v[96:97], v[178:179]
	v_pk_fma_f32 v[180:181], v[126:127], v[96:97], v[180:181]
	v_pk_fma_f32 v[182:183], v[124:125], v[96:97], v[182:183]
	v_pk_fma_f32 v[184:185], v[122:123], v[96:97], v[184:185]
	v_pk_fma_f32 v[186:187], v[120:121], v[96:97], v[186:187]
	v_pk_fma_f32 v[188:189], v[118:119], v[96:97], v[188:189]
	v_pk_fma_f32 v[190:191], v[116:117], v[96:97], v[190:191]
	v_pk_fma_f32 v[78:79], v[114:115], v[96:97], v[78:79]
	v_pk_fma_f32 v[80:81], v[112:113], v[96:97], v[80:81]
	v_pk_fma_f32 v[82:83], v[110:111], v[96:97], v[82:83]
	v_pk_fma_f32 v[84:85], v[108:109], v[96:97], v[84:85]
	v_pk_fma_f32 v[86:87], v[106:107], v[96:97], v[90:91]
	s_waitcnt vmcnt(30)
	s_cbranch_vccnz .Lmx_e15
.Lmx_b15:
	v_lshlrev_b32_e32 v98, 16, v208
	v_and_b32_e32 v99, 0xffff0000, v208
	v_pk_fma_f32 v[172:173], v[136:137], v[98:99], v[172:173]
	v_pk_fma_f32 v[174:175], v[134:135], v[98:99], v[174:175]
	v_pk_fma_f32 v[176:177], v[132:133], v[98:99], v[176:177]
	v_pk_fma_f32 v[178:179], v[130:131], v[98:99], v[178:179]
	v_pk_fma_f32 v[180:181], v[128:129], v[98:99], v[180:181]
	v_pk_fma_f32 v[182:183], v[126:127], v[98:99], v[182:183]
	v_pk_fma_f32 v[184:185], v[124:125], v[98:99], v[184:185]
	v_pk_fma_f32 v[186:187], v[122:123], v[98:99], v[186:187]
	v_pk_fma_f32 v[188:189], v[120:121], v[98:99], v[188:189]
	v_pk_fma_f32 v[190:191], v[118:119], v[98:99], v[190:191]
	v_pk_fma_f32 v[78:79], v[116:117], v[98:99], v[78:79]
	v_pk_fma_f32 v[80:81], v[114:115], v[98:99], v[80:81]
	v_pk_fma_f32 v[82:83], v[112:113], v[98:99], v[82:83]
	v_pk_fma_f32 v[84:85], v[110:111], v[98:99], v[84:85]
	v_pk_fma_f32 v[86:87], v[108:109], v[98:99], v[86:87]
	v_pk_fma_f32 v[88:89], v[106:107], v[98:99], v[90:91]
	s_waitcnt vmcnt(29)
	s_cbranch_vccnz .Lmx_e16
.Lmx_b16:
	v_lshlrev_b32_e32 v96, 16, v209
	v_and_b32_e32 v97, 0xffff0000, v209
	v_pk_fma_f32 v[172:173], v[138:139], v[96:97], v[172:173]
	v_pk_fma_f32 v[174:175], v[136:137], v[96:97], v[174:175]
	v_pk_fma_f32 v[176:177], v[134:135], v[96:97], v[176:177]
	v_pk_fma_f32 v[178:179], v[132:133], v[96:97], v[178:179]
	v_pk_fma_f32 v[180:181], v[130:131], v[96:97], v[180:181]
	v_pk_fma_f32 v[182:183], v[128:129], v[96:97], v[182:183]
	v_pk_fma_f32 v[184:185], v[126:127], v[96:97], v[184:185]
	v_pk_fma_f32 v[186:187], v[124:125], v[96:97], v[186:187]
	v_pk_fma_f32 v[188:189], v[122:123], v[96:97], v[188:189]
	v_pk_fma_f32 v[190:191], v[120:121], v[96:97], v[190:191]
	v_pk_fma_f32 v[78:79], v[118:119], v[96:97], v[78:79]
	v_pk_fma_f32 v[80:81], v[116:117], v[96:97], v[80:81]
	v_pk_fma_f32 v[82:83], v[114:115], v[96:97], v[82:83]
	v_pk_fma_f32 v[84:85], v[112:113], v[96:97], v[84:85]
	v_pk_fma_f32 v[86:87], v[110:111], v[96:97], v[86:87]
	v_pk_fma_f32 v[88:89], v[108:109], v[96:97], v[88:89]
	s_waitcnt vmcnt(28)
	s_cbranch_vccnz .Lmx_e17
.Lmx_b17:
	v_lshlrev_b32_e32 v98, 16, v210
	v_and_b32_e32 v99, 0xffff0000, v210
	v_pk_fma_f32 v[172:173], v[140:141], v[98:99], v[172:173]
	v_pk_fma_f32 v[174:175], v[138:139], v[98:99], v[174:175]
	v_pk_fma_f32 v[176:177], v[136:137], v[98:99], v[176:177]
	v_pk_fma_f32 v[178:179], v[134:135], v[98:99], v[178:179]
	v_pk_fma_f32 v[180:181], v[132:133], v[98:99], v[180:181]
	v_pk_fma_f32 v[182:183], v[130:131], v[98:99], v[182:183]
	v_pk_fma_f32 v[184:185], v[128:129], v[98:99], v[184:185]
	v_pk_fma_f32 v[186:187], v[126:127], v[98:99], v[186:187]
	v_pk_fma_f32 v[188:189], v[124:125], v[98:99], v[188:189]
	v_pk_fma_f32 v[190:191], v[122:123], v[98:99], v[190:191]
	v_pk_fma_f32 v[78:79], v[120:121], v[98:99], v[78:79]
	v_pk_fma_f32 v[80:81], v[118:119], v[98:99], v[80:81]
	v_pk_fma_f32 v[82:83], v[116:117], v[98:99], v[82:83]
	v_pk_fma_f32 v[84:85], v[114:115], v[98:99], v[84:85]
	v_pk_fma_f32 v[86:87], v[112:113], v[98:99], v[86:87]
	v_pk_fma_f32 v[88:89], v[110:111], v[98:99], v[88:89]
	s_waitcnt vmcnt(27)
	s_cbranch_vccnz .Lmx_e18
.Lmx_b18:
	v_lshlrev_b32_e32 v96, 16, v211
	v_and_b32_e32 v97, 0xffff0000, v211
	v_pk_fma_f32 v[172:173], v[142:143], v[96:97], v[172:173]
	v_pk_fma_f32 v[174:175], v[140:141], v[96:97], v[174:175]
	v_pk_fma_f32 v[176:177], v[138:139], v[96:97], v[176:177]
	v_pk_fma_f32 v[178:179], v[136:137], v[96:97], v[178:179]
	v_pk_fma_f32 v[180:181], v[134:135], v[96:97], v[180:181]
	v_pk_fma_f32 v[182:183], v[132:133], v[96:97], v[182:183]
	v_pk_fma_f32 v[184:185], v[130:131], v[96:97], v[184:185]
	v_pk_fma_f32 v[186:187], v[128:129], v[96:97], v[186:187]
	v_pk_fma_f32 v[188:189], v[126:127], v[96:97], v[188:189]
	v_pk_fma_f32 v[190:191], v[124:125], v[96:97], v[190:191]
	v_pk_fma_f32 v[78:79], v[122:123], v[96:97], v[78:79]
	v_pk_fma_f32 v[80:81], v[120:121], v[96:97], v[80:81]
	v_pk_fma_f32 v[82:83], v[118:119], v[96:97], v[82:83]
	v_pk_fma_f32 v[84:85], v[116:117], v[96:97], v[84:85]
	v_pk_fma_f32 v[86:87], v[114:115], v[96:97], v[86:87]
	v_pk_fma_f32 v[88:89], v[112:113], v[96:97], v[88:89]
	s_waitcnt vmcnt(26)
	s_cbranch_vccnz .Lmx_e19
; __device__ __forceinline__ f32x2v bf2(unsigned v) { return (f32x2v){bflo(v), bfhi(v)}; }
; __device__ __forceinline__ void mixer_prompt_run(const Args& p, int run, int c2) {
;     ...
;             for (int i = 0; i < 38; ++i) {
;                 const int ti = t0 + 8 * hh - 30 + i; unsigned v = U32[(rowb + (ti >= 0 ? ti : 0)) * 256 + c2]; v = (ti >= 0) ? v : 0u; const f32x2v x = bf2(v);
; #pragma unroll
;                 for (int t = 0; t < 8; ++t) { const int j = i - t; if (j >= 0 && j <= 30) a[t] = w[j] * x + a[t]; }
.Lmx_b19:
	v_lshlrev_b32_e32 v98, 16, v212
	v_and_b32_e32 v99, 0xffff0000, v212
	v_pk_fma_f32 v[172:173], v[144:145], v[98:99], v[172:173]
	v_pk_fma_f32 v[174:175], v[142:143], v[98:99], v[174:175]
	v_pk_fma_f32 v[176:177], v[140:141], v[98:99], v[176:177]
	v_pk_fma_f32 v[178:179], v[138:139], v[98:99], v[178:179]
	v_pk_fma_f32 v[180:181], v[136:137], v[98:99], v[180:181]
	v_pk_fma_f32 v[182:183], v[134:135], v[98:99], v[182:183]
	v_pk_fma_f32 v[184:185], v[132:133], v[98:99], v[184:185]
	v_pk_fma_f32 v[186:187], v[130:131], v[98:99], v[186:187]
	v_pk_fma_f32 v[188:189], v[128:129], v[98:99], v[188:189]
	v_pk_fma_f32 v[190:191], v[126:127], v[98:99], v[190:191]
	v_pk_fma_f32 v[78:79], v[124:125], v[98:99], v[78:79]
	v_pk_fma_f32 v[80:81], v[122:123], v[98:99], v[80:81]
	v_pk_fma_f32 v[82:83], v[120:121], v[98:99], v[82:83]
	v_pk_fma_f32 v[84:85], v[118:119], v[98:99], v[84:85]
	v_pk_fma_f32 v[86:87], v[116:117], v[98:99], v[86:87]
	v_pk_fma_f32 v[88:89], v[114:115], v[98:99], v[88:89]
	s_waitcnt vmcnt(25)
	s_cbranch_vccnz .Lmx_e20
.Lmx_b20:
	v_lshlrev_b32_e32 v96, 16, v213
	v_and_b32_e32 v97, 0xffff0000, v213
	v_pk_fma_f32 v[172:173], v[146:147], v[96:97], v[172:173]
	v_pk_fma_f32 v[174:175], v[144:145], v[96:97], v[174:175]
	v_pk_fma_f32 v[176:177], v[142:143], v[96:97], v[176:177]
	v_pk_fma_f32 v[178:179], v[140:141], v[96:97], v[178:179]
	v_pk_fma_f32 v[180:181], v[138:139], v[96:97], v[180:181]
	v_pk_fma_f32 v[182:183], v[136:137], v[96:97], v[182:183]
	v_pk_fma_f32 v[184:185], v[134:135], v[96:97], v[184:185]
	v_pk_fma_f32 v[186:187], v[132:133], v[96:97], v[186:187]
	v_pk_fma_f32 v[188:189], v[130:131], v[96:97], v[188:189]
	v_pk_fma_f32 v[190:191], v[128:129], v[96:97], v[190:191]
	v_pk_fma_f32 v[78:79], v[126:127], v[96:97], v[78:79]
	v_pk_fma_f32 v[80:81], v[124:125], v[96:97], v[80:81]
	v_pk_fma_f32 v[82:83], v[122:123], v[96:97], v[82:83]
	v_pk_fma_f32 v[84:85], v[120:121], v[96:97], v[84:85]
	v_pk_fma_f32 v[86:87], v[118:119], v[96:97], v[86:87]
	v_pk_fma_f32 v[88:89], v[116:117], v[96:97], v[88:89]
	s_waitcnt vmcnt(24)
	s_cbranch_vccnz .Lmx_e21
.Lmx_b21:
	v_lshlrev_b32_e32 v98, 16, v214
	v_and_b32_e32 v99, 0xffff0000, v214
	v_pk_fma_f32 v[172:173], v[148:149], v[98:99], v[172:173]
	v_pk_fma_f32 v[174:175], v[146:147], v[98:99], v[174:175]
	v_pk_fma_f32 v[176:177], v[144:145], v[98:99], v[176:177]
	v_pk_fma_f32 v[178:179], v[142:143], v[98:99], v[178:179]
	v_pk_fma_f32 v[180:181], v[140:141], v[98:99], v[180:181]
	v_pk_fma_f32 v[182:183], v[138:139], v[98:99], v[182:183]
	v_pk_fma_f32 v[184:185], v[136:137], v[98:99], v[184:185]
	v_pk_fma_f32 v[186:187], v[134:135], v[98:99], v[186:187]
	v_pk_fma_f32 v[188:189], v[132:133], v[98:99], v[188:189]
	v_pk_fma_f32 v[190:191], v[130:131], v[98:99], v[190:191]
	v_pk_fma_f32 v[78:79], v[128:129], v[98:99], v[78:79]
	v_pk_fma_f32 v[80:81], v[126:127], v[98:99], v[80:81]
	v_pk_fma_f32 v[82:83], v[124:125], v[98:99], v[82:83]
	v_pk_fma_f32 v[84:85], v[122:123], v[98:99], v[84:85]
	v_pk_fma_f32 v[86:87], v[120:121], v[98:99], v[86:87]
	v_pk_fma_f32 v[88:89], v[118:119], v[98:99], v[88:89]
	s_waitcnt vmcnt(23)
	s_cbranch_vccnz .Lmx_e22
.Lmx_b22:
	v_lshlrev_b32_e32 v96, 16, v215
	v_and_b32_e32 v97, 0xffff0000, v215
	v_pk_fma_f32 v[172:173], v[150:151], v[96:97], v[172:173]
	v_pk_fma_f32 v[174:175], v[148:149], v[96:97], v[174:175]
	v_pk_fma_f32 v[176:177], v[146:147], v[96:97], v[176:177]
	v_pk_fma_f32 v[178:179], v[144:145], v[96:97], v[178:179]
	v_pk_fma_f32 v[180:181], v[142:143], v[96:97], v[180:181]
	v_pk_fma_f32 v[182:183], v[140:141], v[96:97], v[182:183]
	v_pk_fma_f32 v[184:185], v[138:139], v[96:97], v[184:185]
	v_pk_fma_f32 v[186:187], v[136:137], v[96:97], v[186:187]
	v_pk_fma_f32 v[188:189], v[134:135], v[96:97], v[188:189]
	v_pk_fma_f32 v[190:191], v[132:133], v[96:97], v[190:191]
	v_pk_fma_f32 v[78:79], v[130:131], v[96:97], v[78:79]
	v_pk_fma_f32 v[80:81], v[128:129], v[96:97], v[80:81]
	v_pk_fma_f32 v[82:83], v[126:127], v[96:97], v[82:83]
	v_pk_fma_f32 v[84:85], v[124:125], v[96:97], v[84:85]
	v_pk_fma_f32 v[86:87], v[122:123], v[96:97], v[86:87]
	v_pk_fma_f32 v[88:89], v[120:121], v[96:97], v[88:89]
	s_waitcnt vmcnt(22)
	s_cbranch_vccnz .Lmx_e23
.Lmx_b23:
	v_lshlrev_b32_e32 v98, 16, v216
	v_and_b32_e32 v99, 0xffff0000, v216
	v_pk_fma_f32 v[172:173], v[152:153], v[98:99], v[172:173]
	v_pk_fma_f32 v[174:175], v[150:151], v[98:99], v[174:175]
	v_pk_fma_f32 v[176:177], v[148:149], v[98:99], v[176:177]
	v_pk_fma_f32 v[178:179], v[146:147], v[98:99], v[178:179]
	v_pk_fma_f32 v[180:181], v[144:145], v[98:99], v[180:181]
	v_pk_fma_f32 v[182:183], v[142:143], v[98:99], v[182:183]
	v_pk_fma_f32 v[184:185], v[140:141], v[98:99], v[184:185]
	v_pk_fma_f32 v[186:187], v[138:139], v[98:99], v[186:187]
	v_pk_fma_f32 v[188:189], v[136:137], v[98:99], v[188:189]
	v_pk_fma_f32 v[190:191], v[134:135], v[98:99], v[190:191]
	v_pk_fma_f32 v[78:79], v[132:133], v[98:99], v[78:79]
	v_pk_fma_f32 v[80:81], v[130:131], v[98:99], v[80:81]
	v_pk_fma_f32 v[82:83], v[128:129], v[98:99], v[82:83]
	v_pk_fma_f32 v[84:85], v[126:127], v[98:99], v[84:85]
	v_pk_fma_f32 v[86:87], v[124:125], v[98:99], v[86:87]
	v_pk_fma_f32 v[88:89], v[122:123], v[98:99], v[88:89]
	s_waitcnt vmcnt(21)
	s_cbranch_vccnz .Lmx_e24
; __device__ __forceinline__ f32x2v bf2(unsigned v) { return (f32x2v){bflo(v), bfhi(v)}; }
; __device__ __forceinline__ void mixer_prompt_run(const Args& p, int run, int c2) {
;     ...
;             for (int i = 0; i < 38; ++i) {
;                 const int ti = t0 + 8 * hh - 30 + i; unsigned v = U32[(rowb + (ti >= 0 ? ti : 0)) * 256 + c2]; v = (ti >= 0) ? v : 0u; const f32x2v x = bf2(v);
; #pragma unroll
;                 for (int t = 0; t < 8; ++t) { const int j = i - t; if (j >= 0 && j <= 30) a[t] = w[j] * x + a[t]; }
.Lmx_b24:
	v_lshlrev_b32_e32 v96, 16, v217
	v_and_b32_e32 v97, 0xffff0000, v217
	v_pk_fma_f32 v[172:173], v[154:155], v[96:97], v[172:173]
	v_pk_fma_f32 v[174:175], v[152:153], v[96:97], v[174:175]
	v_pk_fma_f32 v[176:177], v[150:151], v[96:97], v[176:177]
	v_pk_fma_f32 v[178:179], v[148:149], v[96:97], v[178:179]
	v_pk_fma_f32 v[180:181], v[146:147], v[96:97], v[180:181]
	v_pk_fma_f32 v[182:183], v[144:145], v[96:97], v[182:183]
	v_pk_fma_f32 v[184:185], v[142:143], v[96:97], v[184:185]
	v_pk_fma_f32 v[186:187], v[140:141], v[96:97], v[186:187]
	v_pk_fma_f32 v[188:189], v[138:139], v[96:97], v[188:189]
	v_pk_fma_f32 v[190:191], v[136:137], v[96:97], v[190:191]
	v_pk_fma_f32 v[78:79], v[134:135], v[96:97], v[78:79]
	v_pk_fma_f32 v[80:81], v[132:133], v[96:97], v[80:81]
	v_pk_fma_f32 v[82:83], v[130:131], v[96:97], v[82:83]
	v_pk_fma_f32 v[84:85], v[128:129], v[96:97], v[84:85]
	v_pk_fma_f32 v[86:87], v[126:127], v[96:97], v[86:87]
	v_pk_fma_f32 v[88:89], v[124:125], v[96:97], v[88:89]
	s_waitcnt vmcnt(20)
	s_cbranch_vccnz .Lmx_e25
.Lmx_b25:
	v_lshlrev_b32_e32 v98, 16, v218
	v_and_b32_e32 v99, 0xffff0000, v218
	v_pk_fma_f32 v[172:173], v[156:157], v[98:99], v[172:173]
	v_pk_fma_f32 v[174:175], v[154:155], v[98:99], v[174:175]
	v_pk_fma_f32 v[176:177], v[152:153], v[98:99], v[176:177]
	v_pk_fma_f32 v[178:179], v[150:151], v[98:99], v[178:179]
	v_pk_fma_f32 v[180:181], v[148:149], v[98:99], v[180:181]
	v_pk_fma_f32 v[182:183], v[146:147], v[98:99], v[182:183]
	v_pk_fma_f32 v[184:185], v[144:145], v[98:99], v[184:185]
	v_pk_fma_f32 v[186:187], v[142:143], v[98:99], v[186:187]
	v_pk_fma_f32 v[188:189], v[140:141], v[98:99], v[188:189]
	v_pk_fma_f32 v[190:191], v[138:139], v[98:99], v[190:191]
	v_pk_fma_f32 v[78:79], v[136:137], v[98:99], v[78:79]
	v_pk_fma_f32 v[80:81], v[134:135], v[98:99], v[80:81]
	v_pk_fma_f32 v[82:83], v[132:133], v[98:99], v[82:83]
	v_pk_fma_f32 v[84:85], v[130:131], v[98:99], v[84:85]
	v_pk_fma_f32 v[86:87], v[128:129], v[98:99], v[86:87]
	v_pk_fma_f32 v[88:89], v[126:127], v[98:99], v[88:89]
	s_waitcnt vmcnt(19)
	s_cbranch_vccnz .Lmx_e26
.Lmx_b26:
	v_lshlrev_b32_e32 v96, 16, v219
	v_and_b32_e32 v97, 0xffff0000, v219
	v_pk_fma_f32 v[172:173], v[158:159], v[96:97], v[172:173]
	v_pk_fma_f32 v[174:175], v[156:157], v[96:97], v[174:175]
	v_pk_fma_f32 v[176:177], v[154:155], v[96:97], v[176:177]
	v_pk_fma_f32 v[178:179], v[152:153], v[96:97], v[178:179]
	v_pk_fma_f32 v[180:181], v[150:151], v[96:97], v[180:181]
	v_pk_fma_f32 v[182:183], v[148:149], v[96:97], v[182:183]
	v_pk_fma_f32 v[184:185], v[146:147], v[96:97], v[184:185]
	v_pk_fma_f32 v[186:187], v[144:145], v[96:97], v[186:187]
	v_pk_fma_f32 v[188:189], v[142:143], v[96:97], v[188:189]
	v_pk_fma_f32 v[190:191], v[140:141], v[96:97], v[190:191]
	v_pk_fma_f32 v[78:79], v[138:139], v[96:97], v[78:79]
	v_pk_fma_f32 v[80:81], v[136:137], v[96:97], v[80:81]
	v_pk_fma_f32 v[82:83], v[134:135], v[96:97], v[82:83]
	v_pk_fma_f32 v[84:85], v[132:133], v[96:97], v[84:85]
	v_pk_fma_f32 v[86:87], v[130:131], v[96:97], v[86:87]
	v_pk_fma_f32 v[88:89], v[128:129], v[96:97], v[88:89]
	s_waitcnt vmcnt(18)
	s_cbranch_vccnz .Lmx_e27
.Lmx_b27:
	v_lshlrev_b32_e32 v98, 16, v220
	v_and_b32_e32 v99, 0xffff0000, v220
	v_pk_fma_f32 v[172:173], v[160:161], v[98:99], v[172:173]
	v_pk_fma_f32 v[174:175], v[158:159], v[98:99], v[174:175]
	v_pk_fma_f32 v[176:177], v[156:157], v[98:99], v[176:177]
	v_pk_fma_f32 v[178:179], v[154:155], v[98:99], v[178:179]
	v_pk_fma_f32 v[180:181], v[152:153], v[98:99], v[180:181]
	v_pk_fma_f32 v[182:183], v[150:151], v[98:99], v[182:183]
	v_pk_fma_f32 v[184:185], v[148:149], v[98:99], v[184:185]
	v_pk_fma_f32 v[186:187], v[146:147], v[98:99], v[186:187]
	v_pk_fma_f32 v[188:189], v[144:145], v[98:99], v[188:189]
	v_pk_fma_f32 v[190:191], v[142:143], v[98:99], v[190:191]
	v_pk_fma_f32 v[78:79], v[140:141], v[98:99], v[78:79]
	v_pk_fma_f32 v[80:81], v[138:139], v[98:99], v[80:81]
	v_pk_fma_f32 v[82:83], v[136:137], v[98:99], v[82:83]
	v_pk_fma_f32 v[84:85], v[134:135], v[98:99], v[84:85]
	v_pk_fma_f32 v[86:87], v[132:133], v[98:99], v[86:87]
	v_pk_fma_f32 v[88:89], v[130:131], v[98:99], v[88:89]
	s_waitcnt vmcnt(17)
	s_cbranch_vccnz .Lmx_e28
.Lmx_b28:
	v_lshlrev_b32_e32 v96, 16, v221
	v_and_b32_e32 v97, 0xffff0000, v221
	v_pk_fma_f32 v[172:173], v[162:163], v[96:97], v[172:173]
	v_pk_fma_f32 v[174:175], v[160:161], v[96:97], v[174:175]
	v_pk_fma_f32 v[176:177], v[158:159], v[96:97], v[176:177]
	v_pk_fma_f32 v[178:179], v[156:157], v[96:97], v[178:179]
	v_pk_fma_f32 v[180:181], v[154:155], v[96:97], v[180:181]
	v_pk_fma_f32 v[182:183], v[152:153], v[96:97], v[182:183]
	v_pk_fma_f32 v[184:185], v[150:151], v[96:97], v[184:185]
	v_pk_fma_f32 v[186:187], v[148:149], v[96:97], v[186:187]
	v_pk_fma_f32 v[188:189], v[146:147], v[96:97], v[188:189]
	v_pk_fma_f32 v[190:191], v[144:145], v[96:97], v[190:191]
	v_pk_fma_f32 v[78:79], v[142:143], v[96:97], v[78:79]
	v_pk_fma_f32 v[80:81], v[140:141], v[96:97], v[80:81]
	v_pk_fma_f32 v[82:83], v[138:139], v[96:97], v[82:83]
	v_pk_fma_f32 v[84:85], v[136:137], v[96:97], v[84:85]
	v_pk_fma_f32 v[86:87], v[134:135], v[96:97], v[86:87]
	v_pk_fma_f32 v[88:89], v[132:133], v[96:97], v[88:89]
	s_waitcnt vmcnt(16)
	s_cbranch_vccnz .Lmx_e29
; __device__ __forceinline__ f32x2v bf2(unsigned v) { return (f32x2v){bflo(v), bfhi(v)}; }
; __device__ __forceinline__ void mixer_prompt_run(const Args& p, int run, int c2) {
;     ...
;             for (int i = 0; i < 38; ++i) {
;                 const int ti = t0 + 8 * hh - 30 + i; unsigned v = U32[(rowb + (ti >= 0 ? ti : 0)) * 256 + c2]; v = (ti >= 0) ? v : 0u; const f32x2v x = bf2(v);
; #pragma unroll
;                 for (int t = 0; t < 8; ++t) { const int j = i - t; if (j >= 0 && j <= 30) a[t] = w[j] * x + a[t]; }
.Lmx_b29:
	v_lshlrev_b32_e32 v98, 16, v222
	v_and_b32_e32 v99, 0xffff0000, v222
	v_pk_fma_f32 v[172:173], v[168:169], v[98:99], v[172:173]
	v_pk_fma_f32 v[174:175], v[162:163], v[98:99], v[174:175]
	v_pk_fma_f32 v[176:177], v[160:161], v[98:99], v[176:177]
	v_pk_fma_f32 v[178:179], v[158:159], v[98:99], v[178:179]
	v_pk_fma_f32 v[180:181], v[156:157], v[98:99], v[180:181]
	v_pk_fma_f32 v[182:183], v[154:155], v[98:99], v[182:183]
	v_pk_fma_f32 v[184:185], v[152:153], v[98:99], v[184:185]
	v_pk_fma_f32 v[186:187], v[150:151], v[98:99], v[186:187]
	v_pk_fma_f32 v[188:189], v[148:149], v[98:99], v[188:189]
	v_pk_fma_f32 v[190:191], v[146:147], v[98:99], v[190:191]
	v_pk_fma_f32 v[78:79], v[144:145], v[98:99], v[78:79]
	v_pk_fma_f32 v[80:81], v[142:143], v[98:99], v[80:81]
	v_pk_fma_f32 v[82:83], v[140:141], v[98:99], v[82:83]
	v_pk_fma_f32 v[84:85], v[138:139], v[98:99], v[84:85]
	v_pk_fma_f32 v[86:87], v[136:137], v[98:99], v[86:87]
	v_pk_fma_f32 v[88:89], v[134:135], v[98:99], v[88:89]
	s_waitcnt vmcnt(15)
	v_lshlrev_b32_e32 v96, 16, v223
	v_and_b32_e32 v97, 0xffff0000, v223
	v_pk_fma_f32 v[172:173], v[170:171], v[96:97], v[172:173]
	v_pk_fma_f32 v[174:175], v[168:169], v[96:97], v[174:175]
	v_pk_fma_f32 v[176:177], v[162:163], v[96:97], v[176:177]
	v_pk_fma_f32 v[178:179], v[160:161], v[96:97], v[178:179]
	v_pk_fma_f32 v[180:181], v[158:159], v[96:97], v[180:181]
	v_pk_fma_f32 v[182:183], v[156:157], v[96:97], v[182:183]
	v_pk_fma_f32 v[184:185], v[154:155], v[96:97], v[184:185]
	v_pk_fma_f32 v[186:187], v[152:153], v[96:97], v[186:187]
	v_pk_fma_f32 v[188:189], v[150:151], v[96:97], v[188:189]
	v_pk_fma_f32 v[190:191], v[148:149], v[96:97], v[190:191]
	v_pk_fma_f32 v[78:79], v[146:147], v[96:97], v[78:79]
	v_pk_fma_f32 v[80:81], v[144:145], v[96:97], v[80:81]
	v_pk_fma_f32 v[82:83], v[142:143], v[96:97], v[82:83]
	v_pk_fma_f32 v[84:85], v[140:141], v[96:97], v[84:85]
	v_pk_fma_f32 v[86:87], v[138:139], v[96:97], v[86:87]
	v_pk_fma_f32 v[88:89], v[136:137], v[96:97], v[88:89]
	s_waitcnt vmcnt(14)
	v_lshlrev_b32_e32 v98, 16, v224
	v_and_b32_e32 v99, 0xffff0000, v224
	v_pk_fma_f32 v[174:175], v[170:171], v[98:99], v[174:175]
	v_pk_fma_f32 v[176:177], v[168:169], v[98:99], v[176:177]
	v_pk_fma_f32 v[178:179], v[162:163], v[98:99], v[178:179]
	v_pk_fma_f32 v[180:181], v[160:161], v[98:99], v[180:181]
	v_pk_fma_f32 v[182:183], v[158:159], v[98:99], v[182:183]
	v_pk_fma_f32 v[184:185], v[156:157], v[98:99], v[184:185]
	v_pk_fma_f32 v[186:187], v[154:155], v[98:99], v[186:187]
	v_pk_fma_f32 v[188:189], v[152:153], v[98:99], v[188:189]
	v_pk_fma_f32 v[190:191], v[150:151], v[98:99], v[190:191]
	v_pk_fma_f32 v[78:79], v[148:149], v[98:99], v[78:79]
	v_pk_fma_f32 v[80:81], v[146:147], v[98:99], v[80:81]
	v_pk_fma_f32 v[82:83], v[144:145], v[98:99], v[82:83]
	v_pk_fma_f32 v[84:85], v[142:143], v[98:99], v[84:85]
	v_pk_fma_f32 v[86:87], v[140:141], v[98:99], v[86:87]
	v_pk_fma_f32 v[88:89], v[138:139], v[98:99], v[88:89]
	s_waitcnt vmcnt(13)
	v_lshlrev_b32_e32 v96, 16, v225
	v_and_b32_e32 v97, 0xffff0000, v225
	v_pk_fma_f32 v[176:177], v[170:171], v[96:97], v[176:177]
	v_pk_fma_f32 v[178:179], v[168:169], v[96:97], v[178:179]
	v_pk_fma_f32 v[180:181], v[162:163], v[96:97], v[180:181]
	v_pk_fma_f32 v[182:183], v[160:161], v[96:97], v[182:183]
	v_pk_fma_f32 v[184:185], v[158:159], v[96:97], v[184:185]
	v_pk_fma_f32 v[186:187], v[156:157], v[96:97], v[186:187]
	v_pk_fma_f32 v[188:189], v[154:155], v[96:97], v[188:189]
	v_pk_fma_f32 v[190:191], v[152:153], v[96:97], v[190:191]
	v_pk_fma_f32 v[78:79], v[150:151], v[96:97], v[78:79]
	v_pk_fma_f32 v[80:81], v[148:149], v[96:97], v[80:81]
	v_pk_fma_f32 v[82:83], v[146:147], v[96:97], v[82:83]
	v_pk_fma_f32 v[84:85], v[144:145], v[96:97], v[84:85]
	v_pk_fma_f32 v[86:87], v[142:143], v[96:97], v[86:87]
	v_pk_fma_f32 v[88:89], v[140:141], v[96:97], v[88:89]
	s_waitcnt vmcnt(12)
	v_lshlrev_b32_e32 v98, 16, v226
	v_and_b32_e32 v99, 0xffff0000, v226
	v_pk_fma_f32 v[178:179], v[170:171], v[98:99], v[178:179]
	v_pk_fma_f32 v[180:181], v[168:169], v[98:99], v[180:181]
	v_pk_fma_f32 v[182:183], v[162:163], v[98:99], v[182:183]
	v_pk_fma_f32 v[184:185], v[160:161], v[98:99], v[184:185]
	v_pk_fma_f32 v[186:187], v[158:159], v[98:99], v[186:187]
	v_pk_fma_f32 v[188:189], v[156:157], v[98:99], v[188:189]
	v_pk_fma_f32 v[190:191], v[154:155], v[98:99], v[190:191]
	v_pk_fma_f32 v[78:79], v[152:153], v[98:99], v[78:79]
	v_pk_fma_f32 v[80:81], v[150:151], v[98:99], v[80:81]
	v_pk_fma_f32 v[82:83], v[148:149], v[98:99], v[82:83]
	v_pk_fma_f32 v[84:85], v[146:147], v[98:99], v[84:85]
	v_pk_fma_f32 v[86:87], v[144:145], v[98:99], v[86:87]
	v_pk_fma_f32 v[88:89], v[142:143], v[98:99], v[88:89]
	s_waitcnt vmcnt(11)
	v_lshlrev_b32_e32 v96, 16, v227
	v_and_b32_e32 v97, 0xffff0000, v227
	v_pk_fma_f32 v[180:181], v[170:171], v[96:97], v[180:181]
	v_pk_fma_f32 v[182:183], v[168:169], v[96:97], v[182:183]
	v_pk_fma_f32 v[184:185], v[162:163], v[96:97], v[184:185]
	v_pk_fma_f32 v[186:187], v[160:161], v[96:97], v[186:187]
	v_pk_fma_f32 v[188:189], v[158:159], v[96:97], v[188:189]
	v_pk_fma_f32 v[190:191], v[156:157], v[96:97], v[190:191]
	v_pk_fma_f32 v[78:79], v[154:155], v[96:97], v[78:79]
	v_pk_fma_f32 v[80:81], v[152:153], v[96:97], v[80:81]
	v_pk_fma_f32 v[82:83], v[150:151], v[96:97], v[82:83]
	v_pk_fma_f32 v[84:85], v[148:149], v[96:97], v[84:85]
	v_pk_fma_f32 v[86:87], v[146:147], v[96:97], v[86:87]
	v_pk_fma_f32 v[88:89], v[144:145], v[96:97], v[88:89]
	s_waitcnt vmcnt(10)
; __device__ __forceinline__ f32x2v bf2(unsigned v) { return (f32x2v){bflo(v), bfhi(v)}; }
; __device__ __forceinline__ void mixer_prompt_run(const Args& p, int run, int c2) {
;     ...
;             for (int i = 0; i < 38; ++i) {
;                 const int ti = t0 + 8 * hh - 30 + i; unsigned v = U32[(rowb + (ti >= 0 ? ti : 0)) * 256 + c2]; v = (ti >= 0) ? v : 0u; const f32x2v x = bf2(v);
; #pragma unroll
;                 for (int t = 0; t < 8; ++t) { const int j = i - t; if (j >= 0 && j <= 30) a[t] = w[j] * x + a[t]; }
	v_lshlrev_b32_e32 v98, 16, v228
	v_and_b32_e32 v99, 0xffff0000, v228
	v_pk_fma_f32 v[182:183], v[170:171], v[98:99], v[182:183]
	v_pk_fma_f32 v[184:185], v[168:169], v[98:99], v[184:185]
	v_pk_fma_f32 v[186:187], v[162:163], v[98:99], v[186:187]
	v_pk_fma_f32 v[188:189], v[160:161], v[98:99], v[188:189]
	v_pk_fma_f32 v[190:191], v[158:159], v[98:99], v[190:191]
	v_pk_fma_f32 v[78:79], v[156:157], v[98:99], v[78:79]
	v_pk_fma_f32 v[80:81], v[154:155], v[98:99], v[80:81]
	v_pk_fma_f32 v[82:83], v[152:153], v[98:99], v[82:83]
	v_pk_fma_f32 v[84:85], v[150:151], v[98:99], v[84:85]
	v_pk_fma_f32 v[86:87], v[148:149], v[98:99], v[86:87]
	v_pk_fma_f32 v[88:89], v[146:147], v[98:99], v[88:89]
	s_waitcnt vmcnt(9)
	v_lshlrev_b32_e32 v96, 16, v229
	v_and_b32_e32 v97, 0xffff0000, v229
	v_pk_fma_f32 v[184:185], v[170:171], v[96:97], v[184:185]
	v_pk_fma_f32 v[186:187], v[168:169], v[96:97], v[186:187]
	v_pk_fma_f32 v[188:189], v[162:163], v[96:97], v[188:189]
	v_pk_fma_f32 v[190:191], v[160:161], v[96:97], v[190:191]
	v_pk_fma_f32 v[78:79], v[158:159], v[96:97], v[78:79]
	v_pk_fma_f32 v[80:81], v[156:157], v[96:97], v[80:81]
	v_pk_fma_f32 v[82:83], v[154:155], v[96:97], v[82:83]
	v_pk_fma_f32 v[84:85], v[152:153], v[96:97], v[84:85]
	v_pk_fma_f32 v[86:87], v[150:151], v[96:97], v[86:87]
	v_pk_fma_f32 v[88:89], v[148:149], v[96:97], v[88:89]
	s_waitcnt vmcnt(8)
	v_lshlrev_b32_e32 v98, 16, v230
	v_and_b32_e32 v99, 0xffff0000, v230
	v_pk_fma_f32 v[186:187], v[170:171], v[98:99], v[186:187]
	v_pk_fma_f32 v[188:189], v[168:169], v[98:99], v[188:189]
	v_pk_fma_f32 v[190:191], v[162:163], v[98:99], v[190:191]
	v_pk_fma_f32 v[78:79], v[160:161], v[98:99], v[78:79]
	v_pk_fma_f32 v[80:81], v[158:159], v[98:99], v[80:81]
	v_pk_fma_f32 v[82:83], v[156:157], v[98:99], v[82:83]
	v_pk_fma_f32 v[84:85], v[154:155], v[98:99], v[84:85]
	v_pk_fma_f32 v[86:87], v[152:153], v[98:99], v[86:87]
	v_pk_fma_f32 v[88:89], v[150:151], v[98:99], v[88:89]
	s_waitcnt vmcnt(7)
	v_lshlrev_b32_e32 v96, 16, v231
	v_and_b32_e32 v97, 0xffff0000, v231
	v_pk_fma_f32 v[188:189], v[170:171], v[96:97], v[188:189]
	v_pk_fma_f32 v[190:191], v[168:169], v[96:97], v[190:191]
	v_pk_fma_f32 v[78:79], v[162:163], v[96:97], v[78:79]
	v_pk_fma_f32 v[80:81], v[160:161], v[96:97], v[80:81]
	v_pk_fma_f32 v[82:83], v[158:159], v[96:97], v[82:83]
	v_pk_fma_f32 v[84:85], v[156:157], v[96:97], v[84:85]
	v_pk_fma_f32 v[86:87], v[154:155], v[96:97], v[86:87]
	v_pk_fma_f32 v[88:89], v[152:153], v[96:97], v[88:89]
	s_waitcnt vmcnt(6)
	v_lshlrev_b32_e32 v98, 16, v232
	v_and_b32_e32 v99, 0xffff0000, v232
	v_pk_fma_f32 v[190:191], v[170:171], v[98:99], v[190:191]
	v_pk_fma_f32 v[78:79], v[168:169], v[98:99], v[78:79]
	v_pk_fma_f32 v[80:81], v[162:163], v[98:99], v[80:81]
	v_pk_fma_f32 v[82:83], v[160:161], v[98:99], v[82:83]
	v_pk_fma_f32 v[84:85], v[158:159], v[98:99], v[84:85]
	v_pk_fma_f32 v[86:87], v[156:157], v[98:99], v[86:87]
	v_pk_fma_f32 v[88:89], v[154:155], v[98:99], v[88:89]
	s_waitcnt vmcnt(5)
	v_lshlrev_b32_e32 v96, 16, v233
	v_and_b32_e32 v97, 0xffff0000, v233
	v_pk_fma_f32 v[78:79], v[170:171], v[96:97], v[78:79]
	v_pk_fma_f32 v[80:81], v[168:169], v[96:97], v[80:81]
	v_pk_fma_f32 v[82:83], v[162:163], v[96:97], v[82:83]
	v_pk_fma_f32 v[84:85], v[160:161], v[96:97], v[84:85]
	v_pk_fma_f32 v[86:87], v[158:159], v[96:97], v[86:87]
	v_pk_fma_f32 v[88:89], v[156:157], v[96:97], v[88:89]
	s_waitcnt vmcnt(4)
	v_lshlrev_b32_e32 v98, 16, v234
	v_and_b32_e32 v99, 0xffff0000, v234
	v_pk_fma_f32 v[80:81], v[170:171], v[98:99], v[80:81]
	v_pk_fma_f32 v[82:83], v[168:169], v[98:99], v[82:83]
	v_pk_fma_f32 v[84:85], v[162:163], v[98:99], v[84:85]
	v_pk_fma_f32 v[86:87], v[160:161], v[98:99], v[86:87]
	v_pk_fma_f32 v[88:89], v[158:159], v[98:99], v[88:89]
	s_waitcnt vmcnt(3)
	v_lshlrev_b32_e32 v96, 16, v235
	v_and_b32_e32 v97, 0xffff0000, v235
	v_pk_fma_f32 v[82:83], v[170:171], v[96:97], v[82:83]
	v_pk_fma_f32 v[84:85], v[168:169], v[96:97], v[84:85]
	v_pk_fma_f32 v[86:87], v[162:163], v[96:97], v[86:87]
	v_pk_fma_f32 v[88:89], v[160:161], v[96:97], v[88:89]
	s_waitcnt vmcnt(2)
	v_lshlrev_b32_e32 v98, 16, v236
	v_and_b32_e32 v99, 0xffff0000, v236
	v_pk_fma_f32 v[84:85], v[170:171], v[98:99], v[84:85]
	v_pk_fma_f32 v[86:87], v[168:169], v[98:99], v[86:87]
	v_pk_fma_f32 v[88:89], v[162:163], v[98:99], v[88:89]
	s_waitcnt vmcnt(1)
	v_lshlrev_b32_e32 v96, 16, v237
	v_and_b32_e32 v97, 0xffff0000, v237
	v_pk_fma_f32 v[86:87], v[170:171], v[96:97], v[86:87]
	v_pk_fma_f32 v[88:89], v[168:169], v[96:97], v[88:89]
	s_waitcnt vmcnt(0)
; __device__ __forceinline__ unsigned pk2(float lo, float hi) { f32x2v v = {lo, hi}; b16x2v b = __builtin_convertvector(v, b16x2v); return __builtin_bit_cast(unsigned, b); }
; __device__ __forceinline__ float fsigmoid(float x) { return __builtin_amdgcn_rcpf(1.0f + __expf(-x)); }
; template <int CTRL> __device__ __forceinline__ float dpp_mov(float v) { return __builtin_bit_cast(float, __builtin_amdgcn_update_dpp(0, __builtin_bit_cast(int, v), CTRL, 0xf, 0xf, true)); }
; __device__ __forceinline__ float half_wave_sum(float v) {
;     v += dpp_mov<0xB1>(v);
;     v += dpp_mov<0x4E>(v);
;     v += dpp_mov<0x141>(v);
;     v += dpp_mov<0x140>(v);
;     v += __shfl_xor(v, 16);
;     return v;
; }
; __device__ __forceinline__ void gn_swish_store(float v0, float v1, f32x2v gg, f32x2v gb, unsigned* dst) {
;     const float mean = half_wave_sum(v0 + v1) * (1.0f / 64.0f); const float d0 = v0 - mean, d1 = v1 - mean;
;     const float rstd = rsqrtf(half_wave_sum(d0 * d0 + d1 * d1) * (1.0f / 64.0f) + LN_EPS);
;     float y0 = d0 * rstd * gg.x + gb.x, y1 = d1 * rstd * gg.y + gb.y;
;     y0 = y0 * fsigmoid(y0); y1 = y1 * fsigmoid(y1);
;     *dst = pk2(y0, y1);
	v_lshlrev_b32_e32 v98, 16, v238
	v_and_b32_e32 v99, 0xffff0000, v238
	v_pk_fma_f32 v[88:89], v[170:171], v[98:99], v[88:89]
	v_add_f32_e32 v194, v172, v173
	v_add_f32_e32 v198, v174, v175
	v_add_f32_e32 v202, v176, v177
	v_add_f32_e32 v206, v178, v179
	v_add_f32_e32 v210, v180, v181
	v_add_f32_e32 v214, v182, v183
	v_add_f32_e32 v218, v184, v185
	v_add_f32_e32 v222, v186, v187
	v_add_f32_dpp v194, v194, v194 quad_perm:[1,0,3,2] row_mask:0xf bank_mask:0xf bound_ctrl:1
	v_add_f32_dpp v198, v198, v198 quad_perm:[1,0,3,2] row_mask:0xf bank_mask:0xf bound_ctrl:1
	v_add_f32_dpp v202, v202, v202 quad_perm:[1,0,3,2] row_mask:0xf bank_mask:0xf bound_ctrl:1
	v_add_f32_dpp v206, v206, v206 quad_perm:[1,0,3,2] row_mask:0xf bank_mask:0xf bound_ctrl:1
	v_add_f32_dpp v210, v210, v210 quad_perm:[1,0,3,2] row_mask:0xf bank_mask:0xf bound_ctrl:1
	v_add_f32_dpp v214, v214, v214 quad_perm:[1,0,3,2] row_mask:0xf bank_mask:0xf bound_ctrl:1
	v_add_f32_dpp v218, v218, v218 quad_perm:[1,0,3,2] row_mask:0xf bank_mask:0xf bound_ctrl:1
	v_add_f32_dpp v222, v222, v222 quad_perm:[1,0,3,2] row_mask:0xf bank_mask:0xf bound_ctrl:1
	v_add_f32_dpp v194, v194, v194 quad_perm:[2,3,0,1] row_mask:0xf bank_mask:0xf bound_ctrl:1
	v_add_f32_dpp v198, v198, v198 quad_perm:[2,3,0,1] row_mask:0xf bank_mask:0xf bound_ctrl:1
	v_add_f32_dpp v202, v202, v202 quad_perm:[2,3,0,1] row_mask:0xf bank_mask:0xf bound_ctrl:1
	v_add_f32_dpp v206, v206, v206 quad_perm:[2,3,0,1] row_mask:0xf bank_mask:0xf bound_ctrl:1
	v_add_f32_dpp v210, v210, v210 quad_perm:[2,3,0,1] row_mask:0xf bank_mask:0xf bound_ctrl:1
	v_add_f32_dpp v214, v214, v214 quad_perm:[2,3,0,1] row_mask:0xf bank_mask:0xf bound_ctrl:1
	v_add_f32_dpp v218, v218, v218 quad_perm:[2,3,0,1] row_mask:0xf bank_mask:0xf bound_ctrl:1
	v_add_f32_dpp v222, v222, v222 quad_perm:[2,3,0,1] row_mask:0xf bank_mask:0xf bound_ctrl:1
	v_add_f32_dpp v194, v194, v194 row_half_mirror row_mask:0xf bank_mask:0xf bound_ctrl:1
	v_add_f32_dpp v198, v198, v198 row_half_mirror row_mask:0xf bank_mask:0xf bound_ctrl:1
	v_add_f32_dpp v202, v202, v202 row_half_mirror row_mask:0xf bank_mask:0xf bound_ctrl:1
	v_add_f32_dpp v206, v206, v206 row_half_mirror row_mask:0xf bank_mask:0xf bound_ctrl:1
	v_add_f32_dpp v210, v210, v210 row_half_mirror row_mask:0xf bank_mask:0xf bound_ctrl:1
	v_add_f32_dpp v214, v214, v214 row_half_mirror row_mask:0xf bank_mask:0xf bound_ctrl:1
	v_add_f32_dpp v218, v218, v218 row_half_mirror row_mask:0xf bank_mask:0xf bound_ctrl:1
	v_add_f32_dpp v222, v222, v222 row_half_mirror row_mask:0xf bank_mask:0xf bound_ctrl:1
	v_add_f32_dpp v194, v194, v194 row_mirror row_mask:0xf bank_mask:0xf bound_ctrl:1
	v_add_f32_dpp v198, v198, v198 row_mirror row_mask:0xf bank_mask:0xf bound_ctrl:1
	v_add_f32_dpp v202, v202, v202 row_mirror row_mask:0xf bank_mask:0xf bound_ctrl:1
	v_add_f32_dpp v206, v206, v206 row_mirror row_mask:0xf bank_mask:0xf bound_ctrl:1
	v_add_f32_dpp v210, v210, v210 row_mirror row_mask:0xf bank_mask:0xf bound_ctrl:1
	v_add_f32_dpp v214, v214, v214 row_mirror row_mask:0xf bank_mask:0xf bound_ctrl:1
	v_add_f32_dpp v218, v218, v218 row_mirror row_mask:0xf bank_mask:0xf bound_ctrl:1
	v_add_f32_dpp v222, v222, v222 row_mirror row_mask:0xf bank_mask:0xf bound_ctrl:1
	ds_bpermute_b32 v195, v239, v194
	ds_bpermute_b32 v199, v239, v198
	ds_bpermute_b32 v203, v239, v202
	ds_bpermute_b32 v207, v239, v206
	ds_bpermute_b32 v211, v239, v210
	ds_bpermute_b32 v215, v239, v214
	ds_bpermute_b32 v219, v239, v218
	ds_bpermute_b32 v223, v239, v222
	s_waitcnt lgkmcnt(7)
	v_add_f32_e32 v194, v194, v195
	s_waitcnt lgkmcnt(6)
	v_add_f32_e32 v198, v198, v199
	s_waitcnt lgkmcnt(5)
	v_add_f32_e32 v202, v202, v203
	s_waitcnt lgkmcnt(4)
	v_add_f32_e32 v206, v206, v207
	s_waitcnt lgkmcnt(3)
	v_add_f32_e32 v210, v210, v211
	s_waitcnt lgkmcnt(2)
	v_add_f32_e32 v214, v214, v215
	s_waitcnt lgkmcnt(1)
	v_add_f32_e32 v218, v218, v219
	s_waitcnt lgkmcnt(0)
	v_add_f32_e32 v222, v222, v223
	v_mul_f32_e32 v194, 0x3c800000, v194
	v_mul_f32_e32 v198, 0x3c800000, v198
	v_mul_f32_e32 v202, 0x3c800000, v202
	v_mul_f32_e32 v206, 0x3c800000, v206
	v_mul_f32_e32 v210, 0x3c800000, v210
	v_mul_f32_e32 v214, 0x3c800000, v214
	v_mul_f32_e32 v218, 0x3c800000, v218
	v_mul_f32_e32 v222, 0x3c800000, v222
	v_pk_add_f32 v[172:173], v[172:173], v[194:195] op_sel_hi:[1,0] neg_lo:[0,1] neg_hi:[0,1]
	v_pk_add_f32 v[174:175], v[174:175], v[198:199] op_sel_hi:[1,0] neg_lo:[0,1] neg_hi:[0,1]
	v_pk_add_f32 v[176:177], v[176:177], v[202:203] op_sel_hi:[1,0] neg_lo:[0,1] neg_hi:[0,1]
	v_pk_add_f32 v[178:179], v[178:179], v[206:207] op_sel_hi:[1,0] neg_lo:[0,1] neg_hi:[0,1]
	v_pk_add_f32 v[180:181], v[180:181], v[210:211] op_sel_hi:[1,0] neg_lo:[0,1] neg_hi:[0,1]
	v_pk_add_f32 v[182:183], v[182:183], v[214:215] op_sel_hi:[1,0] neg_lo:[0,1] neg_hi:[0,1]
	v_pk_add_f32 v[184:185], v[184:185], v[218:219] op_sel_hi:[1,0] neg_lo:[0,1] neg_hi:[0,1]
	v_pk_add_f32 v[186:187], v[186:187], v[222:223] op_sel_hi:[1,0] neg_lo:[0,1] neg_hi:[0,1]
	v_pk_mul_f32 v[196:197], v[172:173], v[172:173]
	v_pk_mul_f32 v[200:201], v[174:175], v[174:175]
	v_pk_mul_f32 v[204:205], v[176:177], v[176:177]
	v_pk_mul_f32 v[208:209], v[178:179], v[178:179]
	v_pk_mul_f32 v[212:213], v[180:181], v[180:181]
	v_pk_mul_f32 v[216:217], v[182:183], v[182:183]
	v_pk_mul_f32 v[220:221], v[184:185], v[184:185]
	v_pk_mul_f32 v[224:225], v[186:187], v[186:187]
	v_add_f32_e32 v194, v196, v197
	v_add_f32_e32 v198, v200, v201
	v_add_f32_e32 v202, v204, v205
	v_add_f32_e32 v206, v208, v209
	v_add_f32_e32 v210, v212, v213
	v_add_f32_e32 v214, v216, v217
	v_add_f32_e32 v218, v220, v221
	v_add_f32_e32 v222, v224, v225
; __device__ __forceinline__ unsigned pk2(float lo, float hi) { f32x2v v = {lo, hi}; b16x2v b = __builtin_convertvector(v, b16x2v); return __builtin_bit_cast(unsigned, b); }
; template <int CTRL> __device__ __forceinline__ float dpp_mov(float v) { return __builtin_bit_cast(float, __builtin_amdgcn_update_dpp(0, __builtin_bit_cast(int, v), CTRL, 0xf, 0xf, true)); }
; __device__ __forceinline__ float fsigmoid(float x) { return __builtin_amdgcn_rcpf(1.0f + __expf(-x)); }
; __device__ __forceinline__ float half_wave_sum(float v) {
;     v += dpp_mov<0xB1>(v);
;     v += dpp_mov<0x4E>(v);
;     v += dpp_mov<0x141>(v);
;     v += dpp_mov<0x140>(v);
;     v += __shfl_xor(v, 16);
;     return v;
; }
; __device__ __forceinline__ void gn_swish_store(float v0, float v1, f32x2v gg, f32x2v gb, unsigned* dst) {
;     const float mean = half_wave_sum(v0 + v1) * (1.0f / 64.0f); const float d0 = v0 - mean, d1 = v1 - mean;
;     const float rstd = rsqrtf(half_wave_sum(d0 * d0 + d1 * d1) * (1.0f / 64.0f) + LN_EPS);
;     float y0 = d0 * rstd * gg.x + gb.x, y1 = d1 * rstd * gg.y + gb.y;
;     y0 = y0 * fsigmoid(y0); y1 = y1 * fsigmoid(y1);
;     *dst = pk2(y0, y1);
	v_add_f32_dpp v194, v194, v194 quad_perm:[1,0,3,2] row_mask:0xf bank_mask:0xf bound_ctrl:1
	v_add_f32_dpp v198, v198, v198 quad_perm:[1,0,3,2] row_mask:0xf bank_mask:0xf bound_ctrl:1
	v_add_f32_dpp v202, v202, v202 quad_perm:[1,0,3,2] row_mask:0xf bank_mask:0xf bound_ctrl:1
	v_add_f32_dpp v206, v206, v206 quad_perm:[1,0,3,2] row_mask:0xf bank_mask:0xf bound_ctrl:1
	v_add_f32_dpp v210, v210, v210 quad_perm:[1,0,3,2] row_mask:0xf bank_mask:0xf bound_ctrl:1
	v_add_f32_dpp v214, v214, v214 quad_perm:[1,0,3,2] row_mask:0xf bank_mask:0xf bound_ctrl:1
	v_add_f32_dpp v218, v218, v218 quad_perm:[1,0,3,2] row_mask:0xf bank_mask:0xf bound_ctrl:1
	v_add_f32_dpp v222, v222, v222 quad_perm:[1,0,3,2] row_mask:0xf bank_mask:0xf bound_ctrl:1
	v_add_f32_dpp v194, v194, v194 quad_perm:[2,3,0,1] row_mask:0xf bank_mask:0xf bound_ctrl:1
	v_add_f32_dpp v198, v198, v198 quad_perm:[2,3,0,1] row_mask:0xf bank_mask:0xf bound_ctrl:1
	v_add_f32_dpp v202, v202, v202 quad_perm:[2,3,0,1] row_mask:0xf bank_mask:0xf bound_ctrl:1
	v_add_f32_dpp v206, v206, v206 quad_perm:[2,3,0,1] row_mask:0xf bank_mask:0xf bound_ctrl:1
	v_add_f32_dpp v210, v210, v210 quad_perm:[2,3,0,1] row_mask:0xf bank_mask:0xf bound_ctrl:1
	v_add_f32_dpp v214, v214, v214 quad_perm:[2,3,0,1] row_mask:0xf bank_mask:0xf bound_ctrl:1
	v_add_f32_dpp v218, v218, v218 quad_perm:[2,3,0,1] row_mask:0xf bank_mask:0xf bound_ctrl:1
	v_add_f32_dpp v222, v222, v222 quad_perm:[2,3,0,1] row_mask:0xf bank_mask:0xf bound_ctrl:1
	v_add_f32_dpp v194, v194, v194 row_half_mirror row_mask:0xf bank_mask:0xf bound_ctrl:1
	v_add_f32_dpp v198, v198, v198 row_half_mirror row_mask:0xf bank_mask:0xf bound_ctrl:1
	v_add_f32_dpp v202, v202, v202 row_half_mirror row_mask:0xf bank_mask:0xf bound_ctrl:1
	v_add_f32_dpp v206, v206, v206 row_half_mirror row_mask:0xf bank_mask:0xf bound_ctrl:1
	v_add_f32_dpp v210, v210, v210 row_half_mirror row_mask:0xf bank_mask:0xf bound_ctrl:1
	v_add_f32_dpp v214, v214, v214 row_half_mirror row_mask:0xf bank_mask:0xf bound_ctrl:1
	v_add_f32_dpp v218, v218, v218 row_half_mirror row_mask:0xf bank_mask:0xf bound_ctrl:1
	v_add_f32_dpp v222, v222, v222 row_half_mirror row_mask:0xf bank_mask:0xf bound_ctrl:1
	v_add_f32_dpp v194, v194, v194 row_mirror row_mask:0xf bank_mask:0xf bound_ctrl:1
	v_add_f32_dpp v198, v198, v198 row_mirror row_mask:0xf bank_mask:0xf bound_ctrl:1
	v_add_f32_dpp v202, v202, v202 row_mirror row_mask:0xf bank_mask:0xf bound_ctrl:1
	v_add_f32_dpp v206, v206, v206 row_mirror row_mask:0xf bank_mask:0xf bound_ctrl:1
	v_add_f32_dpp v210, v210, v210 row_mirror row_mask:0xf bank_mask:0xf bound_ctrl:1
	v_add_f32_dpp v214, v214, v214 row_mirror row_mask:0xf bank_mask:0xf bound_ctrl:1
	v_add_f32_dpp v218, v218, v218 row_mirror row_mask:0xf bank_mask:0xf bound_ctrl:1
	v_add_f32_dpp v222, v222, v222 row_mirror row_mask:0xf bank_mask:0xf bound_ctrl:1
	ds_bpermute_b32 v195, v239, v194
	ds_bpermute_b32 v199, v239, v198
	ds_bpermute_b32 v203, v239, v202
	ds_bpermute_b32 v207, v239, v206
	ds_bpermute_b32 v211, v239, v210
	ds_bpermute_b32 v215, v239, v214
	ds_bpermute_b32 v219, v239, v218
	ds_bpermute_b32 v223, v239, v222
	s_waitcnt lgkmcnt(7)
	v_add_f32_e32 v194, v194, v195
	s_waitcnt lgkmcnt(6)
	v_add_f32_e32 v198, v198, v199
	s_waitcnt lgkmcnt(5)
	v_add_f32_e32 v202, v202, v203
	s_waitcnt lgkmcnt(4)
	v_add_f32_e32 v206, v206, v207
	s_waitcnt lgkmcnt(3)
	v_add_f32_e32 v210, v210, v211
	s_waitcnt lgkmcnt(2)
	v_add_f32_e32 v214, v214, v215
	s_waitcnt lgkmcnt(1)
	v_add_f32_e32 v218, v218, v219
	s_waitcnt lgkmcnt(0)
	v_add_f32_e32 v222, v222, v223
	v_mul_f32_e32 v194, 0x3c800000, v194
	v_mul_f32_e32 v198, 0x3c800000, v198
	v_mul_f32_e32 v202, 0x3c800000, v202
	v_mul_f32_e32 v206, 0x3c800000, v206
	v_mul_f32_e32 v210, 0x3c800000, v210
	v_mul_f32_e32 v214, 0x3c800000, v214
	v_mul_f32_e32 v218, 0x3c800000, v218
	v_mul_f32_e32 v222, 0x3c800000, v222
	v_add_f32_e32 v194, 0x3727c5ac, v194
	v_add_f32_e32 v198, 0x3727c5ac, v198
	v_add_f32_e32 v202, 0x3727c5ac, v202
	v_add_f32_e32 v206, 0x3727c5ac, v206
	v_add_f32_e32 v210, 0x3727c5ac, v210
	v_add_f32_e32 v214, 0x3727c5ac, v214
	v_add_f32_e32 v218, 0x3727c5ac, v218
	v_add_f32_e32 v222, 0x3727c5ac, v222
	v_rsq_f32_e32 v194, v194
	v_rsq_f32_e32 v198, v198
	v_rsq_f32_e32 v202, v202
	v_rsq_f32_e32 v206, v206
	v_rsq_f32_e32 v210, v210
	v_rsq_f32_e32 v214, v214
	v_rsq_f32_e32 v218, v218
	v_rsq_f32_e32 v222, v222
	v_pk_mul_f32 v[172:173], v[172:173], v[194:195] op_sel_hi:[1,0]
	v_pk_mul_f32 v[174:175], v[174:175], v[198:199] op_sel_hi:[1,0]
	v_pk_mul_f32 v[176:177], v[176:177], v[202:203] op_sel_hi:[1,0]
	v_pk_mul_f32 v[178:179], v[178:179], v[206:207] op_sel_hi:[1,0]
	v_pk_mul_f32 v[180:181], v[180:181], v[210:211] op_sel_hi:[1,0]
	v_pk_mul_f32 v[182:183], v[182:183], v[214:215] op_sel_hi:[1,0]
	v_pk_mul_f32 v[184:185], v[184:185], v[218:219] op_sel_hi:[1,0]
	v_pk_mul_f32 v[186:187], v[186:187], v[222:223] op_sel_hi:[1,0]
	v_pk_fma_f32 v[172:173], v[172:173], v[92:93], v[94:95]
	v_pk_fma_f32 v[174:175], v[174:175], v[92:93], v[94:95]
	v_pk_fma_f32 v[176:177], v[176:177], v[92:93], v[94:95]
	v_pk_fma_f32 v[178:179], v[178:179], v[92:93], v[94:95]
	v_pk_fma_f32 v[180:181], v[180:181], v[92:93], v[94:95]
	v_pk_fma_f32 v[182:183], v[182:183], v[92:93], v[94:95]
	v_pk_fma_f32 v[184:185], v[184:185], v[92:93], v[94:95]
	v_pk_fma_f32 v[186:187], v[186:187], v[92:93], v[94:95]
	v_mul_f32_e32 v196, 0xbfb8aa3b, v172
	v_mul_f32_e32 v197, 0xbfb8aa3b, v173
	v_mul_f32_e32 v200, 0xbfb8aa3b, v174
	v_mul_f32_e32 v201, 0xbfb8aa3b, v175
	v_mul_f32_e32 v204, 0xbfb8aa3b, v176
	v_mul_f32_e32 v205, 0xbfb8aa3b, v177
	v_mul_f32_e32 v208, 0xbfb8aa3b, v178
	v_mul_f32_e32 v209, 0xbfb8aa3b, v179
; __device__ __forceinline__ unsigned pk2(float lo, float hi) { f32x2v v = {lo, hi}; b16x2v b = __builtin_convertvector(v, b16x2v); return __builtin_bit_cast(unsigned, b); }
; __device__ __forceinline__ float fsigmoid(float x) { return __builtin_amdgcn_rcpf(1.0f + __expf(-x)); }
; __device__ __forceinline__ void gn_swish_store(float v0, float v1, f32x2v gg, f32x2v gb, unsigned* dst) {
;     const float mean = half_wave_sum(v0 + v1) * (1.0f / 64.0f); const float d0 = v0 - mean, d1 = v1 - mean;
;     const float rstd = rsqrtf(half_wave_sum(d0 * d0 + d1 * d1) * (1.0f / 64.0f) + LN_EPS);
;     float y0 = d0 * rstd * gg.x + gb.x, y1 = d1 * rstd * gg.y + gb.y;
;     y0 = y0 * fsigmoid(y0); y1 = y1 * fsigmoid(y1);
;     *dst = pk2(y0, y1);
	v_mul_f32_e32 v212, 0xbfb8aa3b, v180
	v_mul_f32_e32 v213, 0xbfb8aa3b, v181
	v_mul_f32_e32 v216, 0xbfb8aa3b, v182
	v_mul_f32_e32 v217, 0xbfb8aa3b, v183
	v_mul_f32_e32 v220, 0xbfb8aa3b, v184
	v_mul_f32_e32 v221, 0xbfb8aa3b, v185
	v_mul_f32_e32 v224, 0xbfb8aa3b, v186
	v_mul_f32_e32 v225, 0xbfb8aa3b, v187
	v_exp_f32_e32 v196, v196
	v_exp_f32_e32 v197, v197
	v_exp_f32_e32 v200, v200
	v_exp_f32_e32 v201, v201
	v_exp_f32_e32 v204, v204
	v_exp_f32_e32 v205, v205
	v_exp_f32_e32 v208, v208
	v_exp_f32_e32 v209, v209
	v_exp_f32_e32 v212, v212
	v_exp_f32_e32 v213, v213
	v_exp_f32_e32 v216, v216
	v_exp_f32_e32 v217, v217
	v_exp_f32_e32 v220, v220
	v_exp_f32_e32 v221, v221
	v_exp_f32_e32 v224, v224
	v_exp_f32_e32 v225, v225
	v_add_f32_e32 v196, 1.0, v196
	v_add_f32_e32 v197, 1.0, v197
	v_add_f32_e32 v200, 1.0, v200
	v_add_f32_e32 v201, 1.0, v201
	v_add_f32_e32 v204, 1.0, v204
	v_add_f32_e32 v205, 1.0, v205
	v_add_f32_e32 v208, 1.0, v208
	v_add_f32_e32 v209, 1.0, v209
	v_add_f32_e32 v212, 1.0, v212
	v_add_f32_e32 v213, 1.0, v213
	v_add_f32_e32 v216, 1.0, v216
	v_add_f32_e32 v217, 1.0, v217
	v_add_f32_e32 v220, 1.0, v220
	v_add_f32_e32 v221, 1.0, v221
	v_add_f32_e32 v224, 1.0, v224
	v_add_f32_e32 v225, 1.0, v225
	v_rcp_f32_e32 v196, v196
	v_rcp_f32_e32 v197, v197
	v_rcp_f32_e32 v200, v200
	v_rcp_f32_e32 v201, v201
	v_rcp_f32_e32 v204, v204
	v_rcp_f32_e32 v205, v205
	v_rcp_f32_e32 v208, v208
	v_rcp_f32_e32 v209, v209
	v_rcp_f32_e32 v212, v212
	v_rcp_f32_e32 v213, v213
	v_rcp_f32_e32 v216, v216
	v_rcp_f32_e32 v217, v217
	v_rcp_f32_e32 v220, v220
	v_rcp_f32_e32 v221, v221
	v_rcp_f32_e32 v224, v224
	v_rcp_f32_e32 v225, v225
	v_pk_mul_f32 v[172:173], v[172:173], v[196:197]
	v_pk_mul_f32 v[174:175], v[174:175], v[200:201]
	v_pk_mul_f32 v[176:177], v[176:177], v[204:205]
	v_pk_mul_f32 v[178:179], v[178:179], v[208:209]
	v_pk_mul_f32 v[180:181], v[180:181], v[212:213]
	v_pk_mul_f32 v[182:183], v[182:183], v[216:217]
	v_pk_mul_f32 v[184:185], v[184:185], v[220:221]
	v_pk_mul_f32 v[186:187], v[186:187], v[224:225]
	v_cvt_pk_bf16_f32 v194, v172, v173
	v_cvt_pk_bf16_f32 v198, v174, v175
	v_cvt_pk_bf16_f32 v202, v176, v177
	v_cvt_pk_bf16_f32 v206, v178, v179
	v_cvt_pk_bf16_f32 v210, v180, v181
	v_cvt_pk_bf16_f32 v214, v182, v183
	v_cvt_pk_bf16_f32 v218, v184, v185
	v_cvt_pk_bf16_f32 v222, v186, v187
	global_store_dword v105, v194, s[70:71] offset:-4096
	global_store_dword v105, v198, s[70:71] offset:-2048
	global_store_dword v105, v202, s[70:71] offset:0
	global_store_dword v105, v206, s[70:71] offset:2048
	s_add_u32 s70, s70, 0x2000
	s_addc_u32 s71, s71, 0
	global_store_dword v105, v210, s[70:71] offset:-4096
	global_store_dword v105, v214, s[70:71] offset:-2048
	global_store_dword v105, v218, s[70:71] offset:0
	global_store_dword v105, v222, s[70:71] offset:2048
	v_add_f32_e32 v194, v188, v189
	v_add_f32_e32 v198, v190, v191
	v_add_f32_e32 v202, v78, v79
	v_add_f32_e32 v206, v80, v81
	v_add_f32_e32 v210, v82, v83
	v_add_f32_e32 v214, v84, v85
	v_add_f32_e32 v218, v86, v87
	v_add_f32_e32 v222, v88, v89
	v_add_f32_dpp v194, v194, v194 quad_perm:[1,0,3,2] row_mask:0xf bank_mask:0xf bound_ctrl:1
	v_add_f32_dpp v198, v198, v198 quad_perm:[1,0,3,2] row_mask:0xf bank_mask:0xf bound_ctrl:1
	v_add_f32_dpp v202, v202, v202 quad_perm:[1,0,3,2] row_mask:0xf bank_mask:0xf bound_ctrl:1
	v_add_f32_dpp v206, v206, v206 quad_perm:[1,0,3,2] row_mask:0xf bank_mask:0xf bound_ctrl:1
	v_add_f32_dpp v210, v210, v210 quad_perm:[1,0,3,2] row_mask:0xf bank_mask:0xf bound_ctrl:1
	v_add_f32_dpp v214, v214, v214 quad_perm:[1,0,3,2] row_mask:0xf bank_mask:0xf bound_ctrl:1
	v_add_f32_dpp v218, v218, v218 quad_perm:[1,0,3,2] row_mask:0xf bank_mask:0xf bound_ctrl:1
	v_add_f32_dpp v222, v222, v222 quad_perm:[1,0,3,2] row_mask:0xf bank_mask:0xf bound_ctrl:1
	v_add_f32_dpp v194, v194, v194 quad_perm:[2,3,0,1] row_mask:0xf bank_mask:0xf bound_ctrl:1
	v_add_f32_dpp v198, v198, v198 quad_perm:[2,3,0,1] row_mask:0xf bank_mask:0xf bound_ctrl:1
	v_add_f32_dpp v202, v202, v202 quad_perm:[2,3,0,1] row_mask:0xf bank_mask:0xf bound_ctrl:1
	v_add_f32_dpp v206, v206, v206 quad_perm:[2,3,0,1] row_mask:0xf bank_mask:0xf bound_ctrl:1
	v_add_f32_dpp v210, v210, v210 quad_perm:[2,3,0,1] row_mask:0xf bank_mask:0xf bound_ctrl:1
	v_add_f32_dpp v214, v214, v214 quad_perm:[2,3,0,1] row_mask:0xf bank_mask:0xf bound_ctrl:1
	v_add_f32_dpp v218, v218, v218 quad_perm:[2,3,0,1] row_mask:0xf bank_mask:0xf bound_ctrl:1
	v_add_f32_dpp v222, v222, v222 quad_perm:[2,3,0,1] row_mask:0xf bank_mask:0xf bound_ctrl:1
	v_add_f32_dpp v194, v194, v194 row_half_mirror row_mask:0xf bank_mask:0xf bound_ctrl:1
	v_add_f32_dpp v198, v198, v198 row_half_mirror row_mask:0xf bank_mask:0xf bound_ctrl:1
	v_add_f32_dpp v202, v202, v202 row_half_mirror row_mask:0xf bank_mask:0xf bound_ctrl:1
	v_add_f32_dpp v206, v206, v206 row_half_mirror row_mask:0xf bank_mask:0xf bound_ctrl:1
	v_add_f32_dpp v210, v210, v210 row_half_mirror row_mask:0xf bank_mask:0xf bound_ctrl:1
	v_add_f32_dpp v214, v214, v214 row_half_mirror row_mask:0xf bank_mask:0xf bound_ctrl:1
	v_add_f32_dpp v218, v218, v218 row_half_mirror row_mask:0xf bank_mask:0xf bound_ctrl:1
	v_add_f32_dpp v222, v222, v222 row_half_mirror row_mask:0xf bank_mask:0xf bound_ctrl:1
	v_add_f32_dpp v194, v194, v194 row_mirror row_mask:0xf bank_mask:0xf bound_ctrl:1
	v_add_f32_dpp v198, v198, v198 row_mirror row_mask:0xf bank_mask:0xf bound_ctrl:1
	v_add_f32_dpp v202, v202, v202 row_mirror row_mask:0xf bank_mask:0xf bound_ctrl:1
	v_add_f32_dpp v206, v206, v206 row_mirror row_mask:0xf bank_mask:0xf bound_ctrl:1
	v_add_f32_dpp v210, v210, v210 row_mirror row_mask:0xf bank_mask:0xf bound_ctrl:1
	v_add_f32_dpp v214, v214, v214 row_mirror row_mask:0xf bank_mask:0xf bound_ctrl:1
	v_add_f32_dpp v218, v218, v218 row_mirror row_mask:0xf bank_mask:0xf bound_ctrl:1
	v_add_f32_dpp v222, v222, v222 row_mirror row_mask:0xf bank_mask:0xf bound_ctrl:1
	ds_bpermute_b32 v195, v239, v194
	ds_bpermute_b32 v199, v239, v198
	ds_bpermute_b32 v203, v239, v202
	ds_bpermute_b32 v207, v239, v206
	ds_bpermute_b32 v211, v239, v210
	ds_bpermute_b32 v215, v239, v214
	ds_bpermute_b32 v219, v239, v218
	ds_bpermute_b32 v223, v239, v222
	s_waitcnt lgkmcnt(7)
; __device__ __forceinline__ unsigned pk2(float lo, float hi) { f32x2v v = {lo, hi}; b16x2v b = __builtin_convertvector(v, b16x2v); return __builtin_bit_cast(unsigned, b); }
; __device__ __forceinline__ float fsigmoid(float x) { return __builtin_amdgcn_rcpf(1.0f + __expf(-x)); }
; template <int CTRL> __device__ __forceinline__ float dpp_mov(float v) { return __builtin_bit_cast(float, __builtin_amdgcn_update_dpp(0, __builtin_bit_cast(int, v), CTRL, 0xf, 0xf, true)); }
; __device__ __forceinline__ float half_wave_sum(float v) {
;     v += dpp_mov<0xB1>(v);
;     v += dpp_mov<0x4E>(v);
;     v += dpp_mov<0x141>(v);
;     v += dpp_mov<0x140>(v);
;     v += __shfl_xor(v, 16);
;     return v;
; }
; __device__ __forceinline__ void gn_swish_store(float v0, float v1, f32x2v gg, f32x2v gb, unsigned* dst) {
;     const float mean = half_wave_sum(v0 + v1) * (1.0f / 64.0f); const float d0 = v0 - mean, d1 = v1 - mean;
;     const float rstd = rsqrtf(half_wave_sum(d0 * d0 + d1 * d1) * (1.0f / 64.0f) + LN_EPS);
;     float y0 = d0 * rstd * gg.x + gb.x, y1 = d1 * rstd * gg.y + gb.y;
;     y0 = y0 * fsigmoid(y0); y1 = y1 * fsigmoid(y1);
;     *dst = pk2(y0, y1);
	v_add_f32_e32 v194, v194, v195
	s_waitcnt lgkmcnt(6)
	v_add_f32_e32 v198, v198, v199
	s_waitcnt lgkmcnt(5)
	v_add_f32_e32 v202, v202, v203
	s_waitcnt lgkmcnt(4)
	v_add_f32_e32 v206, v206, v207
	s_waitcnt lgkmcnt(3)
	v_add_f32_e32 v210, v210, v211
	s_waitcnt lgkmcnt(2)
	v_add_f32_e32 v214, v214, v215
	s_waitcnt lgkmcnt(1)
	v_add_f32_e32 v218, v218, v219
	s_waitcnt lgkmcnt(0)
	v_add_f32_e32 v222, v222, v223
	v_mul_f32_e32 v194, 0x3c800000, v194
	v_mul_f32_e32 v198, 0x3c800000, v198
	v_mul_f32_e32 v202, 0x3c800000, v202
	v_mul_f32_e32 v206, 0x3c800000, v206
	v_mul_f32_e32 v210, 0x3c800000, v210
	v_mul_f32_e32 v214, 0x3c800000, v214
	v_mul_f32_e32 v218, 0x3c800000, v218
	v_mul_f32_e32 v222, 0x3c800000, v222
	v_pk_add_f32 v[188:189], v[188:189], v[194:195] op_sel_hi:[1,0] neg_lo:[0,1] neg_hi:[0,1]
	v_pk_add_f32 v[190:191], v[190:191], v[198:199] op_sel_hi:[1,0] neg_lo:[0,1] neg_hi:[0,1]
	v_pk_add_f32 v[78:79], v[78:79], v[202:203] op_sel_hi:[1,0] neg_lo:[0,1] neg_hi:[0,1]
	v_pk_add_f32 v[80:81], v[80:81], v[206:207] op_sel_hi:[1,0] neg_lo:[0,1] neg_hi:[0,1]
	v_pk_add_f32 v[82:83], v[82:83], v[210:211] op_sel_hi:[1,0] neg_lo:[0,1] neg_hi:[0,1]
	v_pk_add_f32 v[84:85], v[84:85], v[214:215] op_sel_hi:[1,0] neg_lo:[0,1] neg_hi:[0,1]
	v_pk_add_f32 v[86:87], v[86:87], v[218:219] op_sel_hi:[1,0] neg_lo:[0,1] neg_hi:[0,1]
	v_pk_add_f32 v[88:89], v[88:89], v[222:223] op_sel_hi:[1,0] neg_lo:[0,1] neg_hi:[0,1]
	v_pk_mul_f32 v[196:197], v[188:189], v[188:189]
	v_pk_mul_f32 v[200:201], v[190:191], v[190:191]
	v_pk_mul_f32 v[204:205], v[78:79], v[78:79]
	v_pk_mul_f32 v[208:209], v[80:81], v[80:81]
	v_pk_mul_f32 v[212:213], v[82:83], v[82:83]
	v_pk_mul_f32 v[216:217], v[84:85], v[84:85]
	v_pk_mul_f32 v[220:221], v[86:87], v[86:87]
	v_pk_mul_f32 v[224:225], v[88:89], v[88:89]
	v_add_f32_e32 v194, v196, v197
	v_add_f32_e32 v198, v200, v201
	v_add_f32_e32 v202, v204, v205
	v_add_f32_e32 v206, v208, v209
	v_add_f32_e32 v210, v212, v213
	v_add_f32_e32 v214, v216, v217
	v_add_f32_e32 v218, v220, v221
	v_add_f32_e32 v222, v224, v225
	v_add_f32_dpp v194, v194, v194 quad_perm:[1,0,3,2] row_mask:0xf bank_mask:0xf bound_ctrl:1
	v_add_f32_dpp v198, v198, v198 quad_perm:[1,0,3,2] row_mask:0xf bank_mask:0xf bound_ctrl:1
	v_add_f32_dpp v202, v202, v202 quad_perm:[1,0,3,2] row_mask:0xf bank_mask:0xf bound_ctrl:1
	v_add_f32_dpp v206, v206, v206 quad_perm:[1,0,3,2] row_mask:0xf bank_mask:0xf bound_ctrl:1
	v_add_f32_dpp v210, v210, v210 quad_perm:[1,0,3,2] row_mask:0xf bank_mask:0xf bound_ctrl:1
	v_add_f32_dpp v214, v214, v214 quad_perm:[1,0,3,2] row_mask:0xf bank_mask:0xf bound_ctrl:1
	v_add_f32_dpp v218, v218, v218 quad_perm:[1,0,3,2] row_mask:0xf bank_mask:0xf bound_ctrl:1
	v_add_f32_dpp v222, v222, v222 quad_perm:[1,0,3,2] row_mask:0xf bank_mask:0xf bound_ctrl:1
	v_add_f32_dpp v194, v194, v194 quad_perm:[2,3,0,1] row_mask:0xf bank_mask:0xf bound_ctrl:1
	v_add_f32_dpp v198, v198, v198 quad_perm:[2,3,0,1] row_mask:0xf bank_mask:0xf bound_ctrl:1
	v_add_f32_dpp v202, v202, v202 quad_perm:[2,3,0,1] row_mask:0xf bank_mask:0xf bound_ctrl:1
	v_add_f32_dpp v206, v206, v206 quad_perm:[2,3,0,1] row_mask:0xf bank_mask:0xf bound_ctrl:1
	v_add_f32_dpp v210, v210, v210 quad_perm:[2,3,0,1] row_mask:0xf bank_mask:0xf bound_ctrl:1
	v_add_f32_dpp v214, v214, v214 quad_perm:[2,3,0,1] row_mask:0xf bank_mask:0xf bound_ctrl:1
	v_add_f32_dpp v218, v218, v218 quad_perm:[2,3,0,1] row_mask:0xf bank_mask:0xf bound_ctrl:1
	v_add_f32_dpp v222, v222, v222 quad_perm:[2,3,0,1] row_mask:0xf bank_mask:0xf bound_ctrl:1
	v_add_f32_dpp v194, v194, v194 row_half_mirror row_mask:0xf bank_mask:0xf bound_ctrl:1
	v_add_f32_dpp v198, v198, v198 row_half_mirror row_mask:0xf bank_mask:0xf bound_ctrl:1
	v_add_f32_dpp v202, v202, v202 row_half_mirror row_mask:0xf bank_mask:0xf bound_ctrl:1
	v_add_f32_dpp v206, v206, v206 row_half_mirror row_mask:0xf bank_mask:0xf bound_ctrl:1
	v_add_f32_dpp v210, v210, v210 row_half_mirror row_mask:0xf bank_mask:0xf bound_ctrl:1
	v_add_f32_dpp v214, v214, v214 row_half_mirror row_mask:0xf bank_mask:0xf bound_ctrl:1
	v_add_f32_dpp v218, v218, v218 row_half_mirror row_mask:0xf bank_mask:0xf bound_ctrl:1
	v_add_f32_dpp v222, v222, v222 row_half_mirror row_mask:0xf bank_mask:0xf bound_ctrl:1
	v_add_f32_dpp v194, v194, v194 row_mirror row_mask:0xf bank_mask:0xf bound_ctrl:1
	v_add_f32_dpp v198, v198, v198 row_mirror row_mask:0xf bank_mask:0xf bound_ctrl:1
	v_add_f32_dpp v202, v202, v202 row_mirror row_mask:0xf bank_mask:0xf bound_ctrl:1
	v_add_f32_dpp v206, v206, v206 row_mirror row_mask:0xf bank_mask:0xf bound_ctrl:1
	v_add_f32_dpp v210, v210, v210 row_mirror row_mask:0xf bank_mask:0xf bound_ctrl:1
	v_add_f32_dpp v214, v214, v214 row_mirror row_mask:0xf bank_mask:0xf bound_ctrl:1
	v_add_f32_dpp v218, v218, v218 row_mirror row_mask:0xf bank_mask:0xf bound_ctrl:1
	v_add_f32_dpp v222, v222, v222 row_mirror row_mask:0xf bank_mask:0xf bound_ctrl:1
	ds_bpermute_b32 v195, v239, v194
	ds_bpermute_b32 v199, v239, v198
	ds_bpermute_b32 v203, v239, v202
	ds_bpermute_b32 v207, v239, v206
	ds_bpermute_b32 v211, v239, v210
	ds_bpermute_b32 v215, v239, v214
	ds_bpermute_b32 v219, v239, v218
	ds_bpermute_b32 v223, v239, v222
	s_waitcnt lgkmcnt(7)
	v_add_f32_e32 v194, v194, v195
	s_waitcnt lgkmcnt(6)
	v_add_f32_e32 v198, v198, v199
	s_waitcnt lgkmcnt(5)
	v_add_f32_e32 v202, v202, v203
	s_waitcnt lgkmcnt(4)
	v_add_f32_e32 v206, v206, v207
	s_waitcnt lgkmcnt(3)
	v_add_f32_e32 v210, v210, v211
	s_waitcnt lgkmcnt(2)
	v_add_f32_e32 v214, v214, v215
	s_waitcnt lgkmcnt(1)
	v_add_f32_e32 v218, v218, v219
	s_waitcnt lgkmcnt(0)
; __device__ __forceinline__ unsigned pk2(float lo, float hi) { f32x2v v = {lo, hi}; b16x2v b = __builtin_convertvector(v, b16x2v); return __builtin_bit_cast(unsigned, b); }
; __device__ __forceinline__ float fsigmoid(float x) { return __builtin_amdgcn_rcpf(1.0f + __expf(-x)); }
; __device__ __forceinline__ void gn_swish_store(float v0, float v1, f32x2v gg, f32x2v gb, unsigned* dst) {
;     const float mean = half_wave_sum(v0 + v1) * (1.0f / 64.0f); const float d0 = v0 - mean, d1 = v1 - mean;
;     const float rstd = rsqrtf(half_wave_sum(d0 * d0 + d1 * d1) * (1.0f / 64.0f) + LN_EPS);
;     float y0 = d0 * rstd * gg.x + gb.x, y1 = d1 * rstd * gg.y + gb.y;
;     y0 = y0 * fsigmoid(y0); y1 = y1 * fsigmoid(y1);
;     *dst = pk2(y0, y1);
	v_add_f32_e32 v222, v222, v223
	v_mul_f32_e32 v194, 0x3c800000, v194
	v_mul_f32_e32 v198, 0x3c800000, v198
	v_mul_f32_e32 v202, 0x3c800000, v202
	v_mul_f32_e32 v206, 0x3c800000, v206
	v_mul_f32_e32 v210, 0x3c800000, v210
	v_mul_f32_e32 v214, 0x3c800000, v214
	v_mul_f32_e32 v218, 0x3c800000, v218
	v_mul_f32_e32 v222, 0x3c800000, v222
	v_add_f32_e32 v194, 0x3727c5ac, v194
	v_add_f32_e32 v198, 0x3727c5ac, v198
	v_add_f32_e32 v202, 0x3727c5ac, v202
	v_add_f32_e32 v206, 0x3727c5ac, v206
	v_add_f32_e32 v210, 0x3727c5ac, v210
	v_add_f32_e32 v214, 0x3727c5ac, v214
	v_add_f32_e32 v218, 0x3727c5ac, v218
	v_add_f32_e32 v222, 0x3727c5ac, v222
	v_rsq_f32_e32 v194, v194
	v_rsq_f32_e32 v198, v198
	v_rsq_f32_e32 v202, v202
	v_rsq_f32_e32 v206, v206
	v_rsq_f32_e32 v210, v210
	v_rsq_f32_e32 v214, v214
	v_rsq_f32_e32 v218, v218
	v_rsq_f32_e32 v222, v222
	v_pk_mul_f32 v[188:189], v[188:189], v[194:195] op_sel_hi:[1,0]
	v_pk_mul_f32 v[190:191], v[190:191], v[198:199] op_sel_hi:[1,0]
	v_pk_mul_f32 v[78:79], v[78:79], v[202:203] op_sel_hi:[1,0]
	v_pk_mul_f32 v[80:81], v[80:81], v[206:207] op_sel_hi:[1,0]
	v_pk_mul_f32 v[82:83], v[82:83], v[210:211] op_sel_hi:[1,0]
	v_pk_mul_f32 v[84:85], v[84:85], v[214:215] op_sel_hi:[1,0]
	v_pk_mul_f32 v[86:87], v[86:87], v[218:219] op_sel_hi:[1,0]
	v_pk_mul_f32 v[88:89], v[88:89], v[222:223] op_sel_hi:[1,0]
	v_pk_fma_f32 v[188:189], v[188:189], v[92:93], v[94:95]
	v_pk_fma_f32 v[190:191], v[190:191], v[92:93], v[94:95]
	v_pk_fma_f32 v[78:79], v[78:79], v[92:93], v[94:95]
	v_pk_fma_f32 v[80:81], v[80:81], v[92:93], v[94:95]
	v_pk_fma_f32 v[82:83], v[82:83], v[92:93], v[94:95]
	v_pk_fma_f32 v[84:85], v[84:85], v[92:93], v[94:95]
	v_pk_fma_f32 v[86:87], v[86:87], v[92:93], v[94:95]
	v_pk_fma_f32 v[88:89], v[88:89], v[92:93], v[94:95]
	v_mul_f32_e32 v196, 0xbfb8aa3b, v188
	v_mul_f32_e32 v197, 0xbfb8aa3b, v189
	v_mul_f32_e32 v200, 0xbfb8aa3b, v190
	v_mul_f32_e32 v201, 0xbfb8aa3b, v191
	v_mul_f32_e32 v204, 0xbfb8aa3b, v78
	v_mul_f32_e32 v205, 0xbfb8aa3b, v79
	v_mul_f32_e32 v208, 0xbfb8aa3b, v80
	v_mul_f32_e32 v209, 0xbfb8aa3b, v81
	v_mul_f32_e32 v212, 0xbfb8aa3b, v82
	v_mul_f32_e32 v213, 0xbfb8aa3b, v83
	v_mul_f32_e32 v216, 0xbfb8aa3b, v84
	v_mul_f32_e32 v217, 0xbfb8aa3b, v85
	v_mul_f32_e32 v220, 0xbfb8aa3b, v86
	v_mul_f32_e32 v221, 0xbfb8aa3b, v87
	v_mul_f32_e32 v224, 0xbfb8aa3b, v88
	v_mul_f32_e32 v225, 0xbfb8aa3b, v89
	v_exp_f32_e32 v196, v196
	v_exp_f32_e32 v197, v197
	v_exp_f32_e32 v200, v200
	v_exp_f32_e32 v201, v201
	v_exp_f32_e32 v204, v204
	v_exp_f32_e32 v205, v205
	v_exp_f32_e32 v208, v208
	v_exp_f32_e32 v209, v209
	v_exp_f32_e32 v212, v212
	v_exp_f32_e32 v213, v213
	v_exp_f32_e32 v216, v216
	v_exp_f32_e32 v217, v217
	v_exp_f32_e32 v220, v220
	v_exp_f32_e32 v221, v221
	v_exp_f32_e32 v224, v224
	v_exp_f32_e32 v225, v225
	v_add_f32_e32 v196, 1.0, v196
	v_add_f32_e32 v197, 1.0, v197
	v_add_f32_e32 v200, 1.0, v200
	v_add_f32_e32 v201, 1.0, v201
	v_add_f32_e32 v204, 1.0, v204
	v_add_f32_e32 v205, 1.0, v205
	v_add_f32_e32 v208, 1.0, v208
	v_add_f32_e32 v209, 1.0, v209
	v_add_f32_e32 v212, 1.0, v212
	v_add_f32_e32 v213, 1.0, v213
	v_add_f32_e32 v216, 1.0, v216
	v_add_f32_e32 v217, 1.0, v217
	v_add_f32_e32 v220, 1.0, v220
	v_add_f32_e32 v221, 1.0, v221
	v_add_f32_e32 v224, 1.0, v224
	v_add_f32_e32 v225, 1.0, v225
	v_rcp_f32_e32 v196, v196
	v_rcp_f32_e32 v197, v197
	v_rcp_f32_e32 v200, v200
	v_rcp_f32_e32 v201, v201
	v_rcp_f32_e32 v204, v204
	v_rcp_f32_e32 v205, v205
	v_rcp_f32_e32 v208, v208
	v_rcp_f32_e32 v209, v209
	v_rcp_f32_e32 v212, v212
	v_rcp_f32_e32 v213, v213
	v_rcp_f32_e32 v216, v216
	v_rcp_f32_e32 v217, v217
	v_rcp_f32_e32 v220, v220
	v_rcp_f32_e32 v221, v221
	v_rcp_f32_e32 v224, v224
	v_rcp_f32_e32 v225, v225
	v_pk_mul_f32 v[188:189], v[188:189], v[196:197]
	v_pk_mul_f32 v[190:191], v[190:191], v[200:201]
	v_pk_mul_f32 v[78:79], v[78:79], v[204:205]
	v_pk_mul_f32 v[80:81], v[80:81], v[208:209]
	v_pk_mul_f32 v[82:83], v[82:83], v[212:213]
	v_pk_mul_f32 v[84:85], v[84:85], v[216:217]
	v_pk_mul_f32 v[86:87], v[86:87], v[220:221]
	v_pk_mul_f32 v[88:89], v[88:89], v[224:225]
	v_cvt_pk_bf16_f32 v194, v188, v189
	v_cvt_pk_bf16_f32 v198, v190, v191
	v_cvt_pk_bf16_f32 v202, v78, v79
	v_cvt_pk_bf16_f32 v206, v80, v81
	v_cvt_pk_bf16_f32 v210, v82, v83
	v_cvt_pk_bf16_f32 v214, v84, v85
	v_cvt_pk_bf16_f32 v218, v86, v87
	v_cvt_pk_bf16_f32 v222, v88, v89
	s_add_u32 s70, s70, 0x2000
	s_addc_u32 s71, s71, 0
	global_store_dword v105, v194, s[70:71] offset:-4096
	global_store_dword v105, v198, s[70:71] offset:-2048
	global_store_dword v105, v202, s[70:71] offset:0
	global_store_dword v105, v206, s[70:71] offset:2048
	s_add_u32 s70, s70, 0x2000
	s_addc_u32 s71, s71, 0
	global_store_dword v105, v210, s[70:71] offset:-4096
	global_store_dword v105, v214, s[70:71] offset:-2048
	global_store_dword v105, v218, s[70:71] offset:0
	global_store_dword v105, v222, s[70:71] offset:2048
	s_branch .Lmx_done
; __device__ __forceinline__ f32x2v bf2(unsigned v) { return (f32x2v){bflo(v), bfhi(v)}; }
; __device__ __forceinline__ void mixer_prompt_run(const Args& p, int run, int c2) {
;     ...
;             for (int i = 0; i < 38; ++i) {
;                 const int ti = t0 + 8 * hh - 30 + i; unsigned v = U32[(rowb + (ti >= 0 ? ti : 0)) * 256 + c2]; v = (ti >= 0) ? v : 0u; const f32x2v x = bf2(v);
; #pragma unroll
;                 for (int t = 0; t < 8; ++t) { const int j = i - t; if (j >= 0 && j <= 30) a[t] = w[j] * x + a[t]; }
.Lmx_e0:
	s_cmp_ge_i32 s64, 30
	s_cbranch_scc1 .Lmx_b0
	v_mov_b32_e32 v193, 0
	s_branch .Lmx_b0
.Lmx_e1:
	s_cmp_ge_i32 s64, 29
	s_cbranch_scc1 .Lmx_b1
	v_mov_b32_e32 v194, 0
	s_branch .Lmx_b1
.Lmx_e2:
	s_cmp_ge_i32 s64, 28
	s_cbranch_scc1 .Lmx_b2
	v_mov_b32_e32 v195, 0
	s_branch .Lmx_b2
.Lmx_e3:
	s_cmp_ge_i32 s64, 27
	s_cbranch_scc1 .Lmx_b3
	v_mov_b32_e32 v196, 0
	s_branch .Lmx_b3
.Lmx_e4:
	s_cmp_ge_i32 s64, 26
	s_cbranch_scc1 .Lmx_b4
	v_mov_b32_e32 v197, 0
	s_branch .Lmx_b4
.Lmx_e5:
	s_cmp_ge_i32 s64, 25
	s_cbranch_scc1 .Lmx_b5
	v_mov_b32_e32 v198, 0
	s_branch .Lmx_b5
.Lmx_e6:
	s_cmp_ge_i32 s64, 24
	s_cbranch_scc1 .Lmx_b6
	v_mov_b32_e32 v199, 0
	s_branch .Lmx_b6
.Lmx_e7:
	s_cmp_ge_i32 s64, 23
	s_cbranch_scc1 .Lmx_b7
	v_mov_b32_e32 v200, 0
	s_branch .Lmx_b7
.Lmx_e8:
	s_cmp_ge_i32 s64, 22
	s_cbranch_scc1 .Lmx_b8
	v_mov_b32_e32 v201, 0
	s_branch .Lmx_b8
.Lmx_e9:
	s_cmp_ge_i32 s64, 21
	s_cbranch_scc1 .Lmx_b9
	v_mov_b32_e32 v202, 0
	s_branch .Lmx_b9
.Lmx_e10:
	s_cmp_ge_i32 s64, 20
	s_cbranch_scc1 .Lmx_b10
	v_mov_b32_e32 v203, 0
	s_branch .Lmx_b10
.Lmx_e11:
	s_cmp_ge_i32 s64, 19
	s_cbranch_scc1 .Lmx_b11
	v_mov_b32_e32 v204, 0
	s_branch .Lmx_b11
.Lmx_e12:
	s_cmp_ge_i32 s64, 18
	s_cbranch_scc1 .Lmx_b12
	v_mov_b32_e32 v205, 0
	s_branch .Lmx_b12
.Lmx_e13:
	s_cmp_ge_i32 s64, 17
	s_cbranch_scc1 .Lmx_b13
	v_mov_b32_e32 v206, 0
	s_branch .Lmx_b13
.Lmx_e14:
	s_cmp_ge_i32 s64, 16
	s_cbranch_scc1 .Lmx_b14
	v_mov_b32_e32 v207, 0
	s_branch .Lmx_b14
.Lmx_e15:
	s_cmp_ge_i32 s64, 15
	s_cbranch_scc1 .Lmx_b15
	v_mov_b32_e32 v208, 0
	s_branch .Lmx_b15
.Lmx_e16:
	s_cmp_ge_i32 s64, 14
	s_cbranch_scc1 .Lmx_b16
	v_mov_b32_e32 v209, 0
	s_branch .Lmx_b16
.Lmx_e17:
	s_cmp_ge_i32 s64, 13
	s_cbranch_scc1 .Lmx_b17
	v_mov_b32_e32 v210, 0
	s_branch .Lmx_b17
.Lmx_e18:
	s_cmp_ge_i32 s64, 12
	s_cbranch_scc1 .Lmx_b18
	v_mov_b32_e32 v211, 0
	s_branch .Lmx_b18
.Lmx_e19:
	s_cmp_ge_i32 s64, 11
	s_cbranch_scc1 .Lmx_b19
	v_mov_b32_e32 v212, 0
	s_branch .Lmx_b19
.Lmx_e20:
	s_cmp_ge_i32 s64, 10
	s_cbranch_scc1 .Lmx_b20
	v_mov_b32_e32 v213, 0
	s_branch .Lmx_b20
.Lmx_e21:
	s_cmp_ge_i32 s64, 9
	s_cbranch_scc1 .Lmx_b21
	v_mov_b32_e32 v214, 0
	s_branch .Lmx_b21
.Lmx_e22:
	s_cmp_ge_i32 s64, 8
	s_cbranch_scc1 .Lmx_b22
	v_mov_b32_e32 v215, 0
	s_branch .Lmx_b22
.Lmx_e23:
	s_cmp_ge_i32 s64, 7
	s_cbranch_scc1 .Lmx_b23
	v_mov_b32_e32 v216, 0
	s_branch .Lmx_b23
.Lmx_e24:
	s_cmp_ge_i32 s64, 6
	s_cbranch_scc1 .Lmx_b24
	v_mov_b32_e32 v217, 0
	s_branch .Lmx_b24
.Lmx_e25:
	s_cmp_ge_i32 s64, 5
	s_cbranch_scc1 .Lmx_b25
	v_mov_b32_e32 v218, 0
	s_branch .Lmx_b25
.Lmx_e26:
	s_cmp_ge_i32 s64, 4
	s_cbranch_scc1 .Lmx_b26
	v_mov_b32_e32 v219, 0
	s_branch .Lmx_b26
.Lmx_e27:
	s_cmp_ge_i32 s64, 3
	s_cbranch_scc1 .Lmx_b27
	v_mov_b32_e32 v220, 0
	s_branch .Lmx_b27
.Lmx_e28:
	s_cmp_ge_i32 s64, 2
	s_cbranch_scc1 .Lmx_b28
	v_mov_b32_e32 v221, 0
	s_branch .Lmx_b28
.Lmx_e29:
	s_cmp_ge_i32 s64, 1
	s_cbranch_scc1 .Lmx_b29
	v_mov_b32_e32 v222, 0
	s_branch .Lmx_b29
.Lmx_done:
	s_branch .LBB0_601
.LBB0_619:
	s_and_b32 s0, s96, 7
	s_cmp_lg_u32 s0, 0
	s_mov_b32 s1, s94
	s_cbranch_scc1 .Ltr2_vcu
	s_and_b32 s0, s94, 7
	s_lshr_b32 s1, s96, 3
	s_mul_i32 s0, s0, s1
	s_lshr_b32 s1, s94, 3
	s_add_u32 s1, s0, s1
